# in-proj epilogue: hoist the 8 per-row rss loads to the epilogue start with counted waits (on top of combine fix)
# speedup vs baseline: 1.0081x; 1.0081x over previous
;     __device__ __forceinline__ void operator()(const f32x4 (&acc)[2][2][4][2], const Unit& u, int wr, int wc, int fr, int fq, PG8_LAS unsigned char* lds) const {
;         const int slot = u.pn * 4 + wc;
;         const int type = slot < 8 ? 0 : slot < 10 ? 1 : slot < 12 ? 2 : slot < 20 ? 3 : slot < 28 ? 4 : 2;
;         const int colbase = u.pn * 256 + wc * 64 + ((fq & 1) << 4) + ((fq >> 1) << 3);
;         f32x4 g[2][2], f4[2];
;         if (type <= 1) { const float* gp = type == 0 ? gq : gk;
; #pragma unroll
;             for (int bj = 0; bj < 2; ++bj)
; #pragma unroll
;                 for (int n = 0; n < 2; ++n) g[bj][n] = *(const f32x4*)(gp + 32 * bj + 16 * n + 4 * fq);
;             f4[0] = *(const f32x4*)(frq + 32 + 4 * fq); f4[1] = f4[0]; }
;         else if (type >= 3) { f4[0] = *(const f32x4*)(frq + 4 * fq); f4[1] = *(const f32x4*)(frq + 16 + 4 * fq); }
;         const int tmask = (u.pm * BM < TPROMPT) ? 2047 : 4095;
;         float kmx = 0.f;
; #pragma unroll
;         for (int ai = 0; ai < 2; ++ai)
; #pragma unroll
;             for (int m = 0; m < 4; ++m) {
;                 const int row = u.pm * BM + ai * HALF + wr * 64 + m * 16 + fr; const int t = row & tmask;
;                 const float rs = __builtin_amdgcn_rsqf((float)rss[row] * (2.3283064365386963e-10f / 1024.0f) + 1e-6f);
;                 f32x4 v[2][2];
; #pragma unroll
;                 for (int bj = 0; bj < 2; ++bj)
; #pragma unroll
;                     for (int n = 0; n < 2; ++n) v[bj][n] = acc[ai][bj][m][n] * rs;
;                 if (type <= 1) {
;                     float ss = 0.f;
; #pragma unroll
;                     for (int bj = 0; bj < 2; ++bj)
; #pragma unroll
;                         for (int n = 0; n < 2; ++n) { const f32x4 x = v[bj][n]; ss += (x[0] * x[0] + x[1] * x[1]) + (x[2] * x[2] + x[3] * x[3]); }
;                     ss += __shfl_xor(ss, 16); ss += __shfl_xor(ss, 32);
;                     float rn = __builtin_amdgcn_rsqf(ss * (1.0f / 64.0f) + 1e-6f); if (type == 0) rn *= QSCALE;
; #pragma unroll
;                     for (int bj = 0; bj < 2; ++bj) { const float pf = (float)(bj == 0 ? (t >> 6) : (t & 63)); f32x4 c, s;
; #pragma unroll
;                         for (int e = 0; e < 4; ++e) { const float a = __builtin_amdgcn_fractf(pf * f4[0][e]); c[e] = __builtin_amdgcn_cosf(a); s[e] = __builtin_amdgcn_sinf(a); }
.LBB0_146:
	s_cmpk_lt_i32 s36, 0x100
	s_cselect_b64 s[72:73], -1, 0
	s_and_b64 s[8:9], s[72:73], exec
	s_cselect_b32 s63, s62, 0xfff
	s_cmp_lg_u32 s10, 2
	s_cselect_b64 s[14:15], -1, 0
	s_cmp_eq_u32 s10, 3
	s_cselect_b64 vcc, -1, 0
	s_cmp_eq_u32 s10, 4
	s_cselect_b64 s[74:75], -1, 0
	s_cmp_eq_u32 s10, 0
	s_cselect_b64 s[8:9], -1, 0
	s_lshl_b32 s45, s36, 8
	v_add_u32_e32 v190, s45, v189
	v_ashrrev_i32_e32 v191, 31, v190
	v_lshl_add_u64 v[152:153], v[190:191], 3, s[24:25]
	global_load_dwordx2 v[210:211], v[152:153], off
	global_load_dwordx2 v[224:225], v[152:153], off offset:128
	global_load_dwordx2 v[226:227], v[152:153], off offset:256
	global_load_dwordx2 v[228:229], v[152:153], off offset:384
	global_load_dwordx2 v[230:231], v[152:153], off offset:1024
	global_load_dwordx2 v[232:233], v[152:153], off offset:1152
	global_load_dwordx2 v[234:235], v[152:153], off offset:1280
	global_load_dwordx2 v[236:237], v[152:153], off offset:1408
	s_mov_b64 s[12:13], -1
	v_and_b32_e32 v216, s63, v190
	s_waitcnt vmcnt(7)
	v_ffbh_u32_e32 v188, v211
	v_min_u32_e32 v209, 32, v188
	v_lshlrev_b64 v[210:211], v209, v[210:211]
	v_min_u32_e32 v188, 1, v210
	v_or_b32_e32 v188, v211, v188
	v_cvt_f32_u32_e32 v210, v188
	v_sub_u32_e32 v209, 32, v209
	v_cndmask_b32_e64 v211, 0, 1, s[14:15]
	v_cndmask_b32_e32 v188, 1.0, v206, vcc
	v_ldexp_f32 v209, v210, v209
	v_fmamk_f32 v209, v209, 0x2a800000, v204
	v_rsq_f32_e32 v210, v209
	v_cmp_ne_u32_e64 s[10:11], 1, v211
	s_and_b64 vcc, exec, s[76:77]
	v_pk_mul_f32 v[150:151], v[150:151], v[210:211] op_sel_hi:[1,0]
	v_pk_mul_f32 v[148:149], v[148:149], v[210:211] op_sel_hi:[1,0]
	v_pk_mul_f32 v[146:147], v[146:147], v[210:211] op_sel_hi:[1,0]
	v_pk_mul_f32 v[144:145], v[144:145], v[210:211] op_sel_hi:[1,0]
	v_pk_mul_f32 v[142:143], v[142:143], v[210:211] op_sel_hi:[1,0]
	v_pk_mul_f32 v[140:141], v[140:141], v[210:211] op_sel_hi:[1,0]
	v_pk_mul_f32 v[138:139], v[138:139], v[210:211] op_sel_hi:[1,0]
	v_pk_mul_f32 v[136:137], v[136:137], v[210:211] op_sel_hi:[1,0]
	s_cbranch_vccz .LBB0_151
	v_mov_b64_e32 v[154:155], v[150:151]
	v_mov_b64_e32 v[162:163], v[146:147]
	v_mov_b64_e32 v[158:159], v[142:143]
	v_mov_b64_e32 v[166:167], v[138:139]
	v_mov_b32_e32 v213, 0
	s_and_b64 vcc, exec, s[10:11]
	v_mov_b64_e32 v[152:153], v[148:149]
	v_mov_b64_e32 v[160:161], v[144:145]
	v_mov_b64_e32 v[156:157], v[140:141]
	v_mov_b64_e32 v[164:165], v[136:137]
	s_cbranch_vccnz .LBB0_150
	v_cvt_f32_u32_e32 v165, v216
	s_andn2_b64 vcc, exec, s[74:75]
	v_mul_f32_e32 v156, v30, v165
	v_fract_f32_e32 v157, v156
	v_mul_f32_e32 v152, v28, v165
	v_mul_f32_e32 v153, v29, v165
	v_cos_f32_e32 v156, v157
	v_sin_f32_e32 v158, v157
	v_mul_f32_e32 v157, v31, v165
	v_fract_f32_e32 v154, v152
	v_fract_f32_e32 v155, v153
	v_fract_f32_e32 v159, v157
	v_cos_f32_e32 v152, v154
	v_sin_f32_e32 v154, v154
	v_cos_f32_e32 v153, v155
	v_cos_f32_e32 v157, v159
	v_sin_f32_e32 v159, v159
	v_sin_f32_e32 v155, v155
	v_pk_mul_f32 v[160:161], v[188:189], v[152:153] op_sel_hi:[0,1]
	v_pk_mul_f32 v[156:157], v[188:189], v[156:157] op_sel_hi:[0,1]
	v_pk_mul_f32 v[158:159], v[188:189], v[158:159] op_sel_hi:[0,1]
	v_pk_mul_f32 v[162:163], v[188:189], v[154:155] op_sel_hi:[0,1]
	v_pk_mul_f32 v[152:153], v[162:163], v[140:141]
	v_pk_mul_f32 v[154:155], v[158:159], v[142:143]
	v_pk_fma_f32 v[152:153], v[160:161], v[148:149], v[152:153] neg_lo:[0,0,1] neg_hi:[0,0,1]
	v_pk_fma_f32 v[154:155], v[156:157], v[150:151], v[154:155] neg_lo:[0,0,1] neg_hi:[0,0,1]
	v_pk_mul_f32 v[160:161], v[160:161], v[140:141]
	v_pk_mul_f32 v[156:157], v[156:157], v[142:143]
	v_mul_f32_e32 v164, v54, v165
	v_pk_fma_f32 v[158:159], v[158:159], v[150:151], v[156:157]
	v_pk_fma_f32 v[156:157], v[162:163], v[148:149], v[160:161]
	v_mul_f32_e32 v160, v52, v165
	v_fract_f32_e32 v161, v160
	v_cos_f32_e32 v160, v161
	v_sin_f32_e32 v162, v161
	v_mul_f32_e32 v161, v53, v165
	v_mul_f32_e32 v165, v55, v165
	v_fract_f32_e32 v163, v161
	v_fract_f32_e32 v166, v164
	v_fract_f32_e32 v167, v165
	v_cos_f32_e32 v161, v163
	v_cos_f32_e32 v164, v166
	v_sin_f32_e32 v166, v166
	v_cos_f32_e32 v165, v167
	v_sin_f32_e32 v167, v167
	v_sin_f32_e32 v163, v163
	v_pk_mul_f32 v[210:211], v[188:189], v[160:161] op_sel_hi:[0,1]
	v_pk_mul_f32 v[164:165], v[188:189], v[164:165] op_sel_hi:[0,1]
	v_pk_mul_f32 v[166:167], v[188:189], v[166:167] op_sel_hi:[0,1]
	v_pk_mul_f32 v[212:213], v[188:189], v[162:163] op_sel_hi:[0,1]
	v_pk_mul_f32 v[160:161], v[212:213], v[136:137]
	v_pk_mul_f32 v[162:163], v[166:167], v[138:139]
	v_pk_fma_f32 v[160:161], v[210:211], v[144:145], v[160:161] neg_lo:[0,0,1] neg_hi:[0,0,1]
	v_pk_fma_f32 v[162:163], v[164:165], v[146:147], v[162:163] neg_lo:[0,0,1] neg_hi:[0,0,1]
	v_pk_mul_f32 v[210:211], v[210:211], v[136:137]
	v_pk_mul_f32 v[164:165], v[164:165], v[138:139]
	s_nop 0
	v_pk_fma_f32 v[166:167], v[166:167], v[146:147], v[164:165]
	v_pk_fma_f32 v[164:165], v[212:213], v[144:145], v[210:211]
	v_mov_b32_e32 v213, 0
	s_cbranch_vccnz .LBB0_150
	v_pk_mul_f32 v[210:211], v[154:155], v[154:155]
	v_pk_mul_f32 v[212:213], v[152:153], v[152:153]
	s_nop 0
	v_pk_mov_b32 v[218:219], v[212:213], v[210:211] op_sel:[1,0]
	v_mov_b32_e32 v213, v211
	v_pk_add_f32 v[210:211], v[218:219], v[212:213]
	v_pk_mul_f32 v[212:213], v[162:163], v[162:163]
	v_pk_add_f32 v[210:211], v[210:211], v[210:211] op_sel_hi:[0,1]
	v_pk_mul_f32 v[218:219], v[160:161], v[160:161]
	v_mul_f32_e32 v210, v156, v156
	v_pk_mov_b32 v[220:221], v[218:219], v[212:213] op_sel:[1,0]
	v_mov_b32_e32 v219, v213
	v_pk_add_f32 v[212:213], v[220:221], v[218:219]
	v_pk_fma_f32 v[218:219], v[156:157], v[156:157], v[210:211] op_sel_hi:[1,1,0]
	v_mul_f32_e32 v210, v158, v158
	v_pk_add_f32 v[212:213], v[212:213], v[212:213] op_sel_hi:[0,1]
	v_pk_fma_f32 v[220:221], v[158:159], v[158:159], v[210:211] op_sel_hi:[1,1,0]
	v_mul_f32_e32 v218, v164, v164
	v_mul_f32_e32 v220, v165, v165
	v_mul_f32_e32 v210, v166, v166
	v_mul_f32_e32 v212, v167, v167
	v_pk_add_f32 v[218:219], v[218:219], v[220:221]
	v_pk_add_f32 v[210:211], v[210:211], v[212:213]
	s_nop 0
	v_pk_add_f32 v[210:211], v[218:219], v[210:211]
	s_nop 0
	v_add_f32_e32 v209, v210, v211
	v_and_b32_e32 v211, 64, v207
	v_xor_b32_e32 v210, 16, v207
	v_add_u32_e32 v211, 64, v211
	v_cmp_lt_i32_e32 vcc, v210, v211
	s_nop 1
	v_cndmask_b32_e32 v210, v207, v210, vcc
	v_lshlrev_b32_e32 v210, 2, v210
	ds_bpermute_b32 v210, v210, v209
	s_waitcnt lgkmcnt(0)
	v_add_f32_e32 v209, v209, v210
	v_xor_b32_e32 v210, 32, v207
	v_cmp_lt_i32_e32 vcc, v210, v211
	s_nop 1
	v_cndmask_b32_e32 v210, v207, v210, vcc
	v_lshlrev_b32_e32 v210, 2, v210
	ds_bpermute_b32 v210, v210, v209
	s_waitcnt lgkmcnt(0)
	v_add_f32_e32 v209, v209, v210
	v_max_f32_e32 v213, 0, v209

;     __device__ __forceinline__ void operator()(const f32x4 (&acc)[2][2][4][2], const Unit& u, int wr, int wc, int fr, int fq, PG8_LAS unsigned char* lds) const {
;     ...
;                 const int row = u.pm * BM + ai * HALF + wr * 64 + m * 16 + fr; const int t = row & tmask;
;                 const float rs = __builtin_amdgcn_rsqf((float)rss[row] * (2.3283064365386963e-10f / 1024.0f) + 1e-6f);
;                 f32x4 v[2][2];
; #pragma unroll
;                 for (int bj = 0; bj < 2; ++bj)
; #pragma unroll
;                     for (int n = 0; n < 2; ++n) v[bj][n] = acc[ai][bj][m][n] * rs;
;                 if (type <= 1) {
;                     float ss = 0.f;
; #pragma unroll
;                     for (int bj = 0; bj < 2; ++bj)
; #pragma unroll
;                         for (int n = 0; n < 2; ++n) { const f32x4 x = v[bj][n]; ss += (x[0] * x[0] + x[1] * x[1]) + (x[2] * x[2] + x[3] * x[3]); }
;                     ss += __shfl_xor(ss, 16); ss += __shfl_xor(ss, 32);
;                     float rn = __builtin_amdgcn_rsqf(ss * (1.0f / 64.0f) + 1e-6f); if (type == 0) rn *= QSCALE;
; #pragma unroll
;                     for (int bj = 0; bj < 2; ++bj) { const float pf = (float)(bj == 0 ? (t >> 6) : (t & 63)); f32x4 c, s;
; #pragma unroll
;                         for (int e = 0; e < 4; ++e) { const float a = __builtin_amdgcn_fractf(pf * f4[0][e]); c[e] = __builtin_amdgcn_cosf(a); s[e] = __builtin_amdgcn_sinf(a); }
;                         const f32x4 x1 = v[bj][0] * g[bj][0] * rn, x2 = v[bj][1] * g[bj][1] * rn;
;                         v[bj][0] = x1 * c - x2 * s; v[bj][1] = x1 * s + x2 * c; }
;                 } else if (type >= 3) {
;                     const float sc = type == 3 ? QSCALE : 1.0f; const float tf = (float)t;
; #pragma unroll
;                     for (int n = 0; n < 2; ++n) { f32x4 c, s;
; #pragma unroll
;                         for (int e = 0; e < 4; ++e) { const float a = __builtin_amdgcn_fractf(tf * f4[n][e]); c[e] = __builtin_amdgcn_cosf(a) * sc; s[e] = __builtin_amdgcn_sinf(a) * sc; }
;                         const f32x4 x1 = v[0][n], x2 = v[1][n];
;                         v[0][n] = x1 * c - x2 * s; v[1][n] = x1 * s + x2 * c; }
;                     if (type == 4) { float ks = 0.f;
; #pragma unroll
;                         for (int bj = 0; bj < 2; ++bj)
; #pragma unroll
.LBB0_153:
	v_mad_i64_i32 v[136:137], s[12:13], s70, v208, v[190:191]
	v_lshlrev_b64 v[136:137], 7, v[136:137]
	v_lshl_add_u64 v[140:141], v[176:177], 0, v[136:137]
	v_cvt_pk_bf16_f32 v136, v152, v153
	v_cvt_pk_bf16_f32 v137, v154, v155
	v_cvt_pk_bf16_f32 v138, v160, v161
	v_cvt_pk_bf16_f32 v139, v162, v163
	v_add_u32_e32 v152, s45, v194
	v_permlane16_swap_b32_e32 v136, v138
	v_permlane16_swap_b32_e32 v137, v139
	global_store_dwordx4 v[140:141], v[136:139], off
	v_ashrrev_i32_e32 v153, 31, v152
	s_andn2_b64 vcc, exec, s[76:77]
	v_cvt_pk_bf16_f32 v136, v156, v157
	v_cvt_pk_bf16_f32 v137, v158, v159
	v_cvt_pk_bf16_f32 v138, v164, v165
	v_cvt_pk_bf16_f32 v139, v166, v167
	v_and_b32_e32 v159, s63, v152
	v_permlane16_swap_b32_e32 v136, v138
	v_permlane16_swap_b32_e32 v137, v139
	global_store_dwordx4 v[140:141], v[136:139], off offset:64
	s_nop 1
	s_waitcnt vmcnt(2)
	v_mov_b64_e32 v[136:137], v[224:225]
	v_ffbh_u32_e32 v138, v137
	v_min_u32_e32 v138, 32, v138
	v_lshlrev_b64 v[136:137], v138, v[136:137]
	v_min_u32_e32 v136, 1, v136
	v_or_b32_e32 v136, v137, v136
	v_cvt_f32_u32_e32 v136, v136
	v_sub_u32_e32 v138, 32, v138
	v_cndmask_b32_e64 v137, 0, 1, s[76:77]
	v_cmp_ne_u32_e64 s[12:13], 1, v137
	v_ldexp_f32 v136, v136, v138
	v_fmamk_f32 v136, v136, 0x2a800000, v204
	v_rsq_f32_e32 v136, v136
	s_mov_b64 s[76:77], -1
	v_pk_mul_f32 v[134:135], v[134:135], v[136:137] op_sel_hi:[1,0]
	v_pk_mul_f32 v[132:133], v[132:133], v[136:137] op_sel_hi:[1,0]
	v_pk_mul_f32 v[130:131], v[130:131], v[136:137] op_sel_hi:[1,0]
	v_pk_mul_f32 v[128:129], v[128:129], v[136:137] op_sel_hi:[1,0]
	v_pk_mul_f32 v[126:127], v[126:127], v[136:137] op_sel_hi:[1,0]
	v_pk_mul_f32 v[124:125], v[124:125], v[136:137] op_sel_hi:[1,0]
	v_pk_mul_f32 v[122:123], v[122:123], v[136:137] op_sel_hi:[1,0]
	v_pk_mul_f32 v[120:121], v[120:121], v[136:137] op_sel_hi:[1,0]
	s_cbranch_vccnz .LBB0_158
	v_mov_b64_e32 v[138:139], v[134:135]
	v_mov_b64_e32 v[146:147], v[130:131]
	v_mov_b64_e32 v[142:143], v[126:127]
	v_mov_b64_e32 v[150:151], v[122:123]
	s_and_b64 vcc, exec, s[10:11]
	v_mov_b32_e32 v158, v213
	v_mov_b64_e32 v[136:137], v[132:133]
	v_mov_b64_e32 v[144:145], v[128:129]
	v_mov_b64_e32 v[140:141], v[124:125]
	v_mov_b64_e32 v[148:149], v[120:121]
	s_cbranch_vccnz .LBB0_157
	v_cvt_f32_u32_e32 v149, v159
	s_andn2_b64 vcc, exec, s[74:75]
	v_mov_b32_e32 v158, v213
	v_mul_f32_e32 v140, v30, v149
	v_fract_f32_e32 v141, v140
	v_mul_f32_e32 v136, v28, v149
	v_mul_f32_e32 v137, v29, v149
	v_cos_f32_e32 v140, v141
	v_sin_f32_e32 v142, v141
	v_mul_f32_e32 v141, v31, v149
	v_fract_f32_e32 v138, v136
	v_fract_f32_e32 v139, v137
	v_fract_f32_e32 v143, v141
	v_cos_f32_e32 v136, v138
	v_sin_f32_e32 v138, v138
	v_cos_f32_e32 v137, v139
	v_cos_f32_e32 v141, v143
	v_sin_f32_e32 v143, v143
	v_sin_f32_e32 v139, v139
	v_pk_mul_f32 v[144:145], v[188:189], v[136:137] op_sel_hi:[0,1]
	v_pk_mul_f32 v[140:141], v[188:189], v[140:141] op_sel_hi:[0,1]
	v_pk_mul_f32 v[142:143], v[188:189], v[142:143] op_sel_hi:[0,1]
	v_pk_mul_f32 v[146:147], v[188:189], v[138:139] op_sel_hi:[0,1]
	v_pk_mul_f32 v[136:137], v[146:147], v[124:125]
	v_pk_mul_f32 v[138:139], v[142:143], v[126:127]
	v_pk_fma_f32 v[136:137], v[144:145], v[132:133], v[136:137] neg_lo:[0,0,1] neg_hi:[0,0,1]
	v_pk_fma_f32 v[138:139], v[140:141], v[134:135], v[138:139] neg_lo:[0,0,1] neg_hi:[0,0,1]
	v_pk_mul_f32 v[144:145], v[144:145], v[124:125]
	v_pk_mul_f32 v[140:141], v[140:141], v[126:127]
	v_mul_f32_e32 v148, v54, v149
	v_pk_fma_f32 v[142:143], v[142:143], v[134:135], v[140:141]
	v_pk_fma_f32 v[140:141], v[146:147], v[132:133], v[144:145]
	v_mul_f32_e32 v144, v52, v149
	v_fract_f32_e32 v145, v144
	v_cos_f32_e32 v144, v145
	v_sin_f32_e32 v146, v145
	v_mul_f32_e32 v145, v53, v149
	v_mul_f32_e32 v149, v55, v149
	v_fract_f32_e32 v147, v145
	v_fract_f32_e32 v150, v148
	v_fract_f32_e32 v151, v149
	v_cos_f32_e32 v145, v147
	v_cos_f32_e32 v148, v150
	v_sin_f32_e32 v150, v150
	v_cos_f32_e32 v149, v151
	v_sin_f32_e32 v151, v151
	v_sin_f32_e32 v147, v147
	v_pk_mul_f32 v[154:155], v[188:189], v[144:145] op_sel_hi:[0,1]
	v_pk_mul_f32 v[148:149], v[188:189], v[148:149] op_sel_hi:[0,1]
	v_pk_mul_f32 v[150:151], v[188:189], v[150:151] op_sel_hi:[0,1]
	v_pk_mul_f32 v[156:157], v[188:189], v[146:147] op_sel_hi:[0,1]
	v_pk_mul_f32 v[144:145], v[156:157], v[120:121]
	v_pk_mul_f32 v[146:147], v[150:151], v[122:123]
	v_pk_fma_f32 v[144:145], v[154:155], v[128:129], v[144:145] neg_lo:[0,0,1] neg_hi:[0,0,1]
	v_pk_fma_f32 v[146:147], v[148:149], v[130:131], v[146:147] neg_lo:[0,0,1] neg_hi:[0,0,1]
	v_pk_mul_f32 v[154:155], v[154:155], v[120:121]
	v_pk_mul_f32 v[148:149], v[148:149], v[122:123]
	s_nop 0
	v_pk_fma_f32 v[150:151], v[150:151], v[130:131], v[148:149]
	v_pk_fma_f32 v[148:149], v[156:157], v[128:129], v[154:155]
	s_cbranch_vccnz .LBB0_157
	v_pk_mul_f32 v[154:155], v[138:139], v[138:139]
	v_pk_mul_f32 v[156:157], v[136:137], v[136:137]
	s_nop 0
	v_pk_mov_b32 v[160:161], v[156:157], v[154:155] op_sel:[1,0]
	v_mov_b32_e32 v157, v155
	v_pk_add_f32 v[154:155], v[160:161], v[156:157]
	v_pk_mul_f32 v[156:157], v[146:147], v[146:147]
	v_pk_add_f32 v[154:155], v[154:155], v[154:155] op_sel_hi:[0,1]
	v_pk_mul_f32 v[160:161], v[144:145], v[144:145]
	v_mul_f32_e32 v154, v140, v140
	v_pk_mov_b32 v[162:163], v[160:161], v[156:157] op_sel:[1,0]
	v_mov_b32_e32 v161, v157
	v_pk_add_f32 v[156:157], v[162:163], v[160:161]
	v_pk_fma_f32 v[160:161], v[140:141], v[140:141], v[154:155] op_sel_hi:[1,1,0]
	v_mul_f32_e32 v154, v142, v142
	v_pk_add_f32 v[156:157], v[156:157], v[156:157] op_sel_hi:[0,1]
	v_pk_fma_f32 v[162:163], v[142:143], v[142:143], v[154:155] op_sel_hi:[1,1,0]
	v_mul_f32_e32 v160, v148, v148
	v_mul_f32_e32 v162, v149, v149
	v_mul_f32_e32 v154, v150, v150
	v_mul_f32_e32 v156, v151, v151
	v_pk_add_f32 v[160:161], v[160:161], v[162:163]
	v_pk_add_f32 v[154:155], v[154:155], v[156:157]
	v_and_b32_e32 v156, 64, v207
	v_pk_add_f32 v[154:155], v[160:161], v[154:155]
	v_add_u32_e32 v156, 64, v156
	v_add_f32_e32 v154, v154, v155
	v_xor_b32_e32 v155, 16, v207
	v_cmp_lt_i32_e32 vcc, v155, v156
	s_nop 1
	v_cndmask_b32_e32 v155, v207, v155, vcc
	v_lshlrev_b32_e32 v155, 2, v155
	ds_bpermute_b32 v155, v155, v154
	s_waitcnt lgkmcnt(0)
	v_add_f32_e32 v154, v154, v155
	v_xor_b32_e32 v155, 32, v207
	v_cmp_lt_i32_e32 vcc, v155, v156
	s_nop 1
	v_cndmask_b32_e32 v155, v207, v155, vcc
	v_lshlrev_b32_e32 v155, 2, v155
	ds_bpermute_b32 v155, v155, v154
	s_waitcnt lgkmcnt(0)
	v_add_f32_e32 v154, v154, v155
	v_max_f32_e32 v155, v213, v213
	v_max_f32_e32 v158, v155, v154

;     __device__ __forceinline__ void operator()(const f32x4 (&acc)[2][2][4][2], const Unit& u, int wr, int wc, int fr, int fq, PG8_LAS unsigned char* lds) const {
;     ...
;                 const int row = u.pm * BM + ai * HALF + wr * 64 + m * 16 + fr; const int t = row & tmask;
;                 const float rs = __builtin_amdgcn_rsqf((float)rss[row] * (2.3283064365386963e-10f / 1024.0f) + 1e-6f);
;                 f32x4 v[2][2];
; #pragma unroll
;                 for (int bj = 0; bj < 2; ++bj)
; #pragma unroll
;                     for (int n = 0; n < 2; ++n) v[bj][n] = acc[ai][bj][m][n] * rs;
;                 if (type <= 1) {
;                     float ss = 0.f;
; #pragma unroll
;                     for (int bj = 0; bj < 2; ++bj)
; #pragma unroll
;                         for (int n = 0; n < 2; ++n) { const f32x4 x = v[bj][n]; ss += (x[0] * x[0] + x[1] * x[1]) + (x[2] * x[2] + x[3] * x[3]); }
;                     ss += __shfl_xor(ss, 16); ss += __shfl_xor(ss, 32);
;                     float rn = __builtin_amdgcn_rsqf(ss * (1.0f / 64.0f) + 1e-6f); if (type == 0) rn *= QSCALE;
; #pragma unroll
;                     for (int bj = 0; bj < 2; ++bj) { const float pf = (float)(bj == 0 ? (t >> 6) : (t & 63)); f32x4 c, s;
; #pragma unroll
;                         for (int e = 0; e < 4; ++e) { const float a = __builtin_amdgcn_fractf(pf * f4[0][e]); c[e] = __builtin_amdgcn_cosf(a); s[e] = __builtin_amdgcn_sinf(a); }
;                         const f32x4 x1 = v[bj][0] * g[bj][0] * rn, x2 = v[bj][1] * g[bj][1] * rn;
;                         v[bj][0] = x1 * c - x2 * s; v[bj][1] = x1 * s + x2 * c; }
;                 } else if (type >= 3) {
;                     const float sc = type == 3 ? QSCALE : 1.0f; const float tf = (float)t;
; #pragma unroll
;                     for (int n = 0; n < 2; ++n) { f32x4 c, s;
; #pragma unroll
;                         for (int e = 0; e < 4; ++e) { const float a = __builtin_amdgcn_fractf(tf * f4[n][e]); c[e] = __builtin_amdgcn_cosf(a) * sc; s[e] = __builtin_amdgcn_sinf(a) * sc; }
;                         const f32x4 x1 = v[0][n], x2 = v[1][n];
;                         v[0][n] = x1 * c - x2 * s; v[1][n] = x1 * s + x2 * c; }
;                     if (type == 4) { float ks = 0.f;
; #pragma unroll
;                         for (int bj = 0; bj < 2; ++bj)
; #pragma unroll
.LBB0_160:
	s_mul_hi_i32 s77, s70, 0x14000
	s_mul_i32 s76, s70, 0x14000
	v_lshl_add_u64 v[120:121], s[76:77], 0, v[152:153]
	v_lshlrev_b64 v[120:121], 7, v[120:121]
	v_lshl_add_u64 v[124:125], v[176:177], 0, v[120:121]
	v_cvt_pk_bf16_f32 v120, v136, v137
	v_cvt_pk_bf16_f32 v121, v138, v139
	v_cvt_pk_bf16_f32 v122, v144, v145
	v_cvt_pk_bf16_f32 v123, v146, v147
	v_add_u32_e32 v136, s45, v196
	v_permlane16_swap_b32_e32 v120, v122
	v_permlane16_swap_b32_e32 v121, v123
	global_store_dwordx4 v[124:125], v[120:123], off
	v_ashrrev_i32_e32 v137, 31, v136
	s_and_b64 vcc, exec, s[12:13]
	v_cvt_pk_bf16_f32 v120, v140, v141
	v_cvt_pk_bf16_f32 v121, v142, v143
	v_cvt_pk_bf16_f32 v122, v148, v149
	v_cvt_pk_bf16_f32 v123, v150, v151
	v_and_b32_e32 v143, s63, v136
	v_permlane16_swap_b32_e32 v120, v122
	v_permlane16_swap_b32_e32 v121, v123
	global_store_dwordx4 v[124:125], v[120:123], off offset:64
	s_mov_b64 s[78:79], -1
	s_nop 0
	s_waitcnt vmcnt(4)
	v_mov_b64_e32 v[120:121], v[226:227]
	v_ffbh_u32_e32 v122, v121
	v_min_u32_e32 v122, 32, v122
	v_lshlrev_b64 v[120:121], v122, v[120:121]
	v_min_u32_e32 v120, 1, v120
	v_or_b32_e32 v120, v121, v120
	v_cvt_f32_u32_e32 v120, v120
	v_sub_u32_e32 v121, 32, v122
	v_ldexp_f32 v120, v120, v121
	v_fmamk_f32 v120, v120, 0x2a800000, v204
	v_rsq_f32_e32 v120, v120
	s_nop 0
	v_pk_mul_f32 v[118:119], v[118:119], v[120:121] op_sel_hi:[1,0]
	v_pk_mul_f32 v[116:117], v[116:117], v[120:121] op_sel_hi:[1,0]
	v_pk_mul_f32 v[114:115], v[114:115], v[120:121] op_sel_hi:[1,0]
	v_pk_mul_f32 v[112:113], v[112:113], v[120:121] op_sel_hi:[1,0]
	v_pk_mul_f32 v[110:111], v[110:111], v[120:121] op_sel_hi:[1,0]
	v_pk_mul_f32 v[108:109], v[108:109], v[120:121] op_sel_hi:[1,0]
	v_pk_mul_f32 v[106:107], v[106:107], v[120:121] op_sel_hi:[1,0]
	v_pk_mul_f32 v[104:105], v[104:105], v[120:121] op_sel_hi:[1,0]
	s_cbranch_vccnz .LBB0_165
	v_mov_b64_e32 v[122:123], v[118:119]
	v_mov_b64_e32 v[130:131], v[114:115]
	v_mov_b64_e32 v[126:127], v[110:111]
	v_mov_b64_e32 v[134:135], v[106:107]
	s_and_b64 vcc, exec, s[10:11]
	v_mov_b32_e32 v142, v158
	v_mov_b64_e32 v[120:121], v[116:117]
	v_mov_b64_e32 v[128:129], v[112:113]
	v_mov_b64_e32 v[124:125], v[108:109]
	v_mov_b64_e32 v[132:133], v[104:105]
	s_cbranch_vccnz .LBB0_164
	v_cvt_f32_u32_e32 v133, v143
	s_andn2_b64 vcc, exec, s[74:75]
	v_mov_b32_e32 v142, v158
	v_mul_f32_e32 v124, v30, v133
	v_fract_f32_e32 v125, v124
	v_mul_f32_e32 v120, v28, v133
	v_mul_f32_e32 v121, v29, v133
	v_cos_f32_e32 v124, v125
	v_sin_f32_e32 v126, v125
	v_mul_f32_e32 v125, v31, v133
	v_fract_f32_e32 v122, v120
	v_fract_f32_e32 v123, v121
	v_fract_f32_e32 v127, v125
	v_cos_f32_e32 v120, v122
	v_sin_f32_e32 v122, v122
	v_cos_f32_e32 v121, v123
	v_cos_f32_e32 v125, v127
	v_sin_f32_e32 v127, v127
	v_sin_f32_e32 v123, v123
	v_pk_mul_f32 v[128:129], v[188:189], v[120:121] op_sel_hi:[0,1]
	v_pk_mul_f32 v[124:125], v[188:189], v[124:125] op_sel_hi:[0,1]
	v_pk_mul_f32 v[126:127], v[188:189], v[126:127] op_sel_hi:[0,1]
	v_pk_mul_f32 v[130:131], v[188:189], v[122:123] op_sel_hi:[0,1]
	v_pk_mul_f32 v[120:121], v[130:131], v[108:109]
	v_pk_mul_f32 v[122:123], v[126:127], v[110:111]
	v_pk_fma_f32 v[120:121], v[128:129], v[116:117], v[120:121] neg_lo:[0,0,1] neg_hi:[0,0,1]
	v_pk_fma_f32 v[122:123], v[124:125], v[118:119], v[122:123] neg_lo:[0,0,1] neg_hi:[0,0,1]
	v_pk_mul_f32 v[128:129], v[128:129], v[108:109]
	v_pk_mul_f32 v[124:125], v[124:125], v[110:111]
	v_mul_f32_e32 v132, v54, v133
	v_pk_fma_f32 v[126:127], v[126:127], v[118:119], v[124:125]
	v_pk_fma_f32 v[124:125], v[130:131], v[116:117], v[128:129]
	v_mul_f32_e32 v128, v52, v133
	v_fract_f32_e32 v129, v128
	v_cos_f32_e32 v128, v129
	v_sin_f32_e32 v130, v129
	v_mul_f32_e32 v129, v53, v133
	v_mul_f32_e32 v133, v55, v133
	v_fract_f32_e32 v131, v129
	v_fract_f32_e32 v134, v132
	v_fract_f32_e32 v135, v133
	v_cos_f32_e32 v129, v131
	v_cos_f32_e32 v132, v134
	v_sin_f32_e32 v134, v134
	v_cos_f32_e32 v133, v135
	v_sin_f32_e32 v135, v135
	v_sin_f32_e32 v131, v131
	v_pk_mul_f32 v[138:139], v[188:189], v[128:129] op_sel_hi:[0,1]
	v_pk_mul_f32 v[132:133], v[188:189], v[132:133] op_sel_hi:[0,1]
	v_pk_mul_f32 v[134:135], v[188:189], v[134:135] op_sel_hi:[0,1]
	v_pk_mul_f32 v[140:141], v[188:189], v[130:131] op_sel_hi:[0,1]
	v_pk_mul_f32 v[128:129], v[140:141], v[104:105]
	v_pk_mul_f32 v[130:131], v[134:135], v[106:107]
	v_pk_fma_f32 v[128:129], v[138:139], v[112:113], v[128:129] neg_lo:[0,0,1] neg_hi:[0,0,1]
	v_pk_fma_f32 v[130:131], v[132:133], v[114:115], v[130:131] neg_lo:[0,0,1] neg_hi:[0,0,1]
	v_pk_mul_f32 v[138:139], v[138:139], v[104:105]
	v_pk_mul_f32 v[132:133], v[132:133], v[106:107]
	s_nop 0
	v_pk_fma_f32 v[134:135], v[134:135], v[114:115], v[132:133]
	v_pk_fma_f32 v[132:133], v[140:141], v[112:113], v[138:139]
	s_cbranch_vccnz .LBB0_164
	v_pk_mul_f32 v[138:139], v[122:123], v[122:123]
	v_pk_mul_f32 v[140:141], v[120:121], v[120:121]
	s_nop 0
	v_pk_mov_b32 v[144:145], v[140:141], v[138:139] op_sel:[1,0]
	v_mov_b32_e32 v141, v139
	v_pk_add_f32 v[138:139], v[144:145], v[140:141]
	v_pk_mul_f32 v[140:141], v[130:131], v[130:131]
	v_pk_add_f32 v[138:139], v[138:139], v[138:139] op_sel_hi:[0,1]
	v_pk_mul_f32 v[144:145], v[128:129], v[128:129]
	v_mul_f32_e32 v138, v124, v124
	v_pk_mov_b32 v[146:147], v[144:145], v[140:141] op_sel:[1,0]
	v_mov_b32_e32 v145, v141
	v_pk_add_f32 v[140:141], v[146:147], v[144:145]
	v_pk_fma_f32 v[144:145], v[124:125], v[124:125], v[138:139] op_sel_hi:[1,1,0]
	v_mul_f32_e32 v138, v126, v126
	v_pk_add_f32 v[140:141], v[140:141], v[140:141] op_sel_hi:[0,1]
	v_pk_fma_f32 v[146:147], v[126:127], v[126:127], v[138:139] op_sel_hi:[1,1,0]
	v_mul_f32_e32 v144, v132, v132
	v_mul_f32_e32 v146, v133, v133
	v_mul_f32_e32 v138, v134, v134
	v_mul_f32_e32 v140, v135, v135
	v_pk_add_f32 v[144:145], v[144:145], v[146:147]
	v_pk_add_f32 v[138:139], v[138:139], v[140:141]
	v_and_b32_e32 v140, 64, v207
	v_pk_add_f32 v[138:139], v[144:145], v[138:139]
	v_add_u32_e32 v140, 64, v140
	v_add_f32_e32 v138, v138, v139
	v_xor_b32_e32 v139, 16, v207
	v_cmp_lt_i32_e32 vcc, v139, v140
	s_nop 1
	v_cndmask_b32_e32 v139, v207, v139, vcc
	v_lshlrev_b32_e32 v139, 2, v139
	ds_bpermute_b32 v139, v139, v138
	s_waitcnt lgkmcnt(0)
	v_add_f32_e32 v138, v138, v139
	v_xor_b32_e32 v139, 32, v207
	v_cmp_lt_i32_e32 vcc, v139, v140
	s_nop 1
	v_cndmask_b32_e32 v139, v207, v139, vcc
	v_lshlrev_b32_e32 v139, 2, v139
	ds_bpermute_b32 v139, v139, v138
	s_waitcnt lgkmcnt(0)
	v_add_f32_e32 v138, v138, v139
	v_max_f32_e32 v139, v158, v158
	v_max_f32_e32 v142, v139, v138

;     __device__ __forceinline__ void operator()(const f32x4 (&acc)[2][2][4][2], const Unit& u, int wr, int wc, int fr, int fq, PG8_LAS unsigned char* lds) const {
;     ...
;                 const int row = u.pm * BM + ai * HALF + wr * 64 + m * 16 + fr; const int t = row & tmask;
;                 const float rs = __builtin_amdgcn_rsqf((float)rss[row] * (2.3283064365386963e-10f / 1024.0f) + 1e-6f);
;                 f32x4 v[2][2];
; #pragma unroll
;                 for (int bj = 0; bj < 2; ++bj)
; #pragma unroll
;                     for (int n = 0; n < 2; ++n) v[bj][n] = acc[ai][bj][m][n] * rs;
;                 if (type <= 1) {
;                     float ss = 0.f;
; #pragma unroll
;                     for (int bj = 0; bj < 2; ++bj)
; #pragma unroll
;                         for (int n = 0; n < 2; ++n) { const f32x4 x = v[bj][n]; ss += (x[0] * x[0] + x[1] * x[1]) + (x[2] * x[2] + x[3] * x[3]); }
;                     ss += __shfl_xor(ss, 16); ss += __shfl_xor(ss, 32);
;                     float rn = __builtin_amdgcn_rsqf(ss * (1.0f / 64.0f) + 1e-6f); if (type == 0) rn *= QSCALE;
; #pragma unroll
;                     for (int bj = 0; bj < 2; ++bj) { const float pf = (float)(bj == 0 ? (t >> 6) : (t & 63)); f32x4 c, s;
; #pragma unroll
;                         for (int e = 0; e < 4; ++e) { const float a = __builtin_amdgcn_fractf(pf * f4[0][e]); c[e] = __builtin_amdgcn_cosf(a); s[e] = __builtin_amdgcn_sinf(a); }
;                         const f32x4 x1 = v[bj][0] * g[bj][0] * rn, x2 = v[bj][1] * g[bj][1] * rn;
;                         v[bj][0] = x1 * c - x2 * s; v[bj][1] = x1 * s + x2 * c; }
;                 } else if (type >= 3) {
;                     const float sc = type == 3 ? QSCALE : 1.0f; const float tf = (float)t;
; #pragma unroll
;                     for (int n = 0; n < 2; ++n) { f32x4 c, s;
; #pragma unroll
;                         for (int e = 0; e < 4; ++e) { const float a = __builtin_amdgcn_fractf(tf * f4[n][e]); c[e] = __builtin_amdgcn_cosf(a) * sc; s[e] = __builtin_amdgcn_sinf(a) * sc; }
;                         const f32x4 x1 = v[0][n], x2 = v[1][n];
;                         v[0][n] = x1 * c - x2 * s; v[1][n] = x1 * s + x2 * c; }
;                     if (type == 4) { float ks = 0.f;
; #pragma unroll
;                         for (int bj = 0; bj < 2; ++bj)
; #pragma unroll
.LBB0_167:
	v_lshl_add_u64 v[104:105], s[76:77], 0, v[136:137]
	v_lshlrev_b64 v[104:105], 7, v[104:105]
	v_lshl_add_u64 v[108:109], v[176:177], 0, v[104:105]
	v_cvt_pk_bf16_f32 v104, v120, v121
	v_cvt_pk_bf16_f32 v105, v122, v123
	v_cvt_pk_bf16_f32 v106, v128, v129
	v_cvt_pk_bf16_f32 v107, v130, v131
	v_add_u32_e32 v120, s45, v198
	v_permlane16_swap_b32_e32 v104, v106
	v_permlane16_swap_b32_e32 v105, v107
	global_store_dwordx4 v[108:109], v[104:107], off
	v_ashrrev_i32_e32 v121, 31, v120
	s_and_b64 vcc, exec, s[12:13]
	v_cvt_pk_bf16_f32 v104, v124, v125
	v_cvt_pk_bf16_f32 v105, v126, v127
	v_cvt_pk_bf16_f32 v106, v132, v133
	v_cvt_pk_bf16_f32 v107, v134, v135
	v_and_b32_e32 v127, s63, v120
	v_permlane16_swap_b32_e32 v104, v106
	v_permlane16_swap_b32_e32 v105, v107
	global_store_dwordx4 v[108:109], v[104:107], off offset:64
	s_mov_b64 s[78:79], -1
	s_nop 0
	s_waitcnt vmcnt(6)
	v_mov_b64_e32 v[104:105], v[228:229]
	v_ffbh_u32_e32 v106, v105
	v_min_u32_e32 v106, 32, v106
	v_lshlrev_b64 v[104:105], v106, v[104:105]
	v_min_u32_e32 v104, 1, v104
	v_or_b32_e32 v104, v105, v104
	v_cvt_f32_u32_e32 v104, v104
	v_sub_u32_e32 v105, 32, v106
	v_ldexp_f32 v104, v104, v105
	v_fmamk_f32 v104, v104, 0x2a800000, v204
	v_rsq_f32_e32 v104, v104
	s_nop 0
	v_pk_mul_f32 v[102:103], v[102:103], v[104:105] op_sel_hi:[1,0]
	v_pk_mul_f32 v[100:101], v[100:101], v[104:105] op_sel_hi:[1,0]
	v_pk_mul_f32 v[98:99], v[98:99], v[104:105] op_sel_hi:[1,0]
	v_pk_mul_f32 v[96:97], v[96:97], v[104:105] op_sel_hi:[1,0]
	v_pk_mul_f32 v[94:95], v[94:95], v[104:105] op_sel_hi:[1,0]
	v_pk_mul_f32 v[92:93], v[92:93], v[104:105] op_sel_hi:[1,0]
	v_pk_mul_f32 v[90:91], v[90:91], v[104:105] op_sel_hi:[1,0]
	v_pk_mul_f32 v[88:89], v[88:89], v[104:105] op_sel_hi:[1,0]
	s_cbranch_vccnz .LBB0_172
	v_mov_b64_e32 v[106:107], v[102:103]
	v_mov_b64_e32 v[114:115], v[98:99]
	v_mov_b64_e32 v[110:111], v[94:95]
	v_mov_b64_e32 v[118:119], v[90:91]
	s_and_b64 vcc, exec, s[10:11]
	v_mov_b32_e32 v126, v142
	v_mov_b64_e32 v[104:105], v[100:101]
	v_mov_b64_e32 v[112:113], v[96:97]
	v_mov_b64_e32 v[108:109], v[92:93]
	v_mov_b64_e32 v[116:117], v[88:89]
	s_cbranch_vccnz .LBB0_171
	v_cvt_f32_u32_e32 v117, v127
	s_andn2_b64 vcc, exec, s[74:75]
	v_mov_b32_e32 v126, v142
	v_mul_f32_e32 v108, v30, v117
	v_fract_f32_e32 v109, v108
	v_mul_f32_e32 v104, v28, v117
	v_mul_f32_e32 v105, v29, v117
	v_cos_f32_e32 v108, v109
	v_sin_f32_e32 v110, v109
	v_mul_f32_e32 v109, v31, v117
	v_fract_f32_e32 v106, v104
	v_fract_f32_e32 v107, v105
	v_fract_f32_e32 v111, v109
	v_cos_f32_e32 v104, v106
	v_sin_f32_e32 v106, v106
	v_cos_f32_e32 v105, v107
	v_cos_f32_e32 v109, v111
	v_sin_f32_e32 v111, v111
	v_sin_f32_e32 v107, v107
	v_pk_mul_f32 v[112:113], v[188:189], v[104:105] op_sel_hi:[0,1]
	v_pk_mul_f32 v[108:109], v[188:189], v[108:109] op_sel_hi:[0,1]
	v_pk_mul_f32 v[110:111], v[188:189], v[110:111] op_sel_hi:[0,1]
	v_pk_mul_f32 v[114:115], v[188:189], v[106:107] op_sel_hi:[0,1]
	v_pk_mul_f32 v[104:105], v[114:115], v[92:93]
	v_pk_mul_f32 v[106:107], v[110:111], v[94:95]
	v_pk_fma_f32 v[104:105], v[112:113], v[100:101], v[104:105] neg_lo:[0,0,1] neg_hi:[0,0,1]
	v_pk_fma_f32 v[106:107], v[108:109], v[102:103], v[106:107] neg_lo:[0,0,1] neg_hi:[0,0,1]
	v_pk_mul_f32 v[112:113], v[112:113], v[92:93]
	v_pk_mul_f32 v[108:109], v[108:109], v[94:95]
	v_mul_f32_e32 v116, v54, v117
	v_pk_fma_f32 v[110:111], v[110:111], v[102:103], v[108:109]
	v_pk_fma_f32 v[108:109], v[114:115], v[100:101], v[112:113]
	v_mul_f32_e32 v112, v52, v117
	v_fract_f32_e32 v113, v112
	v_cos_f32_e32 v112, v113
	v_sin_f32_e32 v114, v113
	v_mul_f32_e32 v113, v53, v117
	v_mul_f32_e32 v117, v55, v117
	v_fract_f32_e32 v115, v113
	v_fract_f32_e32 v118, v116
	v_fract_f32_e32 v119, v117
	v_cos_f32_e32 v113, v115
	v_cos_f32_e32 v116, v118
	v_sin_f32_e32 v118, v118
	v_cos_f32_e32 v117, v119
	v_sin_f32_e32 v119, v119
	v_sin_f32_e32 v115, v115
	v_pk_mul_f32 v[122:123], v[188:189], v[112:113] op_sel_hi:[0,1]
	v_pk_mul_f32 v[116:117], v[188:189], v[116:117] op_sel_hi:[0,1]
	v_pk_mul_f32 v[118:119], v[188:189], v[118:119] op_sel_hi:[0,1]
	v_pk_mul_f32 v[124:125], v[188:189], v[114:115] op_sel_hi:[0,1]
	v_pk_mul_f32 v[112:113], v[124:125], v[88:89]
	v_pk_mul_f32 v[114:115], v[118:119], v[90:91]
	v_pk_fma_f32 v[112:113], v[122:123], v[96:97], v[112:113] neg_lo:[0,0,1] neg_hi:[0,0,1]
	v_pk_fma_f32 v[114:115], v[116:117], v[98:99], v[114:115] neg_lo:[0,0,1] neg_hi:[0,0,1]
	v_pk_mul_f32 v[122:123], v[122:123], v[88:89]
	v_pk_mul_f32 v[116:117], v[116:117], v[90:91]
	s_nop 0
	v_pk_fma_f32 v[118:119], v[118:119], v[98:99], v[116:117]
	v_pk_fma_f32 v[116:117], v[124:125], v[96:97], v[122:123]
	s_cbranch_vccnz .LBB0_171
	v_pk_mul_f32 v[122:123], v[106:107], v[106:107]
	v_pk_mul_f32 v[124:125], v[104:105], v[104:105]
	s_nop 0
	v_pk_mov_b32 v[128:129], v[124:125], v[122:123] op_sel:[1,0]
	v_mov_b32_e32 v125, v123
	v_pk_add_f32 v[122:123], v[128:129], v[124:125]
	v_pk_mul_f32 v[124:125], v[114:115], v[114:115]
	v_pk_add_f32 v[122:123], v[122:123], v[122:123] op_sel_hi:[0,1]
	v_pk_mul_f32 v[128:129], v[112:113], v[112:113]
	v_mul_f32_e32 v122, v108, v108
	v_pk_mov_b32 v[130:131], v[128:129], v[124:125] op_sel:[1,0]
	v_mov_b32_e32 v129, v125
	v_pk_add_f32 v[124:125], v[130:131], v[128:129]
	v_pk_fma_f32 v[128:129], v[108:109], v[108:109], v[122:123] op_sel_hi:[1,1,0]
	v_mul_f32_e32 v122, v110, v110
	v_pk_add_f32 v[124:125], v[124:125], v[124:125] op_sel_hi:[0,1]
	v_pk_fma_f32 v[130:131], v[110:111], v[110:111], v[122:123] op_sel_hi:[1,1,0]
	v_mul_f32_e32 v128, v116, v116
	v_mul_f32_e32 v130, v117, v117
	v_mul_f32_e32 v122, v118, v118
	v_mul_f32_e32 v124, v119, v119
	v_pk_add_f32 v[128:129], v[128:129], v[130:131]
	v_pk_add_f32 v[122:123], v[122:123], v[124:125]
	v_and_b32_e32 v124, 64, v207
	v_pk_add_f32 v[122:123], v[128:129], v[122:123]
	v_add_u32_e32 v124, 64, v124
	v_add_f32_e32 v122, v122, v123
	v_xor_b32_e32 v123, 16, v207
	v_cmp_lt_i32_e32 vcc, v123, v124
	s_nop 1
	v_cndmask_b32_e32 v123, v207, v123, vcc
	v_lshlrev_b32_e32 v123, 2, v123
	ds_bpermute_b32 v123, v123, v122
	s_waitcnt lgkmcnt(0)
	v_add_f32_e32 v122, v122, v123
	v_xor_b32_e32 v123, 32, v207
	v_cmp_lt_i32_e32 vcc, v123, v124
	s_nop 1
	v_cndmask_b32_e32 v123, v207, v123, vcc
	v_lshlrev_b32_e32 v123, 2, v123
	ds_bpermute_b32 v123, v123, v122
	s_waitcnt lgkmcnt(0)
	v_add_f32_e32 v122, v122, v123
	v_max_f32_e32 v123, v142, v142
	v_max_f32_e32 v126, v123, v122

;     __device__ __forceinline__ void operator()(const f32x4 (&acc)[2][2][4][2], const Unit& u, int wr, int wc, int fr, int fq, PG8_LAS unsigned char* lds) const {
;     ...
;                 const int row = u.pm * BM + ai * HALF + wr * 64 + m * 16 + fr; const int t = row & tmask;
;                 const float rs = __builtin_amdgcn_rsqf((float)rss[row] * (2.3283064365386963e-10f / 1024.0f) + 1e-6f);
;                 f32x4 v[2][2];
; #pragma unroll
;                 for (int bj = 0; bj < 2; ++bj)
; #pragma unroll
;                     for (int n = 0; n < 2; ++n) v[bj][n] = acc[ai][bj][m][n] * rs;
;                 if (type <= 1) {
;                     float ss = 0.f;
; #pragma unroll
;                     for (int bj = 0; bj < 2; ++bj)
; #pragma unroll
;                         for (int n = 0; n < 2; ++n) { const f32x4 x = v[bj][n]; ss += (x[0] * x[0] + x[1] * x[1]) + (x[2] * x[2] + x[3] * x[3]); }
;                     ss += __shfl_xor(ss, 16); ss += __shfl_xor(ss, 32);
;                     float rn = __builtin_amdgcn_rsqf(ss * (1.0f / 64.0f) + 1e-6f); if (type == 0) rn *= QSCALE;
; #pragma unroll
;                     for (int bj = 0; bj < 2; ++bj) { const float pf = (float)(bj == 0 ? (t >> 6) : (t & 63)); f32x4 c, s;
; #pragma unroll
;                         for (int e = 0; e < 4; ++e) { const float a = __builtin_amdgcn_fractf(pf * f4[0][e]); c[e] = __builtin_amdgcn_cosf(a); s[e] = __builtin_amdgcn_sinf(a); }
;                         const f32x4 x1 = v[bj][0] * g[bj][0] * rn, x2 = v[bj][1] * g[bj][1] * rn;
;                         v[bj][0] = x1 * c - x2 * s; v[bj][1] = x1 * s + x2 * c; }
;                 } else if (type >= 3) {
;                     const float sc = type == 3 ? QSCALE : 1.0f; const float tf = (float)t;
; #pragma unroll
;                     for (int n = 0; n < 2; ++n) { f32x4 c, s;
; #pragma unroll
;                         for (int e = 0; e < 4; ++e) { const float a = __builtin_amdgcn_fractf(tf * f4[n][e]); c[e] = __builtin_amdgcn_cosf(a) * sc; s[e] = __builtin_amdgcn_sinf(a) * sc; }
;                         const f32x4 x1 = v[0][n], x2 = v[1][n];
;                         v[0][n] = x1 * c - x2 * s; v[1][n] = x1 * s + x2 * c; }
;                     if (type == 4) { float ks = 0.f;
; #pragma unroll
;                         for (int bj = 0; bj < 2; ++bj)
; #pragma unroll
.LBB0_174:
	v_lshl_add_u64 v[88:89], s[76:77], 0, v[120:121]
	v_lshlrev_b64 v[88:89], 7, v[88:89]
	v_lshl_add_u64 v[92:93], v[176:177], 0, v[88:89]
	v_cvt_pk_bf16_f32 v88, v104, v105
	v_cvt_pk_bf16_f32 v89, v106, v107
	v_cvt_pk_bf16_f32 v90, v112, v113
	v_cvt_pk_bf16_f32 v91, v114, v115
	v_add_u32_e32 v104, 0x80, v190
	v_permlane16_swap_b32_e32 v88, v90
	v_permlane16_swap_b32_e32 v89, v91
	global_store_dwordx4 v[92:93], v[88:91], off
	v_ashrrev_i32_e32 v105, 31, v104
	s_and_b64 vcc, exec, s[12:13]
	v_cvt_pk_bf16_f32 v88, v108, v109
	v_cvt_pk_bf16_f32 v89, v110, v111
	v_cvt_pk_bf16_f32 v90, v116, v117
	v_cvt_pk_bf16_f32 v91, v118, v119
	v_and_b32_e32 v107, s63, v104
	v_permlane16_swap_b32_e32 v88, v90
	v_permlane16_swap_b32_e32 v89, v91
	global_store_dwordx4 v[92:93], v[88:91], off offset:64
	s_mov_b64 s[78:79], -1
	s_nop 0
	s_waitcnt vmcnt(8)
	v_mov_b64_e32 v[88:89], v[230:231]
	v_ffbh_u32_e32 v90, v89
	v_min_u32_e32 v90, 32, v90
	v_lshlrev_b64 v[88:89], v90, v[88:89]
	v_min_u32_e32 v88, 1, v88
	v_or_b32_e32 v88, v89, v88
	v_cvt_f32_u32_e32 v88, v88
	v_sub_u32_e32 v89, 32, v90
	v_ldexp_f32 v88, v88, v89
	v_fmamk_f32 v88, v88, 0x2a800000, v204
	v_rsq_f32_e32 v88, v88
	s_nop 0
	v_pk_mul_f32 v[86:87], v[86:87], v[88:89] op_sel_hi:[1,0]
	v_pk_mul_f32 v[84:85], v[84:85], v[88:89] op_sel_hi:[1,0]
	v_pk_mul_f32 v[82:83], v[82:83], v[88:89] op_sel_hi:[1,0]
	v_pk_mul_f32 v[80:81], v[80:81], v[88:89] op_sel_hi:[1,0]
	v_pk_mul_f32 v[78:79], v[78:79], v[88:89] op_sel_hi:[1,0]
	v_pk_mul_f32 v[76:77], v[76:77], v[88:89] op_sel_hi:[1,0]
	v_pk_mul_f32 v[74:75], v[74:75], v[88:89] op_sel_hi:[1,0]
	v_pk_mul_f32 v[72:73], v[72:73], v[88:89] op_sel_hi:[1,0]
	s_cbranch_vccnz .LBB0_179
	v_mov_b64_e32 v[90:91], v[86:87]
	v_mov_b64_e32 v[98:99], v[82:83]
	v_mov_b64_e32 v[94:95], v[78:79]
	v_mov_b64_e32 v[102:103], v[74:75]
	s_and_b64 vcc, exec, s[10:11]
	v_mov_b32_e32 v106, v126
	v_mov_b64_e32 v[88:89], v[84:85]
	v_mov_b64_e32 v[96:97], v[80:81]
	v_mov_b64_e32 v[92:93], v[76:77]
	v_mov_b64_e32 v[100:101], v[72:73]
	s_cbranch_vccnz .LBB0_178
	v_cvt_f32_u32_e32 v101, v107
	s_andn2_b64 vcc, exec, s[74:75]
	v_mov_b32_e32 v106, v126
	v_mul_f32_e32 v92, v30, v101
	v_fract_f32_e32 v93, v92
	v_mul_f32_e32 v88, v28, v101
	v_mul_f32_e32 v89, v29, v101
	v_cos_f32_e32 v92, v93
	v_sin_f32_e32 v94, v93
	v_mul_f32_e32 v93, v31, v101
	v_fract_f32_e32 v90, v88
	v_fract_f32_e32 v91, v89
	v_fract_f32_e32 v95, v93
	v_cos_f32_e32 v88, v90
	v_sin_f32_e32 v90, v90
	v_cos_f32_e32 v89, v91
	v_cos_f32_e32 v93, v95
	v_sin_f32_e32 v95, v95
	v_sin_f32_e32 v91, v91
	v_pk_mul_f32 v[96:97], v[188:189], v[88:89] op_sel_hi:[0,1]
	v_pk_mul_f32 v[92:93], v[188:189], v[92:93] op_sel_hi:[0,1]
	v_pk_mul_f32 v[94:95], v[188:189], v[94:95] op_sel_hi:[0,1]
	v_pk_mul_f32 v[98:99], v[188:189], v[90:91] op_sel_hi:[0,1]
	v_pk_mul_f32 v[88:89], v[98:99], v[76:77]
	v_pk_mul_f32 v[90:91], v[94:95], v[78:79]
	v_pk_fma_f32 v[88:89], v[96:97], v[84:85], v[88:89] neg_lo:[0,0,1] neg_hi:[0,0,1]
	v_pk_fma_f32 v[90:91], v[92:93], v[86:87], v[90:91] neg_lo:[0,0,1] neg_hi:[0,0,1]
	v_pk_mul_f32 v[96:97], v[96:97], v[76:77]
	v_pk_mul_f32 v[92:93], v[92:93], v[78:79]
	v_mul_f32_e32 v100, v54, v101
	v_pk_fma_f32 v[94:95], v[94:95], v[86:87], v[92:93]
	v_pk_fma_f32 v[92:93], v[98:99], v[84:85], v[96:97]
	v_mul_f32_e32 v96, v52, v101
	v_fract_f32_e32 v97, v96
	v_cos_f32_e32 v96, v97
	v_sin_f32_e32 v98, v97
	v_mul_f32_e32 v97, v53, v101
	v_mul_f32_e32 v101, v55, v101
	v_fract_f32_e32 v99, v97
	v_fract_f32_e32 v102, v100
	v_fract_f32_e32 v103, v101
	v_cos_f32_e32 v97, v99
	v_cos_f32_e32 v100, v102
	v_sin_f32_e32 v102, v102
	v_cos_f32_e32 v101, v103
	v_sin_f32_e32 v103, v103
	v_sin_f32_e32 v99, v99
	v_pk_mul_f32 v[108:109], v[188:189], v[96:97] op_sel_hi:[0,1]
	v_pk_mul_f32 v[100:101], v[188:189], v[100:101] op_sel_hi:[0,1]
	v_pk_mul_f32 v[102:103], v[188:189], v[102:103] op_sel_hi:[0,1]
	v_pk_mul_f32 v[110:111], v[188:189], v[98:99] op_sel_hi:[0,1]
	v_pk_mul_f32 v[96:97], v[110:111], v[72:73]
	v_pk_mul_f32 v[98:99], v[102:103], v[74:75]
	v_pk_fma_f32 v[96:97], v[108:109], v[80:81], v[96:97] neg_lo:[0,0,1] neg_hi:[0,0,1]
	v_pk_fma_f32 v[98:99], v[100:101], v[82:83], v[98:99] neg_lo:[0,0,1] neg_hi:[0,0,1]
	v_pk_mul_f32 v[108:109], v[108:109], v[72:73]
	v_pk_mul_f32 v[100:101], v[100:101], v[74:75]
	s_nop 0
	v_pk_fma_f32 v[102:103], v[102:103], v[82:83], v[100:101]
	v_pk_fma_f32 v[100:101], v[110:111], v[80:81], v[108:109]
	s_cbranch_vccnz .LBB0_178
	v_pk_mul_f32 v[108:109], v[90:91], v[90:91]
	v_pk_mul_f32 v[110:111], v[88:89], v[88:89]
	v_mul_f32_e32 v106, v92, v92
	v_pk_mov_b32 v[112:113], v[110:111], v[108:109] op_sel:[1,0]
	v_mov_b32_e32 v111, v109
	v_pk_add_f32 v[108:109], v[112:113], v[110:111]
	v_pk_mul_f32 v[110:111], v[98:99], v[98:99]
	v_pk_mul_f32 v[112:113], v[96:97], v[96:97]
	v_pk_add_f32 v[108:109], v[108:109], v[108:109] op_sel_hi:[0,1]
	v_pk_mov_b32 v[114:115], v[112:113], v[110:111] op_sel:[1,0]
	v_mov_b32_e32 v113, v111
	v_pk_add_f32 v[110:111], v[114:115], v[112:113]
	v_pk_fma_f32 v[112:113], v[92:93], v[92:93], v[106:107] op_sel_hi:[1,1,0]
	v_mul_f32_e32 v106, v94, v94
	v_pk_add_f32 v[110:111], v[110:111], v[110:111] op_sel_hi:[0,1]
	v_pk_fma_f32 v[114:115], v[94:95], v[94:95], v[106:107] op_sel_hi:[1,1,0]
	v_mul_f32_e32 v112, v100, v100
	v_mul_f32_e32 v114, v101, v101
	v_mul_f32_e32 v108, v102, v102
	v_mul_f32_e32 v110, v103, v103
	v_pk_add_f32 v[112:113], v[112:113], v[114:115]
	v_pk_add_f32 v[108:109], v[108:109], v[110:111]
	s_nop 0
	v_pk_add_f32 v[108:109], v[112:113], v[108:109]
	s_nop 0
	v_add_f32_e32 v106, v108, v109
	v_and_b32_e32 v109, 64, v207
	v_xor_b32_e32 v108, 16, v207
	v_add_u32_e32 v109, 64, v109
	v_cmp_lt_i32_e32 vcc, v108, v109
	s_nop 1
	v_cndmask_b32_e32 v108, v207, v108, vcc
	v_lshlrev_b32_e32 v108, 2, v108
	ds_bpermute_b32 v108, v108, v106
	s_waitcnt lgkmcnt(0)
	v_add_f32_e32 v106, v106, v108
	v_xor_b32_e32 v108, 32, v207
	v_cmp_lt_i32_e32 vcc, v108, v109
	s_nop 1
	v_cndmask_b32_e32 v108, v207, v108, vcc
	v_lshlrev_b32_e32 v108, 2, v108
	ds_bpermute_b32 v108, v108, v106
	s_waitcnt lgkmcnt(0)
	v_add_f32_e32 v106, v106, v108
	v_max_f32_e32 v108, v126, v126
	v_max_f32_e32 v106, v108, v106

;     __device__ __forceinline__ void operator()(const f32x4 (&acc)[2][2][4][2], const Unit& u, int wr, int wc, int fr, int fq, PG8_LAS unsigned char* lds) const {
;     ...
;                 const int row = u.pm * BM + ai * HALF + wr * 64 + m * 16 + fr; const int t = row & tmask;
;                 const float rs = __builtin_amdgcn_rsqf((float)rss[row] * (2.3283064365386963e-10f / 1024.0f) + 1e-6f);
;                 f32x4 v[2][2];
; #pragma unroll
;                 for (int bj = 0; bj < 2; ++bj)
; #pragma unroll
;                     for (int n = 0; n < 2; ++n) v[bj][n] = acc[ai][bj][m][n] * rs;
;                 if (type <= 1) {
;                     float ss = 0.f;
; #pragma unroll
;                     for (int bj = 0; bj < 2; ++bj)
; #pragma unroll
;                         for (int n = 0; n < 2; ++n) { const f32x4 x = v[bj][n]; ss += (x[0] * x[0] + x[1] * x[1]) + (x[2] * x[2] + x[3] * x[3]); }
;                     ss += __shfl_xor(ss, 16); ss += __shfl_xor(ss, 32);
;                     float rn = __builtin_amdgcn_rsqf(ss * (1.0f / 64.0f) + 1e-6f); if (type == 0) rn *= QSCALE;
; #pragma unroll
;                     for (int bj = 0; bj < 2; ++bj) { const float pf = (float)(bj == 0 ? (t >> 6) : (t & 63)); f32x4 c, s;
; #pragma unroll
;                         for (int e = 0; e < 4; ++e) { const float a = __builtin_amdgcn_fractf(pf * f4[0][e]); c[e] = __builtin_amdgcn_cosf(a); s[e] = __builtin_amdgcn_sinf(a); }
;                         const f32x4 x1 = v[bj][0] * g[bj][0] * rn, x2 = v[bj][1] * g[bj][1] * rn;
;                         v[bj][0] = x1 * c - x2 * s; v[bj][1] = x1 * s + x2 * c; }
;                 } else if (type >= 3) {
;                     const float sc = type == 3 ? QSCALE : 1.0f; const float tf = (float)t;
; #pragma unroll
;                     for (int n = 0; n < 2; ++n) { f32x4 c, s;
; #pragma unroll
;                         for (int e = 0; e < 4; ++e) { const float a = __builtin_amdgcn_fractf(tf * f4[n][e]); c[e] = __builtin_amdgcn_cosf(a) * sc; s[e] = __builtin_amdgcn_sinf(a) * sc; }
;                         const f32x4 x1 = v[0][n], x2 = v[1][n];
;                         v[0][n] = x1 * c - x2 * s; v[1][n] = x1 * s + x2 * c; }
;                     if (type == 4) { float ks = 0.f;
; #pragma unroll
;                         for (int bj = 0; bj < 2; ++bj)
; #pragma unroll
.LBB0_181:
	v_lshl_add_u64 v[72:73], s[76:77], 0, v[104:105]
	v_lshlrev_b64 v[72:73], 7, v[72:73]
	v_lshl_add_u64 v[76:77], v[176:177], 0, v[72:73]
	v_cvt_pk_bf16_f32 v72, v88, v89
	v_cvt_pk_bf16_f32 v73, v90, v91
	v_cvt_pk_bf16_f32 v74, v96, v97
	v_cvt_pk_bf16_f32 v75, v98, v99
	v_add_u32_e32 v88, 0x90, v190
	v_permlane16_swap_b32_e32 v72, v74
	v_permlane16_swap_b32_e32 v73, v75
	global_store_dwordx4 v[76:77], v[72:75], off
	v_ashrrev_i32_e32 v89, 31, v88
	s_and_b64 vcc, exec, s[12:13]
	v_cvt_pk_bf16_f32 v72, v92, v93
	v_cvt_pk_bf16_f32 v73, v94, v95
	v_cvt_pk_bf16_f32 v74, v100, v101
	v_cvt_pk_bf16_f32 v75, v102, v103
	v_and_b32_e32 v91, s63, v88
	v_permlane16_swap_b32_e32 v72, v74
	v_permlane16_swap_b32_e32 v73, v75
	global_store_dwordx4 v[76:77], v[72:75], off offset:64
	s_mov_b64 s[78:79], -1
	s_nop 0
	s_waitcnt vmcnt(10)
	v_mov_b64_e32 v[72:73], v[232:233]
	v_ffbh_u32_e32 v74, v73
	v_min_u32_e32 v74, 32, v74
	v_lshlrev_b64 v[72:73], v74, v[72:73]
	v_min_u32_e32 v72, 1, v72
	v_or_b32_e32 v72, v73, v72
	v_cvt_f32_u32_e32 v72, v72
	v_sub_u32_e32 v73, 32, v74
	v_ldexp_f32 v72, v72, v73
	v_fmamk_f32 v72, v72, 0x2a800000, v204
	v_rsq_f32_e32 v72, v72
	s_nop 0
	v_pk_mul_f32 v[70:71], v[70:71], v[72:73] op_sel_hi:[1,0]
	v_pk_mul_f32 v[68:69], v[68:69], v[72:73] op_sel_hi:[1,0]
	v_pk_mul_f32 v[66:67], v[66:67], v[72:73] op_sel_hi:[1,0]
	v_pk_mul_f32 v[64:65], v[64:65], v[72:73] op_sel_hi:[1,0]
	v_pk_mul_f32 v[62:63], v[62:63], v[72:73] op_sel_hi:[1,0]
	v_pk_mul_f32 v[60:61], v[60:61], v[72:73] op_sel_hi:[1,0]
	v_pk_mul_f32 v[58:59], v[58:59], v[72:73] op_sel_hi:[1,0]
	v_pk_mul_f32 v[56:57], v[56:57], v[72:73] op_sel_hi:[1,0]
	s_cbranch_vccnz .LBB0_186
	v_mov_b64_e32 v[74:75], v[70:71]
	v_mov_b64_e32 v[82:83], v[66:67]
	v_mov_b64_e32 v[78:79], v[62:63]
	v_mov_b64_e32 v[86:87], v[58:59]
	s_and_b64 vcc, exec, s[10:11]
	v_mov_b32_e32 v90, v106
	v_mov_b64_e32 v[72:73], v[68:69]
	v_mov_b64_e32 v[80:81], v[64:65]
	v_mov_b64_e32 v[76:77], v[60:61]
	v_mov_b64_e32 v[84:85], v[56:57]
	s_cbranch_vccnz .LBB0_185
	v_cvt_f32_u32_e32 v85, v91
	s_andn2_b64 vcc, exec, s[74:75]
	v_mov_b32_e32 v90, v106
	v_mul_f32_e32 v76, v30, v85
	v_fract_f32_e32 v77, v76
	v_mul_f32_e32 v72, v28, v85
	v_mul_f32_e32 v73, v29, v85
	v_cos_f32_e32 v76, v77
	v_sin_f32_e32 v78, v77
	v_mul_f32_e32 v77, v31, v85
	v_fract_f32_e32 v74, v72
	v_fract_f32_e32 v75, v73
	v_fract_f32_e32 v79, v77
	v_cos_f32_e32 v72, v74
	v_sin_f32_e32 v74, v74
	v_cos_f32_e32 v73, v75
	v_cos_f32_e32 v77, v79
	v_sin_f32_e32 v79, v79
	v_sin_f32_e32 v75, v75
	v_pk_mul_f32 v[80:81], v[188:189], v[72:73] op_sel_hi:[0,1]
	v_pk_mul_f32 v[76:77], v[188:189], v[76:77] op_sel_hi:[0,1]
	v_pk_mul_f32 v[78:79], v[188:189], v[78:79] op_sel_hi:[0,1]
	v_pk_mul_f32 v[82:83], v[188:189], v[74:75] op_sel_hi:[0,1]
	v_pk_mul_f32 v[72:73], v[82:83], v[60:61]
	v_pk_mul_f32 v[74:75], v[78:79], v[62:63]
	v_pk_fma_f32 v[72:73], v[80:81], v[68:69], v[72:73] neg_lo:[0,0,1] neg_hi:[0,0,1]
	v_pk_fma_f32 v[74:75], v[76:77], v[70:71], v[74:75] neg_lo:[0,0,1] neg_hi:[0,0,1]
	v_pk_mul_f32 v[80:81], v[80:81], v[60:61]
	v_pk_mul_f32 v[76:77], v[76:77], v[62:63]
	v_mul_f32_e32 v84, v54, v85
	v_pk_fma_f32 v[78:79], v[78:79], v[70:71], v[76:77]
	v_pk_fma_f32 v[76:77], v[82:83], v[68:69], v[80:81]
	v_mul_f32_e32 v80, v52, v85
	v_fract_f32_e32 v81, v80
	v_cos_f32_e32 v80, v81
	v_sin_f32_e32 v82, v81
	v_mul_f32_e32 v81, v53, v85
	v_mul_f32_e32 v85, v55, v85
	v_fract_f32_e32 v83, v81
	v_fract_f32_e32 v86, v84
	v_fract_f32_e32 v87, v85
	v_cos_f32_e32 v81, v83
	v_cos_f32_e32 v84, v86
	v_sin_f32_e32 v86, v86
	v_cos_f32_e32 v85, v87
	v_sin_f32_e32 v87, v87
	v_sin_f32_e32 v83, v83
	v_pk_mul_f32 v[92:93], v[188:189], v[80:81] op_sel_hi:[0,1]
	v_pk_mul_f32 v[84:85], v[188:189], v[84:85] op_sel_hi:[0,1]
	v_pk_mul_f32 v[86:87], v[188:189], v[86:87] op_sel_hi:[0,1]
	v_pk_mul_f32 v[94:95], v[188:189], v[82:83] op_sel_hi:[0,1]
	v_pk_mul_f32 v[80:81], v[94:95], v[56:57]
	v_pk_mul_f32 v[82:83], v[86:87], v[58:59]
	v_pk_fma_f32 v[80:81], v[92:93], v[64:65], v[80:81] neg_lo:[0,0,1] neg_hi:[0,0,1]
	v_pk_fma_f32 v[82:83], v[84:85], v[66:67], v[82:83] neg_lo:[0,0,1] neg_hi:[0,0,1]
	v_pk_mul_f32 v[92:93], v[92:93], v[56:57]
	v_pk_mul_f32 v[84:85], v[84:85], v[58:59]
	s_nop 0
	v_pk_fma_f32 v[86:87], v[86:87], v[66:67], v[84:85]
	v_pk_fma_f32 v[84:85], v[94:95], v[64:65], v[92:93]
	s_cbranch_vccnz .LBB0_185
	v_pk_mul_f32 v[92:93], v[74:75], v[74:75]
	v_pk_mul_f32 v[94:95], v[72:73], v[72:73]
	v_mul_f32_e32 v90, v76, v76
	v_pk_mov_b32 v[96:97], v[94:95], v[92:93] op_sel:[1,0]
	v_mov_b32_e32 v95, v93
	v_pk_add_f32 v[92:93], v[96:97], v[94:95]
	v_pk_mul_f32 v[94:95], v[82:83], v[82:83]
	v_pk_mul_f32 v[96:97], v[80:81], v[80:81]
	v_pk_add_f32 v[92:93], v[92:93], v[92:93] op_sel_hi:[0,1]
	v_pk_mov_b32 v[98:99], v[96:97], v[94:95] op_sel:[1,0]
	v_mov_b32_e32 v97, v95
	v_pk_add_f32 v[94:95], v[98:99], v[96:97]
	v_pk_fma_f32 v[96:97], v[76:77], v[76:77], v[90:91] op_sel_hi:[1,1,0]
	v_mul_f32_e32 v90, v78, v78
	v_pk_add_f32 v[94:95], v[94:95], v[94:95] op_sel_hi:[0,1]
	v_pk_fma_f32 v[98:99], v[78:79], v[78:79], v[90:91] op_sel_hi:[1,1,0]
	v_mul_f32_e32 v96, v84, v84
	v_mul_f32_e32 v98, v85, v85
	v_mul_f32_e32 v92, v86, v86
	v_mul_f32_e32 v94, v87, v87
	v_pk_add_f32 v[96:97], v[96:97], v[98:99]
	v_pk_add_f32 v[92:93], v[92:93], v[94:95]
	s_nop 0
	v_pk_add_f32 v[92:93], v[96:97], v[92:93]
	s_nop 0
	v_add_f32_e32 v90, v92, v93
	v_and_b32_e32 v93, 64, v207
	v_xor_b32_e32 v92, 16, v207
	v_add_u32_e32 v93, 64, v93
	v_cmp_lt_i32_e32 vcc, v92, v93
	s_nop 1
	v_cndmask_b32_e32 v92, v207, v92, vcc
	v_lshlrev_b32_e32 v92, 2, v92
	ds_bpermute_b32 v92, v92, v90
	s_waitcnt lgkmcnt(0)
	v_add_f32_e32 v90, v90, v92
	v_xor_b32_e32 v92, 32, v207
	v_cmp_lt_i32_e32 vcc, v92, v93
	s_nop 1
	v_cndmask_b32_e32 v92, v207, v92, vcc
	v_lshlrev_b32_e32 v92, 2, v92
	ds_bpermute_b32 v92, v92, v90
	s_waitcnt lgkmcnt(0)
	v_add_f32_e32 v90, v90, v92
	v_max_f32_e32 v92, v106, v106
	v_max_f32_e32 v90, v92, v90

;     __device__ __forceinline__ void operator()(const f32x4 (&acc)[2][2][4][2], const Unit& u, int wr, int wc, int fr, int fq, PG8_LAS unsigned char* lds) const {
;     ...
;                 const int row = u.pm * BM + ai * HALF + wr * 64 + m * 16 + fr; const int t = row & tmask;
;                 const float rs = __builtin_amdgcn_rsqf((float)rss[row] * (2.3283064365386963e-10f / 1024.0f) + 1e-6f);
;                 f32x4 v[2][2];
; #pragma unroll
;                 for (int bj = 0; bj < 2; ++bj)
; #pragma unroll
;                     for (int n = 0; n < 2; ++n) v[bj][n] = acc[ai][bj][m][n] * rs;
;                 if (type <= 1) {
;                     float ss = 0.f;
; #pragma unroll
;                     for (int bj = 0; bj < 2; ++bj)
; #pragma unroll
;                         for (int n = 0; n < 2; ++n) { const f32x4 x = v[bj][n]; ss += (x[0] * x[0] + x[1] * x[1]) + (x[2] * x[2] + x[3] * x[3]); }
;                     ss += __shfl_xor(ss, 16); ss += __shfl_xor(ss, 32);
;                     float rn = __builtin_amdgcn_rsqf(ss * (1.0f / 64.0f) + 1e-6f); if (type == 0) rn *= QSCALE;
; #pragma unroll
;                     for (int bj = 0; bj < 2; ++bj) { const float pf = (float)(bj == 0 ? (t >> 6) : (t & 63)); f32x4 c, s;
; #pragma unroll
;                         for (int e = 0; e < 4; ++e) { const float a = __builtin_amdgcn_fractf(pf * f4[0][e]); c[e] = __builtin_amdgcn_cosf(a); s[e] = __builtin_amdgcn_sinf(a); }
;                         const f32x4 x1 = v[bj][0] * g[bj][0] * rn, x2 = v[bj][1] * g[bj][1] * rn;
;                         v[bj][0] = x1 * c - x2 * s; v[bj][1] = x1 * s + x2 * c; }
;                 } else if (type >= 3) {
;                     const float sc = type == 3 ? QSCALE : 1.0f; const float tf = (float)t;
; #pragma unroll
;                     for (int n = 0; n < 2; ++n) { f32x4 c, s;
; #pragma unroll
;                         for (int e = 0; e < 4; ++e) { const float a = __builtin_amdgcn_fractf(tf * f4[n][e]); c[e] = __builtin_amdgcn_cosf(a) * sc; s[e] = __builtin_amdgcn_sinf(a) * sc; }
;                         const f32x4 x1 = v[0][n], x2 = v[1][n];
;                         v[0][n] = x1 * c - x2 * s; v[1][n] = x1 * s + x2 * c; }
;                     if (type == 4) { float ks = 0.f;
; #pragma unroll
;                         for (int bj = 0; bj < 2; ++bj)
; #pragma unroll
.LBB0_188:
	v_lshl_add_u64 v[56:57], s[76:77], 0, v[88:89]
	v_lshlrev_b64 v[56:57], 7, v[56:57]
	v_lshl_add_u64 v[60:61], v[176:177], 0, v[56:57]
	v_cvt_pk_bf16_f32 v56, v72, v73
	v_cvt_pk_bf16_f32 v57, v74, v75
	v_cvt_pk_bf16_f32 v58, v80, v81
	v_cvt_pk_bf16_f32 v59, v82, v83
	v_add_u32_e32 v72, 0xa0, v190
	v_permlane16_swap_b32_e32 v56, v58
	v_permlane16_swap_b32_e32 v57, v59
	global_store_dwordx4 v[60:61], v[56:59], off
	v_ashrrev_i32_e32 v73, 31, v72
	s_and_b64 vcc, exec, s[12:13]
	v_cvt_pk_bf16_f32 v56, v76, v77
	v_cvt_pk_bf16_f32 v57, v78, v79
	v_cvt_pk_bf16_f32 v58, v84, v85
	v_cvt_pk_bf16_f32 v59, v86, v87
	v_and_b32_e32 v75, s63, v72
	v_permlane16_swap_b32_e32 v56, v58
	v_permlane16_swap_b32_e32 v57, v59
	global_store_dwordx4 v[60:61], v[56:59], off offset:64
	s_mov_b64 s[78:79], -1
	s_nop 0
	s_waitcnt vmcnt(12)
	v_mov_b64_e32 v[56:57], v[234:235]
	v_ffbh_u32_e32 v58, v57
	v_min_u32_e32 v58, 32, v58
	v_lshlrev_b64 v[56:57], v58, v[56:57]
	v_min_u32_e32 v56, 1, v56
	v_or_b32_e32 v56, v57, v56
	v_cvt_f32_u32_e32 v56, v56
	v_sub_u32_e32 v57, 32, v58
	v_ldexp_f32 v56, v56, v57
	v_fmamk_f32 v56, v56, 0x2a800000, v204
	v_rsq_f32_e32 v56, v56
	s_nop 0
	v_pk_mul_f32 v[34:35], v[34:35], v[56:57] op_sel_hi:[1,0]
	v_pk_mul_f32 v[32:33], v[32:33], v[56:57] op_sel_hi:[1,0]
	v_pk_mul_f32 v[26:27], v[26:27], v[56:57] op_sel_hi:[1,0]
	v_pk_mul_f32 v[24:25], v[24:25], v[56:57] op_sel_hi:[1,0]
	v_pk_mul_f32 v[22:23], v[22:23], v[56:57] op_sel_hi:[1,0]
	v_pk_mul_f32 v[20:21], v[20:21], v[56:57] op_sel_hi:[1,0]
	v_pk_mul_f32 v[18:19], v[18:19], v[56:57] op_sel_hi:[1,0]
	v_pk_mul_f32 v[16:17], v[16:17], v[56:57] op_sel_hi:[1,0]
	s_cbranch_vccnz .LBB0_193
	v_mov_b64_e32 v[58:59], v[34:35]
	v_mov_b64_e32 v[66:67], v[26:27]
	v_mov_b64_e32 v[62:63], v[22:23]
	v_mov_b64_e32 v[70:71], v[18:19]
	s_and_b64 vcc, exec, s[10:11]
	v_mov_b32_e32 v74, v90
	v_mov_b64_e32 v[56:57], v[32:33]
	v_mov_b64_e32 v[64:65], v[24:25]
	v_mov_b64_e32 v[60:61], v[20:21]
	v_mov_b64_e32 v[68:69], v[16:17]
	s_cbranch_vccnz .LBB0_192
	v_cvt_f32_u32_e32 v69, v75
	s_andn2_b64 vcc, exec, s[74:75]
	v_mov_b32_e32 v74, v90
	v_mul_f32_e32 v60, v30, v69
	v_fract_f32_e32 v61, v60
	v_mul_f32_e32 v56, v28, v69
	v_mul_f32_e32 v57, v29, v69
	v_cos_f32_e32 v60, v61
	v_sin_f32_e32 v62, v61
	v_mul_f32_e32 v61, v31, v69
	v_fract_f32_e32 v58, v56
	v_fract_f32_e32 v59, v57
	v_fract_f32_e32 v63, v61
	v_cos_f32_e32 v56, v58
	v_sin_f32_e32 v58, v58
	v_cos_f32_e32 v57, v59
	v_cos_f32_e32 v61, v63
	v_sin_f32_e32 v63, v63
	v_sin_f32_e32 v59, v59
	v_pk_mul_f32 v[64:65], v[188:189], v[56:57] op_sel_hi:[0,1]
	v_pk_mul_f32 v[60:61], v[188:189], v[60:61] op_sel_hi:[0,1]
	v_pk_mul_f32 v[62:63], v[188:189], v[62:63] op_sel_hi:[0,1]
	v_pk_mul_f32 v[66:67], v[188:189], v[58:59] op_sel_hi:[0,1]
	v_pk_mul_f32 v[56:57], v[66:67], v[20:21]
	v_pk_mul_f32 v[58:59], v[62:63], v[22:23]
	v_pk_fma_f32 v[56:57], v[64:65], v[32:33], v[56:57] neg_lo:[0,0,1] neg_hi:[0,0,1]
	v_pk_fma_f32 v[58:59], v[60:61], v[34:35], v[58:59] neg_lo:[0,0,1] neg_hi:[0,0,1]
	v_pk_mul_f32 v[64:65], v[64:65], v[20:21]
	v_pk_mul_f32 v[60:61], v[60:61], v[22:23]
	v_mul_f32_e32 v68, v54, v69
	v_pk_fma_f32 v[62:63], v[62:63], v[34:35], v[60:61]
	v_pk_fma_f32 v[60:61], v[66:67], v[32:33], v[64:65]
	v_mul_f32_e32 v64, v52, v69
	v_fract_f32_e32 v65, v64
	v_cos_f32_e32 v64, v65
	v_sin_f32_e32 v66, v65
	v_mul_f32_e32 v65, v53, v69
	v_mul_f32_e32 v69, v55, v69
	v_fract_f32_e32 v67, v65
	v_fract_f32_e32 v70, v68
	v_fract_f32_e32 v71, v69
	v_cos_f32_e32 v65, v67
	v_cos_f32_e32 v68, v70
	v_sin_f32_e32 v70, v70
	v_cos_f32_e32 v69, v71
	v_sin_f32_e32 v71, v71
	v_sin_f32_e32 v67, v67
	v_pk_mul_f32 v[76:77], v[188:189], v[64:65] op_sel_hi:[0,1]
	v_pk_mul_f32 v[68:69], v[188:189], v[68:69] op_sel_hi:[0,1]
	v_pk_mul_f32 v[70:71], v[188:189], v[70:71] op_sel_hi:[0,1]
	v_pk_mul_f32 v[78:79], v[188:189], v[66:67] op_sel_hi:[0,1]
	v_pk_mul_f32 v[64:65], v[78:79], v[16:17]
	v_pk_mul_f32 v[66:67], v[70:71], v[18:19]
	v_pk_fma_f32 v[64:65], v[76:77], v[24:25], v[64:65] neg_lo:[0,0,1] neg_hi:[0,0,1]
	v_pk_fma_f32 v[66:67], v[68:69], v[26:27], v[66:67] neg_lo:[0,0,1] neg_hi:[0,0,1]
	v_pk_mul_f32 v[76:77], v[76:77], v[16:17]
	v_pk_mul_f32 v[68:69], v[68:69], v[18:19]
	s_nop 0
	v_pk_fma_f32 v[70:71], v[70:71], v[26:27], v[68:69]
	v_pk_fma_f32 v[68:69], v[78:79], v[24:25], v[76:77]
	s_cbranch_vccnz .LBB0_192
	v_pk_mul_f32 v[76:77], v[58:59], v[58:59]
	v_pk_mul_f32 v[78:79], v[56:57], v[56:57]
	v_mul_f32_e32 v74, v60, v60
	v_pk_mov_b32 v[80:81], v[78:79], v[76:77] op_sel:[1,0]
	v_mov_b32_e32 v79, v77
	v_pk_add_f32 v[76:77], v[80:81], v[78:79]
	v_pk_mul_f32 v[78:79], v[66:67], v[66:67]
	v_pk_mul_f32 v[80:81], v[64:65], v[64:65]
	v_pk_add_f32 v[76:77], v[76:77], v[76:77] op_sel_hi:[0,1]
	v_pk_mov_b32 v[82:83], v[80:81], v[78:79] op_sel:[1,0]
	v_mov_b32_e32 v81, v79
	v_pk_add_f32 v[78:79], v[82:83], v[80:81]
	v_pk_fma_f32 v[80:81], v[60:61], v[60:61], v[74:75] op_sel_hi:[1,1,0]
	v_mul_f32_e32 v74, v62, v62
	v_pk_add_f32 v[78:79], v[78:79], v[78:79] op_sel_hi:[0,1]
	v_pk_fma_f32 v[82:83], v[62:63], v[62:63], v[74:75] op_sel_hi:[1,1,0]
	v_mul_f32_e32 v80, v68, v68
	v_mul_f32_e32 v82, v69, v69
	v_mul_f32_e32 v76, v70, v70
	v_mul_f32_e32 v78, v71, v71
	v_pk_add_f32 v[80:81], v[80:81], v[82:83]
	v_pk_add_f32 v[76:77], v[76:77], v[78:79]
	s_nop 0
	v_pk_add_f32 v[76:77], v[80:81], v[76:77]
	s_nop 0
	v_add_f32_e32 v74, v76, v77
	v_and_b32_e32 v77, 64, v207
	v_xor_b32_e32 v76, 16, v207
	v_add_u32_e32 v77, 64, v77
	v_cmp_lt_i32_e32 vcc, v76, v77
	s_nop 1
	v_cndmask_b32_e32 v76, v207, v76, vcc
	v_lshlrev_b32_e32 v76, 2, v76
	ds_bpermute_b32 v76, v76, v74
	s_waitcnt lgkmcnt(0)
	v_add_f32_e32 v74, v74, v76
	v_xor_b32_e32 v76, 32, v207
	v_cmp_lt_i32_e32 vcc, v76, v77
	s_nop 1
	v_cndmask_b32_e32 v76, v207, v76, vcc
	v_lshlrev_b32_e32 v76, 2, v76
	ds_bpermute_b32 v76, v76, v74
	s_waitcnt lgkmcnt(0)
	v_add_f32_e32 v74, v74, v76
	v_max_f32_e32 v76, v90, v90
	v_max_f32_e32 v74, v76, v74

;     __device__ __forceinline__ void operator()(const f32x4 (&acc)[2][2][4][2], const Unit& u, int wr, int wc, int fr, int fq, PG8_LAS unsigned char* lds) const {
;     ...
;                 const int row = u.pm * BM + ai * HALF + wr * 64 + m * 16 + fr; const int t = row & tmask;
;                 const float rs = __builtin_amdgcn_rsqf((float)rss[row] * (2.3283064365386963e-10f / 1024.0f) + 1e-6f);
;                 f32x4 v[2][2];
; #pragma unroll
;                 for (int bj = 0; bj < 2; ++bj)
; #pragma unroll
;                     for (int n = 0; n < 2; ++n) v[bj][n] = acc[ai][bj][m][n] * rs;
;                 if (type <= 1) {
;                     float ss = 0.f;
; #pragma unroll
;                     for (int bj = 0; bj < 2; ++bj)
; #pragma unroll
;                         for (int n = 0; n < 2; ++n) { const f32x4 x = v[bj][n]; ss += (x[0] * x[0] + x[1] * x[1]) + (x[2] * x[2] + x[3] * x[3]); }
;                     ss += __shfl_xor(ss, 16); ss += __shfl_xor(ss, 32);
;                     float rn = __builtin_amdgcn_rsqf(ss * (1.0f / 64.0f) + 1e-6f); if (type == 0) rn *= QSCALE;
; #pragma unroll
;                     for (int bj = 0; bj < 2; ++bj) { const float pf = (float)(bj == 0 ? (t >> 6) : (t & 63)); f32x4 c, s;
; #pragma unroll
;                         for (int e = 0; e < 4; ++e) { const float a = __builtin_amdgcn_fractf(pf * f4[0][e]); c[e] = __builtin_amdgcn_cosf(a); s[e] = __builtin_amdgcn_sinf(a); }
;                         const f32x4 x1 = v[bj][0] * g[bj][0] * rn, x2 = v[bj][1] * g[bj][1] * rn;
;                         v[bj][0] = x1 * c - x2 * s; v[bj][1] = x1 * s + x2 * c; }
;                 } else if (type >= 3) {
;                     const float sc = type == 3 ? QSCALE : 1.0f; const float tf = (float)t;
; #pragma unroll
;                     for (int n = 0; n < 2; ++n) { f32x4 c, s;
; #pragma unroll
;                         for (int e = 0; e < 4; ++e) { const float a = __builtin_amdgcn_fractf(tf * f4[n][e]); c[e] = __builtin_amdgcn_cosf(a) * sc; s[e] = __builtin_amdgcn_sinf(a) * sc; }
;                         const f32x4 x1 = v[0][n], x2 = v[1][n];
;                         v[0][n] = x1 * c - x2 * s; v[1][n] = x1 * s + x2 * c; }
;                     if (type == 4) { float ks = 0.f;
; #pragma unroll
;                         for (int bj = 0; bj < 2; ++bj)
; #pragma unroll
.LBB0_195:
	v_lshl_add_u64 v[16:17], s[76:77], 0, v[72:73]
	v_lshlrev_b64 v[16:17], 7, v[16:17]
	v_lshl_add_u64 v[20:21], v[176:177], 0, v[16:17]
	v_cvt_pk_bf16_f32 v16, v56, v57
	v_cvt_pk_bf16_f32 v17, v58, v59
	v_cvt_pk_bf16_f32 v18, v64, v65
	v_cvt_pk_bf16_f32 v19, v66, v67
	v_add_u32_e32 v56, 0xb0, v190
	v_permlane16_swap_b32_e32 v16, v18
	v_permlane16_swap_b32_e32 v17, v19
	global_store_dwordx4 v[20:21], v[16:19], off
	v_ashrrev_i32_e32 v57, 31, v56
	s_and_b64 vcc, exec, s[12:13]
	v_cvt_pk_bf16_f32 v16, v60, v61
	v_cvt_pk_bf16_f32 v17, v62, v63
	v_cvt_pk_bf16_f32 v18, v68, v69
	v_cvt_pk_bf16_f32 v19, v70, v71
	v_and_b32_e32 v58, s63, v56
	v_permlane16_swap_b32_e32 v16, v18
	v_permlane16_swap_b32_e32 v17, v19
	global_store_dwordx4 v[20:21], v[16:19], off offset:64
	s_mov_b64 s[12:13], -1
	s_nop 0
	s_waitcnt vmcnt(14)
	v_mov_b64_e32 v[16:17], v[236:237]
	v_ffbh_u32_e32 v18, v17
	v_min_u32_e32 v18, 32, v18
	v_lshlrev_b64 v[16:17], v18, v[16:17]
	v_min_u32_e32 v16, 1, v16
	v_or_b32_e32 v16, v17, v16
	v_cvt_f32_u32_e32 v16, v16
	v_sub_u32_e32 v17, 32, v18
	v_ldexp_f32 v16, v16, v17
	v_fmamk_f32 v16, v16, 0x2a800000, v204
	v_rsq_f32_e32 v16, v16
	s_nop 0
	v_pk_mul_f32 v[14:15], v[14:15], v[16:17] op_sel_hi:[1,0]
	v_pk_mul_f32 v[12:13], v[12:13], v[16:17] op_sel_hi:[1,0]
	v_pk_mul_f32 v[10:11], v[10:11], v[16:17] op_sel_hi:[1,0]
	v_pk_mul_f32 v[8:9], v[8:9], v[16:17] op_sel_hi:[1,0]
	v_pk_mul_f32 v[6:7], v[6:7], v[16:17] op_sel_hi:[1,0]
	v_pk_mul_f32 v[4:5], v[4:5], v[16:17] op_sel_hi:[1,0]
	v_pk_mul_f32 v[2:3], v[2:3], v[16:17] op_sel_hi:[1,0]
	v_pk_mul_f32 v[0:1], v[0:1], v[16:17] op_sel_hi:[1,0]
	s_cbranch_vccnz .LBB0_200
	v_mov_b64_e32 v[18:19], v[14:15]
	v_mov_b64_e32 v[26:27], v[10:11]
	v_mov_b64_e32 v[22:23], v[6:7]
	v_mov_b64_e32 v[34:35], v[2:3]
	s_and_b64 vcc, exec, s[10:11]
	v_mov_b32_e32 v59, v74
	v_mov_b64_e32 v[16:17], v[12:13]
	v_mov_b64_e32 v[24:25], v[8:9]
	v_mov_b64_e32 v[20:21], v[4:5]
	v_mov_b64_e32 v[32:33], v[0:1]
	s_cbranch_vccnz .LBB0_199
	v_cvt_f32_u32_e32 v33, v58
	s_andn2_b64 vcc, exec, s[74:75]
	v_mov_b32_e32 v59, v74
	v_mul_f32_e32 v20, v30, v33
	v_fract_f32_e32 v21, v20
	v_mul_f32_e32 v16, v28, v33
	v_mul_f32_e32 v17, v29, v33
	v_cos_f32_e32 v20, v21
	v_sin_f32_e32 v22, v21
	v_mul_f32_e32 v21, v31, v33
	v_fract_f32_e32 v18, v16
	v_fract_f32_e32 v19, v17
	v_fract_f32_e32 v23, v21
	v_cos_f32_e32 v16, v18
	v_sin_f32_e32 v18, v18
	v_cos_f32_e32 v17, v19
	v_cos_f32_e32 v21, v23
	v_sin_f32_e32 v23, v23
	v_sin_f32_e32 v19, v19
	v_pk_mul_f32 v[24:25], v[188:189], v[16:17] op_sel_hi:[0,1]
	v_pk_mul_f32 v[20:21], v[188:189], v[20:21] op_sel_hi:[0,1]
	v_pk_mul_f32 v[22:23], v[188:189], v[22:23] op_sel_hi:[0,1]
	v_pk_mul_f32 v[26:27], v[188:189], v[18:19] op_sel_hi:[0,1]
	v_pk_mul_f32 v[16:17], v[26:27], v[4:5]
	v_pk_mul_f32 v[18:19], v[22:23], v[6:7]
	v_pk_fma_f32 v[16:17], v[24:25], v[12:13], v[16:17] neg_lo:[0,0,1] neg_hi:[0,0,1]
	v_pk_fma_f32 v[18:19], v[20:21], v[14:15], v[18:19] neg_lo:[0,0,1] neg_hi:[0,0,1]
	v_pk_mul_f32 v[24:25], v[24:25], v[4:5]
	v_pk_mul_f32 v[20:21], v[20:21], v[6:7]
	v_mul_f32_e32 v32, v54, v33
	v_pk_fma_f32 v[22:23], v[22:23], v[14:15], v[20:21]
	v_pk_fma_f32 v[20:21], v[26:27], v[12:13], v[24:25]
	v_mul_f32_e32 v24, v52, v33
	v_fract_f32_e32 v25, v24
	v_cos_f32_e32 v24, v25
	v_sin_f32_e32 v26, v25
	v_mul_f32_e32 v25, v53, v33
	v_mul_f32_e32 v33, v55, v33
	v_fract_f32_e32 v27, v25
	v_fract_f32_e32 v34, v32
	v_fract_f32_e32 v35, v33
	v_cos_f32_e32 v25, v27
	v_cos_f32_e32 v32, v34
	v_sin_f32_e32 v34, v34
	v_cos_f32_e32 v33, v35
	v_sin_f32_e32 v35, v35
	v_sin_f32_e32 v27, v27
	v_pk_mul_f32 v[52:53], v[188:189], v[24:25] op_sel_hi:[0,1]
	v_pk_mul_f32 v[32:33], v[188:189], v[32:33] op_sel_hi:[0,1]
	v_pk_mul_f32 v[34:35], v[188:189], v[34:35] op_sel_hi:[0,1]
	v_pk_mul_f32 v[54:55], v[188:189], v[26:27] op_sel_hi:[0,1]
	v_pk_mul_f32 v[24:25], v[54:55], v[0:1]
	v_pk_mul_f32 v[26:27], v[34:35], v[2:3]
	v_pk_fma_f32 v[24:25], v[52:53], v[8:9], v[24:25] neg_lo:[0,0,1] neg_hi:[0,0,1]
	v_pk_fma_f32 v[26:27], v[32:33], v[10:11], v[26:27] neg_lo:[0,0,1] neg_hi:[0,0,1]
	v_pk_mul_f32 v[52:53], v[52:53], v[0:1]
	v_pk_mul_f32 v[32:33], v[32:33], v[2:3]
	s_nop 0
	v_pk_fma_f32 v[34:35], v[34:35], v[10:11], v[32:33]
	v_pk_fma_f32 v[32:33], v[54:55], v[8:9], v[52:53]
	s_cbranch_vccnz .LBB0_199
	v_pk_mul_f32 v[52:53], v[18:19], v[18:19]
	v_pk_mul_f32 v[54:55], v[16:17], v[16:17]
	s_nop 0
	v_pk_mov_b32 v[60:61], v[54:55], v[52:53] op_sel:[1,0]
	v_mov_b32_e32 v55, v53
	v_pk_add_f32 v[52:53], v[60:61], v[54:55]
	v_pk_mul_f32 v[54:55], v[26:27], v[26:27]
	v_pk_add_f32 v[52:53], v[52:53], v[52:53] op_sel_hi:[0,1]
	v_pk_mul_f32 v[60:61], v[24:25], v[24:25]
	v_mul_f32_e32 v52, v20, v20
	v_pk_mov_b32 v[62:63], v[60:61], v[54:55] op_sel:[1,0]
	v_mov_b32_e32 v61, v55
	v_pk_add_f32 v[54:55], v[62:63], v[60:61]
	v_pk_fma_f32 v[60:61], v[20:21], v[20:21], v[52:53] op_sel_hi:[1,1,0]
	v_mul_f32_e32 v52, v22, v22
	v_pk_add_f32 v[54:55], v[54:55], v[54:55] op_sel_hi:[0,1]
	v_pk_fma_f32 v[62:63], v[22:23], v[22:23], v[52:53] op_sel_hi:[1,1,0]
	v_mul_f32_e32 v60, v32, v32
	v_mul_f32_e32 v62, v33, v33
	v_mul_f32_e32 v52, v34, v34
	v_mul_f32_e32 v54, v35, v35
	v_pk_add_f32 v[60:61], v[60:61], v[62:63]
	v_pk_add_f32 v[52:53], v[52:53], v[54:55]
	v_and_b32_e32 v54, 64, v207
	v_pk_add_f32 v[52:53], v[60:61], v[52:53]
	v_add_u32_e32 v54, 64, v54
	v_add_f32_e32 v52, v52, v53
	v_xor_b32_e32 v53, 16, v207
	v_cmp_lt_i32_e32 vcc, v53, v54
	s_nop 1
	v_cndmask_b32_e32 v53, v207, v53, vcc
	v_lshlrev_b32_e32 v53, 2, v53
	ds_bpermute_b32 v53, v53, v52
	s_waitcnt lgkmcnt(0)
	v_add_f32_e32 v52, v52, v53
	v_xor_b32_e32 v53, 32, v207
	v_cmp_lt_i32_e32 vcc, v53, v54
	s_nop 1
	v_cndmask_b32_e32 v53, v207, v53, vcc
	v_lshlrev_b32_e32 v53, 2, v53
	ds_bpermute_b32 v53, v53, v52
	s_waitcnt lgkmcnt(0)
	v_add_f32_e32 v52, v52, v53
	v_max_f32_e32 v53, v74, v74
	v_max_f32_e32 v59, v53, v52

;     __device__ __forceinline__ void operator()(const f32x4 (&acc)[2][2][4][2], const Unit& u, int wr, int wc, int fr, int fq, PG8_LAS unsigned char* lds) const {
;         const int slot = u.pn * 4 + wc;
;         const int type = slot < 8 ? 0 : slot < 10 ? 1 : slot < 12 ? 2 : slot < 20 ? 3 : slot < 28 ? 4 : 2;
;         const int colbase = u.pn * 256 + wc * 64 + ((fq & 1) << 4) + ((fq >> 1) << 3);
;         f32x4 g[2][2], f4[2];
;         if (type <= 1) { const float* gp = type == 0 ? gq : gk;
; #pragma unroll
;             for (int bj = 0; bj < 2; ++bj)
; #pragma unroll
;                 for (int n = 0; n < 2; ++n) g[bj][n] = *(const f32x4*)(gp + 32 * bj + 16 * n + 4 * fq);
;             f4[0] = *(const f32x4*)(frq + 32 + 4 * fq); f4[1] = f4[0]; }
;         else if (type >= 3) { f4[0] = *(const f32x4*)(frq + 4 * fq); f4[1] = *(const f32x4*)(frq + 16 + 4 * fq); }
;         const int tmask = (u.pm * BM < TPROMPT) ? 2047 : 4095;
;         float kmx = 0.f;
; #pragma unroll
;         for (int ai = 0; ai < 2; ++ai)
; #pragma unroll
;             for (int m = 0; m < 4; ++m) {
;                 const int row = u.pm * BM + ai * HALF + wr * 64 + m * 16 + fr; const int t = row & tmask;
;                 const float rs = __builtin_amdgcn_rsqf((float)rss[row] * (2.3283064365386963e-10f / 1024.0f) + 1e-6f);
;                 f32x4 v[2][2];
; #pragma unroll
;                 for (int bj = 0; bj < 2; ++bj)
; #pragma unroll
;                     for (int n = 0; n < 2; ++n) v[bj][n] = acc[ai][bj][m][n] * rs;
;                 if (type <= 1) {
;                     float ss = 0.f;
; #pragma unroll
;                     for (int bj = 0; bj < 2; ++bj)
; #pragma unroll
;                         for (int n = 0; n < 2; ++n) { const f32x4 x = v[bj][n]; ss += (x[0] * x[0] + x[1] * x[1]) + (x[2] * x[2] + x[3] * x[3]); }
;                     ss += __shfl_xor(ss, 16); ss += __shfl_xor(ss, 32);
;                     float rn = __builtin_amdgcn_rsqf(ss * (1.0f / 64.0f) + 1e-6f); if (type == 0) rn *= QSCALE;
; #pragma unroll
;                     for (int bj = 0; bj < 2; ++bj) { const float pf = (float)(bj == 0 ? (t >> 6) : (t & 63)); f32x4 c, s;
; #pragma unroll
;                         for (int e = 0; e < 4; ++e) { const float a = __builtin_amdgcn_fractf(pf * f4[0][e]); c[e] = __builtin_amdgcn_cosf(a); s[e] = __builtin_amdgcn_sinf(a); }
.LBB0_699:
	s_cmpk_lt_i32 s38, 0x100
	s_cselect_b64 s[76:77], -1, 0
	s_and_b64 s[8:9], s[76:77], exec
	s_cselect_b32 s69, s63, 0xfff
	s_cmp_lg_u32 s10, 2
	s_cselect_b64 s[14:15], -1, 0
	s_cmp_eq_u32 s10, 3
	s_cselect_b64 vcc, -1, 0
	s_cmp_eq_u32 s10, 4
	s_cselect_b64 s[78:79], -1, 0
	s_cmp_eq_u32 s10, 0
	s_cselect_b64 s[8:9], -1, 0
	s_lshl_b32 s67, s38, 8
	v_add_u32_e32 v190, s67, v189
	v_ashrrev_i32_e32 v191, 31, v190
	v_lshl_add_u64 v[152:153], v[190:191], 3, s[42:43]
	global_load_dwordx2 v[210:211], v[152:153], off
	global_load_dwordx2 v[224:225], v[152:153], off offset:128
	global_load_dwordx2 v[226:227], v[152:153], off offset:256
	global_load_dwordx2 v[228:229], v[152:153], off offset:384
	global_load_dwordx2 v[230:231], v[152:153], off offset:1024
	global_load_dwordx2 v[232:233], v[152:153], off offset:1152
	global_load_dwordx2 v[234:235], v[152:153], off offset:1280
	global_load_dwordx2 v[236:237], v[152:153], off offset:1408
	s_mov_b64 s[12:13], -1
	v_and_b32_e32 v216, s69, v190
	s_waitcnt vmcnt(7)
	v_ffbh_u32_e32 v188, v211
	v_min_u32_e32 v209, 32, v188
	v_lshlrev_b64 v[210:211], v209, v[210:211]
	v_min_u32_e32 v188, 1, v210
	v_or_b32_e32 v188, v211, v188
	v_cvt_f32_u32_e32 v210, v188
	v_sub_u32_e32 v209, 32, v209
	v_cndmask_b32_e64 v211, 0, 1, s[14:15]
	v_cndmask_b32_e32 v188, 1.0, v206, vcc
	v_ldexp_f32 v209, v210, v209
	v_fmamk_f32 v209, v209, 0x2a800000, v204
	v_rsq_f32_e32 v210, v209
	v_cmp_ne_u32_e64 s[10:11], 1, v211
	s_and_b64 vcc, exec, s[80:81]
	v_pk_mul_f32 v[150:151], v[150:151], v[210:211] op_sel_hi:[1,0]
	v_pk_mul_f32 v[148:149], v[148:149], v[210:211] op_sel_hi:[1,0]
	v_pk_mul_f32 v[146:147], v[146:147], v[210:211] op_sel_hi:[1,0]
	v_pk_mul_f32 v[144:145], v[144:145], v[210:211] op_sel_hi:[1,0]
	v_pk_mul_f32 v[142:143], v[142:143], v[210:211] op_sel_hi:[1,0]
	v_pk_mul_f32 v[140:141], v[140:141], v[210:211] op_sel_hi:[1,0]
	v_pk_mul_f32 v[138:139], v[138:139], v[210:211] op_sel_hi:[1,0]
	v_pk_mul_f32 v[136:137], v[136:137], v[210:211] op_sel_hi:[1,0]
	s_cbranch_vccz .LBB0_704
	v_mov_b64_e32 v[154:155], v[150:151]
	v_mov_b64_e32 v[162:163], v[146:147]
	v_mov_b64_e32 v[158:159], v[142:143]
	v_mov_b64_e32 v[166:167], v[138:139]
	v_mov_b32_e32 v213, 0
	s_and_b64 vcc, exec, s[10:11]
	v_mov_b64_e32 v[152:153], v[148:149]
	v_mov_b64_e32 v[160:161], v[144:145]
	v_mov_b64_e32 v[156:157], v[140:141]
	v_mov_b64_e32 v[164:165], v[136:137]
	s_cbranch_vccnz .LBB0_703
	v_cvt_f32_u32_e32 v165, v216
	s_andn2_b64 vcc, exec, s[78:79]
	v_mul_f32_e32 v156, v30, v165
	v_fract_f32_e32 v157, v156
	v_mul_f32_e32 v152, v28, v165
	v_mul_f32_e32 v153, v29, v165
	v_cos_f32_e32 v156, v157
	v_sin_f32_e32 v158, v157
	v_mul_f32_e32 v157, v31, v165
	v_fract_f32_e32 v154, v152
	v_fract_f32_e32 v155, v153
	v_fract_f32_e32 v159, v157
	v_cos_f32_e32 v152, v154
	v_sin_f32_e32 v154, v154
	v_cos_f32_e32 v153, v155
	v_cos_f32_e32 v157, v159
	v_sin_f32_e32 v159, v159
	v_sin_f32_e32 v155, v155
	v_pk_mul_f32 v[160:161], v[188:189], v[152:153] op_sel_hi:[0,1]
	v_pk_mul_f32 v[156:157], v[188:189], v[156:157] op_sel_hi:[0,1]
	v_pk_mul_f32 v[158:159], v[188:189], v[158:159] op_sel_hi:[0,1]
	v_pk_mul_f32 v[162:163], v[188:189], v[154:155] op_sel_hi:[0,1]
	v_pk_mul_f32 v[152:153], v[162:163], v[140:141]
	v_pk_mul_f32 v[154:155], v[158:159], v[142:143]
	v_pk_fma_f32 v[152:153], v[160:161], v[148:149], v[152:153] neg_lo:[0,0,1] neg_hi:[0,0,1]
	v_pk_fma_f32 v[154:155], v[156:157], v[150:151], v[154:155] neg_lo:[0,0,1] neg_hi:[0,0,1]
	v_pk_mul_f32 v[160:161], v[160:161], v[140:141]
	v_pk_mul_f32 v[156:157], v[156:157], v[142:143]
	v_mul_f32_e32 v164, v54, v165
	v_pk_fma_f32 v[158:159], v[158:159], v[150:151], v[156:157]
	v_pk_fma_f32 v[156:157], v[162:163], v[148:149], v[160:161]
	v_mul_f32_e32 v160, v52, v165
	v_fract_f32_e32 v161, v160
	v_cos_f32_e32 v160, v161
	v_sin_f32_e32 v162, v161
	v_mul_f32_e32 v161, v53, v165
	v_mul_f32_e32 v165, v55, v165
	v_fract_f32_e32 v163, v161
	v_fract_f32_e32 v166, v164
	v_fract_f32_e32 v167, v165
	v_cos_f32_e32 v161, v163
	v_cos_f32_e32 v164, v166
	v_sin_f32_e32 v166, v166
	v_cos_f32_e32 v165, v167
	v_sin_f32_e32 v167, v167
	v_sin_f32_e32 v163, v163
	v_pk_mul_f32 v[210:211], v[188:189], v[160:161] op_sel_hi:[0,1]
	v_pk_mul_f32 v[164:165], v[188:189], v[164:165] op_sel_hi:[0,1]
	v_pk_mul_f32 v[166:167], v[188:189], v[166:167] op_sel_hi:[0,1]
	v_pk_mul_f32 v[212:213], v[188:189], v[162:163] op_sel_hi:[0,1]
	v_pk_mul_f32 v[160:161], v[212:213], v[136:137]
	v_pk_mul_f32 v[162:163], v[166:167], v[138:139]
	v_pk_fma_f32 v[160:161], v[210:211], v[144:145], v[160:161] neg_lo:[0,0,1] neg_hi:[0,0,1]
	v_pk_fma_f32 v[162:163], v[164:165], v[146:147], v[162:163] neg_lo:[0,0,1] neg_hi:[0,0,1]
	v_pk_mul_f32 v[210:211], v[210:211], v[136:137]
	v_pk_mul_f32 v[164:165], v[164:165], v[138:139]
	s_nop 0
	v_pk_fma_f32 v[166:167], v[166:167], v[146:147], v[164:165]
	v_pk_fma_f32 v[164:165], v[212:213], v[144:145], v[210:211]
	v_mov_b32_e32 v213, 0
	s_cbranch_vccnz .LBB0_703
	v_pk_mul_f32 v[210:211], v[154:155], v[154:155]
	v_pk_mul_f32 v[212:213], v[152:153], v[152:153]
	s_nop 0
	v_pk_mov_b32 v[218:219], v[212:213], v[210:211] op_sel:[1,0]
	v_mov_b32_e32 v213, v211
	v_pk_add_f32 v[210:211], v[218:219], v[212:213]
	v_pk_mul_f32 v[212:213], v[162:163], v[162:163]
	v_pk_add_f32 v[210:211], v[210:211], v[210:211] op_sel_hi:[0,1]
	v_pk_mul_f32 v[218:219], v[160:161], v[160:161]
	v_mul_f32_e32 v210, v156, v156
	v_pk_mov_b32 v[220:221], v[218:219], v[212:213] op_sel:[1,0]
	v_mov_b32_e32 v219, v213
	v_pk_add_f32 v[212:213], v[220:221], v[218:219]
	v_pk_fma_f32 v[218:219], v[156:157], v[156:157], v[210:211] op_sel_hi:[1,1,0]
	v_mul_f32_e32 v210, v158, v158
	v_pk_add_f32 v[212:213], v[212:213], v[212:213] op_sel_hi:[0,1]
	v_pk_fma_f32 v[220:221], v[158:159], v[158:159], v[210:211] op_sel_hi:[1,1,0]
	v_mul_f32_e32 v218, v164, v164
	v_mul_f32_e32 v220, v165, v165
	v_mul_f32_e32 v210, v166, v166
	v_mul_f32_e32 v212, v167, v167
	v_pk_add_f32 v[218:219], v[218:219], v[220:221]
	v_pk_add_f32 v[210:211], v[210:211], v[212:213]
	s_nop 0
	v_pk_add_f32 v[210:211], v[218:219], v[210:211]
	s_nop 0
	v_add_f32_e32 v209, v210, v211
	v_and_b32_e32 v211, 64, v207
	v_xor_b32_e32 v210, 16, v207
	v_add_u32_e32 v211, 64, v211
	v_cmp_lt_i32_e32 vcc, v210, v211
	s_nop 1
	v_cndmask_b32_e32 v210, v207, v210, vcc
	v_lshlrev_b32_e32 v210, 2, v210
	ds_bpermute_b32 v210, v210, v209
	s_waitcnt lgkmcnt(0)
	v_add_f32_e32 v209, v209, v210
	v_xor_b32_e32 v210, 32, v207
	v_cmp_lt_i32_e32 vcc, v210, v211
	s_nop 1
	v_cndmask_b32_e32 v210, v207, v210, vcc
	v_lshlrev_b32_e32 v210, 2, v210
	ds_bpermute_b32 v210, v210, v209
	s_waitcnt lgkmcnt(0)
	v_add_f32_e32 v209, v209, v210
	v_max_f32_e32 v213, 0, v209

;     __device__ __forceinline__ void operator()(const f32x4 (&acc)[2][2][4][2], const Unit& u, int wr, int wc, int fr, int fq, PG8_LAS unsigned char* lds) const {
;     ...
;                 const int row = u.pm * BM + ai * HALF + wr * 64 + m * 16 + fr; const int t = row & tmask;
;                 const float rs = __builtin_amdgcn_rsqf((float)rss[row] * (2.3283064365386963e-10f / 1024.0f) + 1e-6f);
;                 f32x4 v[2][2];
; #pragma unroll
;                 for (int bj = 0; bj < 2; ++bj)
; #pragma unroll
;                     for (int n = 0; n < 2; ++n) v[bj][n] = acc[ai][bj][m][n] * rs;
;                 if (type <= 1) {
;                     float ss = 0.f;
; #pragma unroll
;                     for (int bj = 0; bj < 2; ++bj)
; #pragma unroll
;                         for (int n = 0; n < 2; ++n) { const f32x4 x = v[bj][n]; ss += (x[0] * x[0] + x[1] * x[1]) + (x[2] * x[2] + x[3] * x[3]); }
;                     ss += __shfl_xor(ss, 16); ss += __shfl_xor(ss, 32);
;                     float rn = __builtin_amdgcn_rsqf(ss * (1.0f / 64.0f) + 1e-6f); if (type == 0) rn *= QSCALE;
; #pragma unroll
;                     for (int bj = 0; bj < 2; ++bj) { const float pf = (float)(bj == 0 ? (t >> 6) : (t & 63)); f32x4 c, s;
; #pragma unroll
;                         for (int e = 0; e < 4; ++e) { const float a = __builtin_amdgcn_fractf(pf * f4[0][e]); c[e] = __builtin_amdgcn_cosf(a); s[e] = __builtin_amdgcn_sinf(a); }
;                         const f32x4 x1 = v[bj][0] * g[bj][0] * rn, x2 = v[bj][1] * g[bj][1] * rn;
;                         v[bj][0] = x1 * c - x2 * s; v[bj][1] = x1 * s + x2 * c; }
;                 } else if (type >= 3) {
;                     const float sc = type == 3 ? QSCALE : 1.0f; const float tf = (float)t;
; #pragma unroll
;                     for (int n = 0; n < 2; ++n) { f32x4 c, s;
; #pragma unroll
;                         for (int e = 0; e < 4; ++e) { const float a = __builtin_amdgcn_fractf(tf * f4[n][e]); c[e] = __builtin_amdgcn_cosf(a) * sc; s[e] = __builtin_amdgcn_sinf(a) * sc; }
;                         const f32x4 x1 = v[0][n], x2 = v[1][n];
;                         v[0][n] = x1 * c - x2 * s; v[1][n] = x1 * s + x2 * c; }
;                     if (type == 4) { float ks = 0.f;
; #pragma unroll
;                         for (int bj = 0; bj < 2; ++bj)
; #pragma unroll
.LBB0_706:
	v_mad_i64_i32 v[136:137], s[12:13], s74, v208, v[190:191]
	v_lshlrev_b64 v[136:137], 7, v[136:137]
	v_lshl_add_u64 v[140:141], v[176:177], 0, v[136:137]
	v_cvt_pk_bf16_f32 v136, v152, v153
	v_cvt_pk_bf16_f32 v137, v154, v155
	v_cvt_pk_bf16_f32 v138, v160, v161
	v_cvt_pk_bf16_f32 v139, v162, v163
	v_add_u32_e32 v152, s67, v194
	v_permlane16_swap_b32_e32 v136, v138
	v_permlane16_swap_b32_e32 v137, v139
	global_store_dwordx4 v[140:141], v[136:139], off
	v_ashrrev_i32_e32 v153, 31, v152
	s_andn2_b64 vcc, exec, s[80:81]
	v_cvt_pk_bf16_f32 v136, v156, v157
	v_cvt_pk_bf16_f32 v137, v158, v159
	v_cvt_pk_bf16_f32 v138, v164, v165
	v_cvt_pk_bf16_f32 v139, v166, v167
	v_and_b32_e32 v159, s69, v152
	v_permlane16_swap_b32_e32 v136, v138
	v_permlane16_swap_b32_e32 v137, v139
	global_store_dwordx4 v[140:141], v[136:139], off offset:64
	s_nop 1
	s_waitcnt vmcnt(2)
	v_mov_b64_e32 v[136:137], v[224:225]
	v_ffbh_u32_e32 v138, v137
	v_min_u32_e32 v138, 32, v138
	v_lshlrev_b64 v[136:137], v138, v[136:137]
	v_min_u32_e32 v136, 1, v136
	v_or_b32_e32 v136, v137, v136
	v_cvt_f32_u32_e32 v136, v136
	v_sub_u32_e32 v138, 32, v138
	v_cndmask_b32_e64 v137, 0, 1, s[80:81]
	v_cmp_ne_u32_e64 s[12:13], 1, v137
	v_ldexp_f32 v136, v136, v138
	v_fmamk_f32 v136, v136, 0x2a800000, v204
	v_rsq_f32_e32 v136, v136
	s_mov_b64 s[80:81], -1
	v_pk_mul_f32 v[134:135], v[134:135], v[136:137] op_sel_hi:[1,0]
	v_pk_mul_f32 v[132:133], v[132:133], v[136:137] op_sel_hi:[1,0]
	v_pk_mul_f32 v[130:131], v[130:131], v[136:137] op_sel_hi:[1,0]
	v_pk_mul_f32 v[128:129], v[128:129], v[136:137] op_sel_hi:[1,0]
	v_pk_mul_f32 v[126:127], v[126:127], v[136:137] op_sel_hi:[1,0]
	v_pk_mul_f32 v[124:125], v[124:125], v[136:137] op_sel_hi:[1,0]
	v_pk_mul_f32 v[122:123], v[122:123], v[136:137] op_sel_hi:[1,0]
	v_pk_mul_f32 v[120:121], v[120:121], v[136:137] op_sel_hi:[1,0]
	s_cbranch_vccnz .LBB0_711
	v_mov_b64_e32 v[138:139], v[134:135]
	v_mov_b64_e32 v[146:147], v[130:131]
	v_mov_b64_e32 v[142:143], v[126:127]
	v_mov_b64_e32 v[150:151], v[122:123]
	s_and_b64 vcc, exec, s[10:11]
	v_mov_b32_e32 v158, v213
	v_mov_b64_e32 v[136:137], v[132:133]
	v_mov_b64_e32 v[144:145], v[128:129]
	v_mov_b64_e32 v[140:141], v[124:125]
	v_mov_b64_e32 v[148:149], v[120:121]
	s_cbranch_vccnz .LBB0_710
	v_cvt_f32_u32_e32 v149, v159
	s_andn2_b64 vcc, exec, s[78:79]
	v_mov_b32_e32 v158, v213
	v_mul_f32_e32 v140, v30, v149
	v_fract_f32_e32 v141, v140
	v_mul_f32_e32 v136, v28, v149
	v_mul_f32_e32 v137, v29, v149
	v_cos_f32_e32 v140, v141
	v_sin_f32_e32 v142, v141
	v_mul_f32_e32 v141, v31, v149
	v_fract_f32_e32 v138, v136
	v_fract_f32_e32 v139, v137
	v_fract_f32_e32 v143, v141
	v_cos_f32_e32 v136, v138
	v_sin_f32_e32 v138, v138
	v_cos_f32_e32 v137, v139
	v_cos_f32_e32 v141, v143
	v_sin_f32_e32 v143, v143
	v_sin_f32_e32 v139, v139
	v_pk_mul_f32 v[144:145], v[188:189], v[136:137] op_sel_hi:[0,1]
	v_pk_mul_f32 v[140:141], v[188:189], v[140:141] op_sel_hi:[0,1]
	v_pk_mul_f32 v[142:143], v[188:189], v[142:143] op_sel_hi:[0,1]
	v_pk_mul_f32 v[146:147], v[188:189], v[138:139] op_sel_hi:[0,1]
	v_pk_mul_f32 v[136:137], v[146:147], v[124:125]
	v_pk_mul_f32 v[138:139], v[142:143], v[126:127]
	v_pk_fma_f32 v[136:137], v[144:145], v[132:133], v[136:137] neg_lo:[0,0,1] neg_hi:[0,0,1]
	v_pk_fma_f32 v[138:139], v[140:141], v[134:135], v[138:139] neg_lo:[0,0,1] neg_hi:[0,0,1]
	v_pk_mul_f32 v[144:145], v[144:145], v[124:125]
	v_pk_mul_f32 v[140:141], v[140:141], v[126:127]
	v_mul_f32_e32 v148, v54, v149
	v_pk_fma_f32 v[142:143], v[142:143], v[134:135], v[140:141]
	v_pk_fma_f32 v[140:141], v[146:147], v[132:133], v[144:145]
	v_mul_f32_e32 v144, v52, v149
	v_fract_f32_e32 v145, v144
	v_cos_f32_e32 v144, v145
	v_sin_f32_e32 v146, v145
	v_mul_f32_e32 v145, v53, v149
	v_mul_f32_e32 v149, v55, v149
	v_fract_f32_e32 v147, v145
	v_fract_f32_e32 v150, v148
	v_fract_f32_e32 v151, v149
	v_cos_f32_e32 v145, v147
	v_cos_f32_e32 v148, v150
	v_sin_f32_e32 v150, v150
	v_cos_f32_e32 v149, v151
	v_sin_f32_e32 v151, v151
	v_sin_f32_e32 v147, v147
	v_pk_mul_f32 v[154:155], v[188:189], v[144:145] op_sel_hi:[0,1]
	v_pk_mul_f32 v[148:149], v[188:189], v[148:149] op_sel_hi:[0,1]
	v_pk_mul_f32 v[150:151], v[188:189], v[150:151] op_sel_hi:[0,1]
	v_pk_mul_f32 v[156:157], v[188:189], v[146:147] op_sel_hi:[0,1]
	v_pk_mul_f32 v[144:145], v[156:157], v[120:121]
	v_pk_mul_f32 v[146:147], v[150:151], v[122:123]
	v_pk_fma_f32 v[144:145], v[154:155], v[128:129], v[144:145] neg_lo:[0,0,1] neg_hi:[0,0,1]
	v_pk_fma_f32 v[146:147], v[148:149], v[130:131], v[146:147] neg_lo:[0,0,1] neg_hi:[0,0,1]
	v_pk_mul_f32 v[154:155], v[154:155], v[120:121]
	v_pk_mul_f32 v[148:149], v[148:149], v[122:123]
	s_nop 0
	v_pk_fma_f32 v[150:151], v[150:151], v[130:131], v[148:149]
	v_pk_fma_f32 v[148:149], v[156:157], v[128:129], v[154:155]
	s_cbranch_vccnz .LBB0_710
	v_pk_mul_f32 v[154:155], v[138:139], v[138:139]
	v_pk_mul_f32 v[156:157], v[136:137], v[136:137]
	s_nop 0
	v_pk_mov_b32 v[160:161], v[156:157], v[154:155] op_sel:[1,0]
	v_mov_b32_e32 v157, v155
	v_pk_add_f32 v[154:155], v[160:161], v[156:157]
	v_pk_mul_f32 v[156:157], v[146:147], v[146:147]
	v_pk_add_f32 v[154:155], v[154:155], v[154:155] op_sel_hi:[0,1]
	v_pk_mul_f32 v[160:161], v[144:145], v[144:145]
	v_mul_f32_e32 v154, v140, v140
	v_pk_mov_b32 v[162:163], v[160:161], v[156:157] op_sel:[1,0]
	v_mov_b32_e32 v161, v157
	v_pk_add_f32 v[156:157], v[162:163], v[160:161]
	v_pk_fma_f32 v[160:161], v[140:141], v[140:141], v[154:155] op_sel_hi:[1,1,0]
	v_mul_f32_e32 v154, v142, v142
	v_pk_add_f32 v[156:157], v[156:157], v[156:157] op_sel_hi:[0,1]
	v_pk_fma_f32 v[162:163], v[142:143], v[142:143], v[154:155] op_sel_hi:[1,1,0]
	v_mul_f32_e32 v160, v148, v148
	v_mul_f32_e32 v162, v149, v149
	v_mul_f32_e32 v154, v150, v150
	v_mul_f32_e32 v156, v151, v151
	v_pk_add_f32 v[160:161], v[160:161], v[162:163]
	v_pk_add_f32 v[154:155], v[154:155], v[156:157]
	v_and_b32_e32 v156, 64, v207
	v_pk_add_f32 v[154:155], v[160:161], v[154:155]
	v_add_u32_e32 v156, 64, v156
	v_add_f32_e32 v154, v154, v155
	v_xor_b32_e32 v155, 16, v207
	v_cmp_lt_i32_e32 vcc, v155, v156
	s_nop 1
	v_cndmask_b32_e32 v155, v207, v155, vcc
	v_lshlrev_b32_e32 v155, 2, v155
	ds_bpermute_b32 v155, v155, v154
	s_waitcnt lgkmcnt(0)
	v_add_f32_e32 v154, v154, v155
	v_xor_b32_e32 v155, 32, v207
	v_cmp_lt_i32_e32 vcc, v155, v156
	s_nop 1
	v_cndmask_b32_e32 v155, v207, v155, vcc
	v_lshlrev_b32_e32 v155, 2, v155
	ds_bpermute_b32 v155, v155, v154
	s_waitcnt lgkmcnt(0)
	v_add_f32_e32 v154, v154, v155
	v_max_f32_e32 v155, v213, v213
	v_max_f32_e32 v158, v155, v154

;     __device__ __forceinline__ void operator()(const f32x4 (&acc)[2][2][4][2], const Unit& u, int wr, int wc, int fr, int fq, PG8_LAS unsigned char* lds) const {
;     ...
;                 const int row = u.pm * BM + ai * HALF + wr * 64 + m * 16 + fr; const int t = row & tmask;
;                 const float rs = __builtin_amdgcn_rsqf((float)rss[row] * (2.3283064365386963e-10f / 1024.0f) + 1e-6f);
;                 f32x4 v[2][2];
; #pragma unroll
;                 for (int bj = 0; bj < 2; ++bj)
; #pragma unroll
;                     for (int n = 0; n < 2; ++n) v[bj][n] = acc[ai][bj][m][n] * rs;
;                 if (type <= 1) {
;                     float ss = 0.f;
; #pragma unroll
;                     for (int bj = 0; bj < 2; ++bj)
; #pragma unroll
;                         for (int n = 0; n < 2; ++n) { const f32x4 x = v[bj][n]; ss += (x[0] * x[0] + x[1] * x[1]) + (x[2] * x[2] + x[3] * x[3]); }
;                     ss += __shfl_xor(ss, 16); ss += __shfl_xor(ss, 32);
;                     float rn = __builtin_amdgcn_rsqf(ss * (1.0f / 64.0f) + 1e-6f); if (type == 0) rn *= QSCALE;
; #pragma unroll
;                     for (int bj = 0; bj < 2; ++bj) { const float pf = (float)(bj == 0 ? (t >> 6) : (t & 63)); f32x4 c, s;
; #pragma unroll
;                         for (int e = 0; e < 4; ++e) { const float a = __builtin_amdgcn_fractf(pf * f4[0][e]); c[e] = __builtin_amdgcn_cosf(a); s[e] = __builtin_amdgcn_sinf(a); }
;                         const f32x4 x1 = v[bj][0] * g[bj][0] * rn, x2 = v[bj][1] * g[bj][1] * rn;
;                         v[bj][0] = x1 * c - x2 * s; v[bj][1] = x1 * s + x2 * c; }
;                 } else if (type >= 3) {
;                     const float sc = type == 3 ? QSCALE : 1.0f; const float tf = (float)t;
; #pragma unroll
;                     for (int n = 0; n < 2; ++n) { f32x4 c, s;
; #pragma unroll
;                         for (int e = 0; e < 4; ++e) { const float a = __builtin_amdgcn_fractf(tf * f4[n][e]); c[e] = __builtin_amdgcn_cosf(a) * sc; s[e] = __builtin_amdgcn_sinf(a) * sc; }
;                         const f32x4 x1 = v[0][n], x2 = v[1][n];
;                         v[0][n] = x1 * c - x2 * s; v[1][n] = x1 * s + x2 * c; }
;                     if (type == 4) { float ks = 0.f;
; #pragma unroll
;                         for (int bj = 0; bj < 2; ++bj)
; #pragma unroll
.LBB0_713:
	s_mul_hi_i32 s81, s74, 0x14000
	s_mul_i32 s80, s74, 0x14000
	v_lshl_add_u64 v[120:121], s[80:81], 0, v[152:153]
	v_lshlrev_b64 v[120:121], 7, v[120:121]
	v_lshl_add_u64 v[124:125], v[176:177], 0, v[120:121]
	v_cvt_pk_bf16_f32 v120, v136, v137
	v_cvt_pk_bf16_f32 v121, v138, v139
	v_cvt_pk_bf16_f32 v122, v144, v145
	v_cvt_pk_bf16_f32 v123, v146, v147
	v_add_u32_e32 v136, s67, v196
	v_permlane16_swap_b32_e32 v120, v122
	v_permlane16_swap_b32_e32 v121, v123
	global_store_dwordx4 v[124:125], v[120:123], off
	v_ashrrev_i32_e32 v137, 31, v136
	s_and_b64 vcc, exec, s[12:13]
	v_cvt_pk_bf16_f32 v120, v140, v141
	v_cvt_pk_bf16_f32 v121, v142, v143
	v_cvt_pk_bf16_f32 v122, v148, v149
	v_cvt_pk_bf16_f32 v123, v150, v151
	v_and_b32_e32 v143, s69, v136
	v_permlane16_swap_b32_e32 v120, v122
	v_permlane16_swap_b32_e32 v121, v123
	global_store_dwordx4 v[124:125], v[120:123], off offset:64
	s_mov_b64 s[82:83], -1
	s_nop 0
	s_waitcnt vmcnt(4)
	v_mov_b64_e32 v[120:121], v[226:227]
	v_ffbh_u32_e32 v122, v121
	v_min_u32_e32 v122, 32, v122
	v_lshlrev_b64 v[120:121], v122, v[120:121]
	v_min_u32_e32 v120, 1, v120
	v_or_b32_e32 v120, v121, v120
	v_cvt_f32_u32_e32 v120, v120
	v_sub_u32_e32 v121, 32, v122
	v_ldexp_f32 v120, v120, v121
	v_fmamk_f32 v120, v120, 0x2a800000, v204
	v_rsq_f32_e32 v120, v120
	s_nop 0
	v_pk_mul_f32 v[118:119], v[118:119], v[120:121] op_sel_hi:[1,0]
	v_pk_mul_f32 v[116:117], v[116:117], v[120:121] op_sel_hi:[1,0]
	v_pk_mul_f32 v[114:115], v[114:115], v[120:121] op_sel_hi:[1,0]
	v_pk_mul_f32 v[112:113], v[112:113], v[120:121] op_sel_hi:[1,0]
	v_pk_mul_f32 v[110:111], v[110:111], v[120:121] op_sel_hi:[1,0]
	v_pk_mul_f32 v[108:109], v[108:109], v[120:121] op_sel_hi:[1,0]
	v_pk_mul_f32 v[106:107], v[106:107], v[120:121] op_sel_hi:[1,0]
	v_pk_mul_f32 v[104:105], v[104:105], v[120:121] op_sel_hi:[1,0]
	s_cbranch_vccnz .LBB0_718
	v_mov_b64_e32 v[122:123], v[118:119]
	v_mov_b64_e32 v[130:131], v[114:115]
	v_mov_b64_e32 v[126:127], v[110:111]
	v_mov_b64_e32 v[134:135], v[106:107]
	s_and_b64 vcc, exec, s[10:11]
	v_mov_b32_e32 v142, v158
	v_mov_b64_e32 v[120:121], v[116:117]
	v_mov_b64_e32 v[128:129], v[112:113]
	v_mov_b64_e32 v[124:125], v[108:109]
	v_mov_b64_e32 v[132:133], v[104:105]
	s_cbranch_vccnz .LBB0_717
	v_cvt_f32_u32_e32 v133, v143
	s_andn2_b64 vcc, exec, s[78:79]
	v_mov_b32_e32 v142, v158
	v_mul_f32_e32 v124, v30, v133
	v_fract_f32_e32 v125, v124
	v_mul_f32_e32 v120, v28, v133
	v_mul_f32_e32 v121, v29, v133
	v_cos_f32_e32 v124, v125
	v_sin_f32_e32 v126, v125
	v_mul_f32_e32 v125, v31, v133
	v_fract_f32_e32 v122, v120
	v_fract_f32_e32 v123, v121
	v_fract_f32_e32 v127, v125
	v_cos_f32_e32 v120, v122
	v_sin_f32_e32 v122, v122
	v_cos_f32_e32 v121, v123
	v_cos_f32_e32 v125, v127
	v_sin_f32_e32 v127, v127
	v_sin_f32_e32 v123, v123
	v_pk_mul_f32 v[128:129], v[188:189], v[120:121] op_sel_hi:[0,1]
	v_pk_mul_f32 v[124:125], v[188:189], v[124:125] op_sel_hi:[0,1]
	v_pk_mul_f32 v[126:127], v[188:189], v[126:127] op_sel_hi:[0,1]
	v_pk_mul_f32 v[130:131], v[188:189], v[122:123] op_sel_hi:[0,1]
	v_pk_mul_f32 v[120:121], v[130:131], v[108:109]
	v_pk_mul_f32 v[122:123], v[126:127], v[110:111]
	v_pk_fma_f32 v[120:121], v[128:129], v[116:117], v[120:121] neg_lo:[0,0,1] neg_hi:[0,0,1]
	v_pk_fma_f32 v[122:123], v[124:125], v[118:119], v[122:123] neg_lo:[0,0,1] neg_hi:[0,0,1]
	v_pk_mul_f32 v[128:129], v[128:129], v[108:109]
	v_pk_mul_f32 v[124:125], v[124:125], v[110:111]
	v_mul_f32_e32 v132, v54, v133
	v_pk_fma_f32 v[126:127], v[126:127], v[118:119], v[124:125]
	v_pk_fma_f32 v[124:125], v[130:131], v[116:117], v[128:129]
	v_mul_f32_e32 v128, v52, v133
	v_fract_f32_e32 v129, v128
	v_cos_f32_e32 v128, v129
	v_sin_f32_e32 v130, v129
	v_mul_f32_e32 v129, v53, v133
	v_mul_f32_e32 v133, v55, v133
	v_fract_f32_e32 v131, v129
	v_fract_f32_e32 v134, v132
	v_fract_f32_e32 v135, v133
	v_cos_f32_e32 v129, v131
	v_cos_f32_e32 v132, v134
	v_sin_f32_e32 v134, v134
	v_cos_f32_e32 v133, v135
	v_sin_f32_e32 v135, v135
	v_sin_f32_e32 v131, v131
	v_pk_mul_f32 v[138:139], v[188:189], v[128:129] op_sel_hi:[0,1]
	v_pk_mul_f32 v[132:133], v[188:189], v[132:133] op_sel_hi:[0,1]
	v_pk_mul_f32 v[134:135], v[188:189], v[134:135] op_sel_hi:[0,1]
	v_pk_mul_f32 v[140:141], v[188:189], v[130:131] op_sel_hi:[0,1]
	v_pk_mul_f32 v[128:129], v[140:141], v[104:105]
	v_pk_mul_f32 v[130:131], v[134:135], v[106:107]
	v_pk_fma_f32 v[128:129], v[138:139], v[112:113], v[128:129] neg_lo:[0,0,1] neg_hi:[0,0,1]
	v_pk_fma_f32 v[130:131], v[132:133], v[114:115], v[130:131] neg_lo:[0,0,1] neg_hi:[0,0,1]
	v_pk_mul_f32 v[138:139], v[138:139], v[104:105]
	v_pk_mul_f32 v[132:133], v[132:133], v[106:107]
	s_nop 0
	v_pk_fma_f32 v[134:135], v[134:135], v[114:115], v[132:133]
	v_pk_fma_f32 v[132:133], v[140:141], v[112:113], v[138:139]
	s_cbranch_vccnz .LBB0_717
	v_pk_mul_f32 v[138:139], v[122:123], v[122:123]
	v_pk_mul_f32 v[140:141], v[120:121], v[120:121]
	s_nop 0
	v_pk_mov_b32 v[144:145], v[140:141], v[138:139] op_sel:[1,0]
	v_mov_b32_e32 v141, v139
	v_pk_add_f32 v[138:139], v[144:145], v[140:141]
	v_pk_mul_f32 v[140:141], v[130:131], v[130:131]
	v_pk_add_f32 v[138:139], v[138:139], v[138:139] op_sel_hi:[0,1]
	v_pk_mul_f32 v[144:145], v[128:129], v[128:129]
	v_mul_f32_e32 v138, v124, v124
	v_pk_mov_b32 v[146:147], v[144:145], v[140:141] op_sel:[1,0]
	v_mov_b32_e32 v145, v141
	v_pk_add_f32 v[140:141], v[146:147], v[144:145]
	v_pk_fma_f32 v[144:145], v[124:125], v[124:125], v[138:139] op_sel_hi:[1,1,0]
	v_mul_f32_e32 v138, v126, v126
	v_pk_add_f32 v[140:141], v[140:141], v[140:141] op_sel_hi:[0,1]
	v_pk_fma_f32 v[146:147], v[126:127], v[126:127], v[138:139] op_sel_hi:[1,1,0]
	v_mul_f32_e32 v144, v132, v132
	v_mul_f32_e32 v146, v133, v133
	v_mul_f32_e32 v138, v134, v134
	v_mul_f32_e32 v140, v135, v135
	v_pk_add_f32 v[144:145], v[144:145], v[146:147]
	v_pk_add_f32 v[138:139], v[138:139], v[140:141]
	v_and_b32_e32 v140, 64, v207
	v_pk_add_f32 v[138:139], v[144:145], v[138:139]
	v_add_u32_e32 v140, 64, v140
	v_add_f32_e32 v138, v138, v139
	v_xor_b32_e32 v139, 16, v207
	v_cmp_lt_i32_e32 vcc, v139, v140
	s_nop 1
	v_cndmask_b32_e32 v139, v207, v139, vcc
	v_lshlrev_b32_e32 v139, 2, v139
	ds_bpermute_b32 v139, v139, v138
	s_waitcnt lgkmcnt(0)
	v_add_f32_e32 v138, v138, v139
	v_xor_b32_e32 v139, 32, v207
	v_cmp_lt_i32_e32 vcc, v139, v140
	s_nop 1
	v_cndmask_b32_e32 v139, v207, v139, vcc
	v_lshlrev_b32_e32 v139, 2, v139
	ds_bpermute_b32 v139, v139, v138
	s_waitcnt lgkmcnt(0)
	v_add_f32_e32 v138, v138, v139
	v_max_f32_e32 v139, v158, v158
	v_max_f32_e32 v142, v139, v138

;     __device__ __forceinline__ void operator()(const f32x4 (&acc)[2][2][4][2], const Unit& u, int wr, int wc, int fr, int fq, PG8_LAS unsigned char* lds) const {
;     ...
;                 const int row = u.pm * BM + ai * HALF + wr * 64 + m * 16 + fr; const int t = row & tmask;
;                 const float rs = __builtin_amdgcn_rsqf((float)rss[row] * (2.3283064365386963e-10f / 1024.0f) + 1e-6f);
;                 f32x4 v[2][2];
; #pragma unroll
;                 for (int bj = 0; bj < 2; ++bj)
; #pragma unroll
;                     for (int n = 0; n < 2; ++n) v[bj][n] = acc[ai][bj][m][n] * rs;
;                 if (type <= 1) {
;                     float ss = 0.f;
; #pragma unroll
;                     for (int bj = 0; bj < 2; ++bj)
; #pragma unroll
;                         for (int n = 0; n < 2; ++n) { const f32x4 x = v[bj][n]; ss += (x[0] * x[0] + x[1] * x[1]) + (x[2] * x[2] + x[3] * x[3]); }
;                     ss += __shfl_xor(ss, 16); ss += __shfl_xor(ss, 32);
;                     float rn = __builtin_amdgcn_rsqf(ss * (1.0f / 64.0f) + 1e-6f); if (type == 0) rn *= QSCALE;
; #pragma unroll
;                     for (int bj = 0; bj < 2; ++bj) { const float pf = (float)(bj == 0 ? (t >> 6) : (t & 63)); f32x4 c, s;
; #pragma unroll
;                         for (int e = 0; e < 4; ++e) { const float a = __builtin_amdgcn_fractf(pf * f4[0][e]); c[e] = __builtin_amdgcn_cosf(a); s[e] = __builtin_amdgcn_sinf(a); }
;                         const f32x4 x1 = v[bj][0] * g[bj][0] * rn, x2 = v[bj][1] * g[bj][1] * rn;
;                         v[bj][0] = x1 * c - x2 * s; v[bj][1] = x1 * s + x2 * c; }
;                 } else if (type >= 3) {
;                     const float sc = type == 3 ? QSCALE : 1.0f; const float tf = (float)t;
; #pragma unroll
;                     for (int n = 0; n < 2; ++n) { f32x4 c, s;
; #pragma unroll
;                         for (int e = 0; e < 4; ++e) { const float a = __builtin_amdgcn_fractf(tf * f4[n][e]); c[e] = __builtin_amdgcn_cosf(a) * sc; s[e] = __builtin_amdgcn_sinf(a) * sc; }
;                         const f32x4 x1 = v[0][n], x2 = v[1][n];
;                         v[0][n] = x1 * c - x2 * s; v[1][n] = x1 * s + x2 * c; }
;                     if (type == 4) { float ks = 0.f;
; #pragma unroll
;                         for (int bj = 0; bj < 2; ++bj)
; #pragma unroll
.LBB0_720:
	v_lshl_add_u64 v[104:105], s[80:81], 0, v[136:137]
	v_lshlrev_b64 v[104:105], 7, v[104:105]
	v_lshl_add_u64 v[108:109], v[176:177], 0, v[104:105]
	v_cvt_pk_bf16_f32 v104, v120, v121
	v_cvt_pk_bf16_f32 v105, v122, v123
	v_cvt_pk_bf16_f32 v106, v128, v129
	v_cvt_pk_bf16_f32 v107, v130, v131
	v_add_u32_e32 v120, s67, v198
	v_permlane16_swap_b32_e32 v104, v106
	v_permlane16_swap_b32_e32 v105, v107
	global_store_dwordx4 v[108:109], v[104:107], off
	v_ashrrev_i32_e32 v121, 31, v120
	s_and_b64 vcc, exec, s[12:13]
	v_cvt_pk_bf16_f32 v104, v124, v125
	v_cvt_pk_bf16_f32 v105, v126, v127
	v_cvt_pk_bf16_f32 v106, v132, v133
	v_cvt_pk_bf16_f32 v107, v134, v135
	v_and_b32_e32 v127, s69, v120
	v_permlane16_swap_b32_e32 v104, v106
	v_permlane16_swap_b32_e32 v105, v107
	global_store_dwordx4 v[108:109], v[104:107], off offset:64
	s_mov_b64 s[82:83], -1
	s_nop 0
	s_waitcnt vmcnt(6)
	v_mov_b64_e32 v[104:105], v[228:229]
	v_ffbh_u32_e32 v106, v105
	v_min_u32_e32 v106, 32, v106
	v_lshlrev_b64 v[104:105], v106, v[104:105]
	v_min_u32_e32 v104, 1, v104
	v_or_b32_e32 v104, v105, v104
	v_cvt_f32_u32_e32 v104, v104
	v_sub_u32_e32 v105, 32, v106
	v_ldexp_f32 v104, v104, v105
	v_fmamk_f32 v104, v104, 0x2a800000, v204
	v_rsq_f32_e32 v104, v104
	s_nop 0
	v_pk_mul_f32 v[102:103], v[102:103], v[104:105] op_sel_hi:[1,0]
	v_pk_mul_f32 v[100:101], v[100:101], v[104:105] op_sel_hi:[1,0]
	v_pk_mul_f32 v[98:99], v[98:99], v[104:105] op_sel_hi:[1,0]
	v_pk_mul_f32 v[96:97], v[96:97], v[104:105] op_sel_hi:[1,0]
	v_pk_mul_f32 v[94:95], v[94:95], v[104:105] op_sel_hi:[1,0]
	v_pk_mul_f32 v[92:93], v[92:93], v[104:105] op_sel_hi:[1,0]
	v_pk_mul_f32 v[90:91], v[90:91], v[104:105] op_sel_hi:[1,0]
	v_pk_mul_f32 v[88:89], v[88:89], v[104:105] op_sel_hi:[1,0]
	s_cbranch_vccnz .LBB0_725
	v_mov_b64_e32 v[106:107], v[102:103]
	v_mov_b64_e32 v[114:115], v[98:99]
	v_mov_b64_e32 v[110:111], v[94:95]
	v_mov_b64_e32 v[118:119], v[90:91]
	s_and_b64 vcc, exec, s[10:11]
	v_mov_b32_e32 v126, v142
	v_mov_b64_e32 v[104:105], v[100:101]
	v_mov_b64_e32 v[112:113], v[96:97]
	v_mov_b64_e32 v[108:109], v[92:93]
	v_mov_b64_e32 v[116:117], v[88:89]
	s_cbranch_vccnz .LBB0_724
	v_cvt_f32_u32_e32 v117, v127
	s_andn2_b64 vcc, exec, s[78:79]
	v_mov_b32_e32 v126, v142
	v_mul_f32_e32 v108, v30, v117
	v_fract_f32_e32 v109, v108
	v_mul_f32_e32 v104, v28, v117
	v_mul_f32_e32 v105, v29, v117
	v_cos_f32_e32 v108, v109
	v_sin_f32_e32 v110, v109
	v_mul_f32_e32 v109, v31, v117
	v_fract_f32_e32 v106, v104
	v_fract_f32_e32 v107, v105
	v_fract_f32_e32 v111, v109
	v_cos_f32_e32 v104, v106
	v_sin_f32_e32 v106, v106
	v_cos_f32_e32 v105, v107
	v_cos_f32_e32 v109, v111
	v_sin_f32_e32 v111, v111
	v_sin_f32_e32 v107, v107
	v_pk_mul_f32 v[112:113], v[188:189], v[104:105] op_sel_hi:[0,1]
	v_pk_mul_f32 v[108:109], v[188:189], v[108:109] op_sel_hi:[0,1]
	v_pk_mul_f32 v[110:111], v[188:189], v[110:111] op_sel_hi:[0,1]
	v_pk_mul_f32 v[114:115], v[188:189], v[106:107] op_sel_hi:[0,1]
	v_pk_mul_f32 v[104:105], v[114:115], v[92:93]
	v_pk_mul_f32 v[106:107], v[110:111], v[94:95]
	v_pk_fma_f32 v[104:105], v[112:113], v[100:101], v[104:105] neg_lo:[0,0,1] neg_hi:[0,0,1]
	v_pk_fma_f32 v[106:107], v[108:109], v[102:103], v[106:107] neg_lo:[0,0,1] neg_hi:[0,0,1]
	v_pk_mul_f32 v[112:113], v[112:113], v[92:93]
	v_pk_mul_f32 v[108:109], v[108:109], v[94:95]
	v_mul_f32_e32 v116, v54, v117
	v_pk_fma_f32 v[110:111], v[110:111], v[102:103], v[108:109]
	v_pk_fma_f32 v[108:109], v[114:115], v[100:101], v[112:113]
	v_mul_f32_e32 v112, v52, v117
	v_fract_f32_e32 v113, v112
	v_cos_f32_e32 v112, v113
	v_sin_f32_e32 v114, v113
	v_mul_f32_e32 v113, v53, v117
	v_mul_f32_e32 v117, v55, v117
	v_fract_f32_e32 v115, v113
	v_fract_f32_e32 v118, v116
	v_fract_f32_e32 v119, v117
	v_cos_f32_e32 v113, v115
	v_cos_f32_e32 v116, v118
	v_sin_f32_e32 v118, v118
	v_cos_f32_e32 v117, v119
	v_sin_f32_e32 v119, v119
	v_sin_f32_e32 v115, v115
	v_pk_mul_f32 v[122:123], v[188:189], v[112:113] op_sel_hi:[0,1]
	v_pk_mul_f32 v[116:117], v[188:189], v[116:117] op_sel_hi:[0,1]
	v_pk_mul_f32 v[118:119], v[188:189], v[118:119] op_sel_hi:[0,1]
	v_pk_mul_f32 v[124:125], v[188:189], v[114:115] op_sel_hi:[0,1]
	v_pk_mul_f32 v[112:113], v[124:125], v[88:89]
	v_pk_mul_f32 v[114:115], v[118:119], v[90:91]
	v_pk_fma_f32 v[112:113], v[122:123], v[96:97], v[112:113] neg_lo:[0,0,1] neg_hi:[0,0,1]
	v_pk_fma_f32 v[114:115], v[116:117], v[98:99], v[114:115] neg_lo:[0,0,1] neg_hi:[0,0,1]
	v_pk_mul_f32 v[122:123], v[122:123], v[88:89]
	v_pk_mul_f32 v[116:117], v[116:117], v[90:91]
	s_nop 0
	v_pk_fma_f32 v[118:119], v[118:119], v[98:99], v[116:117]
	v_pk_fma_f32 v[116:117], v[124:125], v[96:97], v[122:123]
	s_cbranch_vccnz .LBB0_724
	v_pk_mul_f32 v[122:123], v[106:107], v[106:107]
	v_pk_mul_f32 v[124:125], v[104:105], v[104:105]
	s_nop 0
	v_pk_mov_b32 v[128:129], v[124:125], v[122:123] op_sel:[1,0]
	v_mov_b32_e32 v125, v123
	v_pk_add_f32 v[122:123], v[128:129], v[124:125]
	v_pk_mul_f32 v[124:125], v[114:115], v[114:115]
	v_pk_add_f32 v[122:123], v[122:123], v[122:123] op_sel_hi:[0,1]
	v_pk_mul_f32 v[128:129], v[112:113], v[112:113]
	v_mul_f32_e32 v122, v108, v108
	v_pk_mov_b32 v[130:131], v[128:129], v[124:125] op_sel:[1,0]
	v_mov_b32_e32 v129, v125
	v_pk_add_f32 v[124:125], v[130:131], v[128:129]
	v_pk_fma_f32 v[128:129], v[108:109], v[108:109], v[122:123] op_sel_hi:[1,1,0]
	v_mul_f32_e32 v122, v110, v110
	v_pk_add_f32 v[124:125], v[124:125], v[124:125] op_sel_hi:[0,1]
	v_pk_fma_f32 v[130:131], v[110:111], v[110:111], v[122:123] op_sel_hi:[1,1,0]
	v_mul_f32_e32 v128, v116, v116
	v_mul_f32_e32 v130, v117, v117
	v_mul_f32_e32 v122, v118, v118
	v_mul_f32_e32 v124, v119, v119
	v_pk_add_f32 v[128:129], v[128:129], v[130:131]
	v_pk_add_f32 v[122:123], v[122:123], v[124:125]
	v_and_b32_e32 v124, 64, v207
	v_pk_add_f32 v[122:123], v[128:129], v[122:123]
	v_add_u32_e32 v124, 64, v124
	v_add_f32_e32 v122, v122, v123
	v_xor_b32_e32 v123, 16, v207
	v_cmp_lt_i32_e32 vcc, v123, v124
	s_nop 1
	v_cndmask_b32_e32 v123, v207, v123, vcc
	v_lshlrev_b32_e32 v123, 2, v123
	ds_bpermute_b32 v123, v123, v122
	s_waitcnt lgkmcnt(0)
	v_add_f32_e32 v122, v122, v123
	v_xor_b32_e32 v123, 32, v207
	v_cmp_lt_i32_e32 vcc, v123, v124
	s_nop 1
	v_cndmask_b32_e32 v123, v207, v123, vcc
	v_lshlrev_b32_e32 v123, 2, v123
	ds_bpermute_b32 v123, v123, v122
	s_waitcnt lgkmcnt(0)
	v_add_f32_e32 v122, v122, v123
	v_max_f32_e32 v123, v142, v142
	v_max_f32_e32 v126, v123, v122

;     __device__ __forceinline__ void operator()(const f32x4 (&acc)[2][2][4][2], const Unit& u, int wr, int wc, int fr, int fq, PG8_LAS unsigned char* lds) const {
;     ...
;                 const int row = u.pm * BM + ai * HALF + wr * 64 + m * 16 + fr; const int t = row & tmask;
;                 const float rs = __builtin_amdgcn_rsqf((float)rss[row] * (2.3283064365386963e-10f / 1024.0f) + 1e-6f);
;                 f32x4 v[2][2];
; #pragma unroll
;                 for (int bj = 0; bj < 2; ++bj)
; #pragma unroll
;                     for (int n = 0; n < 2; ++n) v[bj][n] = acc[ai][bj][m][n] * rs;
;                 if (type <= 1) {
;                     float ss = 0.f;
; #pragma unroll
;                     for (int bj = 0; bj < 2; ++bj)
; #pragma unroll
;                         for (int n = 0; n < 2; ++n) { const f32x4 x = v[bj][n]; ss += (x[0] * x[0] + x[1] * x[1]) + (x[2] * x[2] + x[3] * x[3]); }
;                     ss += __shfl_xor(ss, 16); ss += __shfl_xor(ss, 32);
;                     float rn = __builtin_amdgcn_rsqf(ss * (1.0f / 64.0f) + 1e-6f); if (type == 0) rn *= QSCALE;
; #pragma unroll
;                     for (int bj = 0; bj < 2; ++bj) { const float pf = (float)(bj == 0 ? (t >> 6) : (t & 63)); f32x4 c, s;
; #pragma unroll
;                         for (int e = 0; e < 4; ++e) { const float a = __builtin_amdgcn_fractf(pf * f4[0][e]); c[e] = __builtin_amdgcn_cosf(a); s[e] = __builtin_amdgcn_sinf(a); }
;                         const f32x4 x1 = v[bj][0] * g[bj][0] * rn, x2 = v[bj][1] * g[bj][1] * rn;
;                         v[bj][0] = x1 * c - x2 * s; v[bj][1] = x1 * s + x2 * c; }
;                 } else if (type >= 3) {
;                     const float sc = type == 3 ? QSCALE : 1.0f; const float tf = (float)t;
; #pragma unroll
;                     for (int n = 0; n < 2; ++n) { f32x4 c, s;
; #pragma unroll
;                         for (int e = 0; e < 4; ++e) { const float a = __builtin_amdgcn_fractf(tf * f4[n][e]); c[e] = __builtin_amdgcn_cosf(a) * sc; s[e] = __builtin_amdgcn_sinf(a) * sc; }
;                         const f32x4 x1 = v[0][n], x2 = v[1][n];
;                         v[0][n] = x1 * c - x2 * s; v[1][n] = x1 * s + x2 * c; }
;                     if (type == 4) { float ks = 0.f;
; #pragma unroll
;                         for (int bj = 0; bj < 2; ++bj)
; #pragma unroll
.LBB0_727:
	v_lshl_add_u64 v[88:89], s[80:81], 0, v[120:121]
	v_lshlrev_b64 v[88:89], 7, v[88:89]
	v_lshl_add_u64 v[92:93], v[176:177], 0, v[88:89]
	v_cvt_pk_bf16_f32 v88, v104, v105
	v_cvt_pk_bf16_f32 v89, v106, v107
	v_cvt_pk_bf16_f32 v90, v112, v113
	v_cvt_pk_bf16_f32 v91, v114, v115
	v_add_u32_e32 v104, 0x80, v190
	v_permlane16_swap_b32_e32 v88, v90
	v_permlane16_swap_b32_e32 v89, v91
	global_store_dwordx4 v[92:93], v[88:91], off
	v_ashrrev_i32_e32 v105, 31, v104
	s_and_b64 vcc, exec, s[12:13]
	v_cvt_pk_bf16_f32 v88, v108, v109
	v_cvt_pk_bf16_f32 v89, v110, v111
	v_cvt_pk_bf16_f32 v90, v116, v117
	v_cvt_pk_bf16_f32 v91, v118, v119
	v_and_b32_e32 v107, s69, v104
	v_permlane16_swap_b32_e32 v88, v90
	v_permlane16_swap_b32_e32 v89, v91
	global_store_dwordx4 v[92:93], v[88:91], off offset:64
	s_mov_b64 s[82:83], -1
	s_nop 0
	s_waitcnt vmcnt(8)
	v_mov_b64_e32 v[88:89], v[230:231]
	v_ffbh_u32_e32 v90, v89
	v_min_u32_e32 v90, 32, v90
	v_lshlrev_b64 v[88:89], v90, v[88:89]
	v_min_u32_e32 v88, 1, v88
	v_or_b32_e32 v88, v89, v88
	v_cvt_f32_u32_e32 v88, v88
	v_sub_u32_e32 v89, 32, v90
	v_ldexp_f32 v88, v88, v89
	v_fmamk_f32 v88, v88, 0x2a800000, v204
	v_rsq_f32_e32 v88, v88
	s_nop 0
	v_pk_mul_f32 v[86:87], v[86:87], v[88:89] op_sel_hi:[1,0]
	v_pk_mul_f32 v[84:85], v[84:85], v[88:89] op_sel_hi:[1,0]
	v_pk_mul_f32 v[82:83], v[82:83], v[88:89] op_sel_hi:[1,0]
	v_pk_mul_f32 v[80:81], v[80:81], v[88:89] op_sel_hi:[1,0]
	v_pk_mul_f32 v[78:79], v[78:79], v[88:89] op_sel_hi:[1,0]
	v_pk_mul_f32 v[76:77], v[76:77], v[88:89] op_sel_hi:[1,0]
	v_pk_mul_f32 v[74:75], v[74:75], v[88:89] op_sel_hi:[1,0]
	v_pk_mul_f32 v[72:73], v[72:73], v[88:89] op_sel_hi:[1,0]
	s_cbranch_vccnz .LBB0_732
	v_mov_b64_e32 v[90:91], v[86:87]
	v_mov_b64_e32 v[98:99], v[82:83]
	v_mov_b64_e32 v[94:95], v[78:79]
	v_mov_b64_e32 v[102:103], v[74:75]
	s_and_b64 vcc, exec, s[10:11]
	v_mov_b32_e32 v106, v126
	v_mov_b64_e32 v[88:89], v[84:85]
	v_mov_b64_e32 v[96:97], v[80:81]
	v_mov_b64_e32 v[92:93], v[76:77]
	v_mov_b64_e32 v[100:101], v[72:73]
	s_cbranch_vccnz .LBB0_731
	v_cvt_f32_u32_e32 v101, v107
	s_andn2_b64 vcc, exec, s[78:79]
	v_mov_b32_e32 v106, v126
	v_mul_f32_e32 v92, v30, v101
	v_fract_f32_e32 v93, v92
	v_mul_f32_e32 v88, v28, v101
	v_mul_f32_e32 v89, v29, v101
	v_cos_f32_e32 v92, v93
	v_sin_f32_e32 v94, v93
	v_mul_f32_e32 v93, v31, v101
	v_fract_f32_e32 v90, v88
	v_fract_f32_e32 v91, v89
	v_fract_f32_e32 v95, v93
	v_cos_f32_e32 v88, v90
	v_sin_f32_e32 v90, v90
	v_cos_f32_e32 v89, v91
	v_cos_f32_e32 v93, v95
	v_sin_f32_e32 v95, v95
	v_sin_f32_e32 v91, v91
	v_pk_mul_f32 v[96:97], v[188:189], v[88:89] op_sel_hi:[0,1]
	v_pk_mul_f32 v[92:93], v[188:189], v[92:93] op_sel_hi:[0,1]
	v_pk_mul_f32 v[94:95], v[188:189], v[94:95] op_sel_hi:[0,1]
	v_pk_mul_f32 v[98:99], v[188:189], v[90:91] op_sel_hi:[0,1]
	v_pk_mul_f32 v[88:89], v[98:99], v[76:77]
	v_pk_mul_f32 v[90:91], v[94:95], v[78:79]
	v_pk_fma_f32 v[88:89], v[96:97], v[84:85], v[88:89] neg_lo:[0,0,1] neg_hi:[0,0,1]
	v_pk_fma_f32 v[90:91], v[92:93], v[86:87], v[90:91] neg_lo:[0,0,1] neg_hi:[0,0,1]
	v_pk_mul_f32 v[96:97], v[96:97], v[76:77]
	v_pk_mul_f32 v[92:93], v[92:93], v[78:79]
	v_mul_f32_e32 v100, v54, v101
	v_pk_fma_f32 v[94:95], v[94:95], v[86:87], v[92:93]
	v_pk_fma_f32 v[92:93], v[98:99], v[84:85], v[96:97]
	v_mul_f32_e32 v96, v52, v101
	v_fract_f32_e32 v97, v96
	v_cos_f32_e32 v96, v97
	v_sin_f32_e32 v98, v97
	v_mul_f32_e32 v97, v53, v101
	v_mul_f32_e32 v101, v55, v101
	v_fract_f32_e32 v99, v97
	v_fract_f32_e32 v102, v100
	v_fract_f32_e32 v103, v101
	v_cos_f32_e32 v97, v99
	v_cos_f32_e32 v100, v102
	v_sin_f32_e32 v102, v102
	v_cos_f32_e32 v101, v103
	v_sin_f32_e32 v103, v103
	v_sin_f32_e32 v99, v99
	v_pk_mul_f32 v[108:109], v[188:189], v[96:97] op_sel_hi:[0,1]
	v_pk_mul_f32 v[100:101], v[188:189], v[100:101] op_sel_hi:[0,1]
	v_pk_mul_f32 v[102:103], v[188:189], v[102:103] op_sel_hi:[0,1]
	v_pk_mul_f32 v[110:111], v[188:189], v[98:99] op_sel_hi:[0,1]
	v_pk_mul_f32 v[96:97], v[110:111], v[72:73]
	v_pk_mul_f32 v[98:99], v[102:103], v[74:75]
	v_pk_fma_f32 v[96:97], v[108:109], v[80:81], v[96:97] neg_lo:[0,0,1] neg_hi:[0,0,1]
	v_pk_fma_f32 v[98:99], v[100:101], v[82:83], v[98:99] neg_lo:[0,0,1] neg_hi:[0,0,1]
	v_pk_mul_f32 v[108:109], v[108:109], v[72:73]
	v_pk_mul_f32 v[100:101], v[100:101], v[74:75]
	s_nop 0
	v_pk_fma_f32 v[102:103], v[102:103], v[82:83], v[100:101]
	v_pk_fma_f32 v[100:101], v[110:111], v[80:81], v[108:109]
	s_cbranch_vccnz .LBB0_731
	v_pk_mul_f32 v[108:109], v[90:91], v[90:91]
	v_pk_mul_f32 v[110:111], v[88:89], v[88:89]
	v_mul_f32_e32 v106, v92, v92
	v_pk_mov_b32 v[112:113], v[110:111], v[108:109] op_sel:[1,0]
	v_mov_b32_e32 v111, v109
	v_pk_add_f32 v[108:109], v[112:113], v[110:111]
	v_pk_mul_f32 v[110:111], v[98:99], v[98:99]
	v_pk_mul_f32 v[112:113], v[96:97], v[96:97]
	v_pk_add_f32 v[108:109], v[108:109], v[108:109] op_sel_hi:[0,1]
	v_pk_mov_b32 v[114:115], v[112:113], v[110:111] op_sel:[1,0]
	v_mov_b32_e32 v113, v111
	v_pk_add_f32 v[110:111], v[114:115], v[112:113]
	v_pk_fma_f32 v[112:113], v[92:93], v[92:93], v[106:107] op_sel_hi:[1,1,0]
	v_mul_f32_e32 v106, v94, v94
	v_pk_add_f32 v[110:111], v[110:111], v[110:111] op_sel_hi:[0,1]
	v_pk_fma_f32 v[114:115], v[94:95], v[94:95], v[106:107] op_sel_hi:[1,1,0]
	v_mul_f32_e32 v112, v100, v100
	v_mul_f32_e32 v114, v101, v101
	v_mul_f32_e32 v108, v102, v102
	v_mul_f32_e32 v110, v103, v103
	v_pk_add_f32 v[112:113], v[112:113], v[114:115]
	v_pk_add_f32 v[108:109], v[108:109], v[110:111]
	s_nop 0
	v_pk_add_f32 v[108:109], v[112:113], v[108:109]
	s_nop 0
	v_add_f32_e32 v106, v108, v109
	v_and_b32_e32 v109, 64, v207
	v_xor_b32_e32 v108, 16, v207
	v_add_u32_e32 v109, 64, v109
	v_cmp_lt_i32_e32 vcc, v108, v109
	s_nop 1
	v_cndmask_b32_e32 v108, v207, v108, vcc
	v_lshlrev_b32_e32 v108, 2, v108
	ds_bpermute_b32 v108, v108, v106
	s_waitcnt lgkmcnt(0)
	v_add_f32_e32 v106, v106, v108
	v_xor_b32_e32 v108, 32, v207
	v_cmp_lt_i32_e32 vcc, v108, v109
	s_nop 1
	v_cndmask_b32_e32 v108, v207, v108, vcc
	v_lshlrev_b32_e32 v108, 2, v108
	ds_bpermute_b32 v108, v108, v106
	s_waitcnt lgkmcnt(0)
	v_add_f32_e32 v106, v106, v108
	v_max_f32_e32 v108, v126, v126
	v_max_f32_e32 v106, v108, v106

;     __device__ __forceinline__ void operator()(const f32x4 (&acc)[2][2][4][2], const Unit& u, int wr, int wc, int fr, int fq, PG8_LAS unsigned char* lds) const {
;     ...
;                 const int row = u.pm * BM + ai * HALF + wr * 64 + m * 16 + fr; const int t = row & tmask;
;                 const float rs = __builtin_amdgcn_rsqf((float)rss[row] * (2.3283064365386963e-10f / 1024.0f) + 1e-6f);
;                 f32x4 v[2][2];
; #pragma unroll
;                 for (int bj = 0; bj < 2; ++bj)
; #pragma unroll
;                     for (int n = 0; n < 2; ++n) v[bj][n] = acc[ai][bj][m][n] * rs;
;                 if (type <= 1) {
;                     float ss = 0.f;
; #pragma unroll
;                     for (int bj = 0; bj < 2; ++bj)
; #pragma unroll
;                         for (int n = 0; n < 2; ++n) { const f32x4 x = v[bj][n]; ss += (x[0] * x[0] + x[1] * x[1]) + (x[2] * x[2] + x[3] * x[3]); }
;                     ss += __shfl_xor(ss, 16); ss += __shfl_xor(ss, 32);
;                     float rn = __builtin_amdgcn_rsqf(ss * (1.0f / 64.0f) + 1e-6f); if (type == 0) rn *= QSCALE;
; #pragma unroll
;                     for (int bj = 0; bj < 2; ++bj) { const float pf = (float)(bj == 0 ? (t >> 6) : (t & 63)); f32x4 c, s;
; #pragma unroll
;                         for (int e = 0; e < 4; ++e) { const float a = __builtin_amdgcn_fractf(pf * f4[0][e]); c[e] = __builtin_amdgcn_cosf(a); s[e] = __builtin_amdgcn_sinf(a); }
;                         const f32x4 x1 = v[bj][0] * g[bj][0] * rn, x2 = v[bj][1] * g[bj][1] * rn;
;                         v[bj][0] = x1 * c - x2 * s; v[bj][1] = x1 * s + x2 * c; }
;                 } else if (type >= 3) {
;                     const float sc = type == 3 ? QSCALE : 1.0f; const float tf = (float)t;
; #pragma unroll
;                     for (int n = 0; n < 2; ++n) { f32x4 c, s;
; #pragma unroll
;                         for (int e = 0; e < 4; ++e) { const float a = __builtin_amdgcn_fractf(tf * f4[n][e]); c[e] = __builtin_amdgcn_cosf(a) * sc; s[e] = __builtin_amdgcn_sinf(a) * sc; }
;                         const f32x4 x1 = v[0][n], x2 = v[1][n];
;                         v[0][n] = x1 * c - x2 * s; v[1][n] = x1 * s + x2 * c; }
;                     if (type == 4) { float ks = 0.f;
; #pragma unroll
;                         for (int bj = 0; bj < 2; ++bj)
; #pragma unroll
.LBB0_734:
	v_lshl_add_u64 v[72:73], s[80:81], 0, v[104:105]
	v_lshlrev_b64 v[72:73], 7, v[72:73]
	v_lshl_add_u64 v[76:77], v[176:177], 0, v[72:73]
	v_cvt_pk_bf16_f32 v72, v88, v89
	v_cvt_pk_bf16_f32 v73, v90, v91
	v_cvt_pk_bf16_f32 v74, v96, v97
	v_cvt_pk_bf16_f32 v75, v98, v99
	v_add_u32_e32 v88, 0x90, v190
	v_permlane16_swap_b32_e32 v72, v74
	v_permlane16_swap_b32_e32 v73, v75
	global_store_dwordx4 v[76:77], v[72:75], off
	v_ashrrev_i32_e32 v89, 31, v88
	s_and_b64 vcc, exec, s[12:13]
	v_cvt_pk_bf16_f32 v72, v92, v93
	v_cvt_pk_bf16_f32 v73, v94, v95
	v_cvt_pk_bf16_f32 v74, v100, v101
	v_cvt_pk_bf16_f32 v75, v102, v103
	v_and_b32_e32 v91, s69, v88
	v_permlane16_swap_b32_e32 v72, v74
	v_permlane16_swap_b32_e32 v73, v75
	global_store_dwordx4 v[76:77], v[72:75], off offset:64
	s_mov_b64 s[82:83], -1
	s_nop 0
	s_waitcnt vmcnt(10)
	v_mov_b64_e32 v[72:73], v[232:233]
	v_ffbh_u32_e32 v74, v73
	v_min_u32_e32 v74, 32, v74
	v_lshlrev_b64 v[72:73], v74, v[72:73]
	v_min_u32_e32 v72, 1, v72
	v_or_b32_e32 v72, v73, v72
	v_cvt_f32_u32_e32 v72, v72
	v_sub_u32_e32 v73, 32, v74
	v_ldexp_f32 v72, v72, v73
	v_fmamk_f32 v72, v72, 0x2a800000, v204
	v_rsq_f32_e32 v72, v72
	s_nop 0
	v_pk_mul_f32 v[70:71], v[70:71], v[72:73] op_sel_hi:[1,0]
	v_pk_mul_f32 v[68:69], v[68:69], v[72:73] op_sel_hi:[1,0]
	v_pk_mul_f32 v[66:67], v[66:67], v[72:73] op_sel_hi:[1,0]
	v_pk_mul_f32 v[64:65], v[64:65], v[72:73] op_sel_hi:[1,0]
	v_pk_mul_f32 v[62:63], v[62:63], v[72:73] op_sel_hi:[1,0]
	v_pk_mul_f32 v[60:61], v[60:61], v[72:73] op_sel_hi:[1,0]
	v_pk_mul_f32 v[58:59], v[58:59], v[72:73] op_sel_hi:[1,0]
	v_pk_mul_f32 v[56:57], v[56:57], v[72:73] op_sel_hi:[1,0]
	s_cbranch_vccnz .LBB0_739
	v_mov_b64_e32 v[74:75], v[70:71]
	v_mov_b64_e32 v[82:83], v[66:67]
	v_mov_b64_e32 v[78:79], v[62:63]
	v_mov_b64_e32 v[86:87], v[58:59]
	s_and_b64 vcc, exec, s[10:11]
	v_mov_b32_e32 v90, v106
	v_mov_b64_e32 v[72:73], v[68:69]
	v_mov_b64_e32 v[80:81], v[64:65]
	v_mov_b64_e32 v[76:77], v[60:61]
	v_mov_b64_e32 v[84:85], v[56:57]
	s_cbranch_vccnz .LBB0_738
	v_cvt_f32_u32_e32 v85, v91
	s_andn2_b64 vcc, exec, s[78:79]
	v_mov_b32_e32 v90, v106
	v_mul_f32_e32 v76, v30, v85
	v_fract_f32_e32 v77, v76
	v_mul_f32_e32 v72, v28, v85
	v_mul_f32_e32 v73, v29, v85
	v_cos_f32_e32 v76, v77
	v_sin_f32_e32 v78, v77
	v_mul_f32_e32 v77, v31, v85
	v_fract_f32_e32 v74, v72
	v_fract_f32_e32 v75, v73
	v_fract_f32_e32 v79, v77
	v_cos_f32_e32 v72, v74
	v_sin_f32_e32 v74, v74
	v_cos_f32_e32 v73, v75
	v_cos_f32_e32 v77, v79
	v_sin_f32_e32 v79, v79
	v_sin_f32_e32 v75, v75
	v_pk_mul_f32 v[80:81], v[188:189], v[72:73] op_sel_hi:[0,1]
	v_pk_mul_f32 v[76:77], v[188:189], v[76:77] op_sel_hi:[0,1]
	v_pk_mul_f32 v[78:79], v[188:189], v[78:79] op_sel_hi:[0,1]
	v_pk_mul_f32 v[82:83], v[188:189], v[74:75] op_sel_hi:[0,1]
	v_pk_mul_f32 v[72:73], v[82:83], v[60:61]
	v_pk_mul_f32 v[74:75], v[78:79], v[62:63]
	v_pk_fma_f32 v[72:73], v[80:81], v[68:69], v[72:73] neg_lo:[0,0,1] neg_hi:[0,0,1]
	v_pk_fma_f32 v[74:75], v[76:77], v[70:71], v[74:75] neg_lo:[0,0,1] neg_hi:[0,0,1]
	v_pk_mul_f32 v[80:81], v[80:81], v[60:61]
	v_pk_mul_f32 v[76:77], v[76:77], v[62:63]
	v_mul_f32_e32 v84, v54, v85
	v_pk_fma_f32 v[78:79], v[78:79], v[70:71], v[76:77]
	v_pk_fma_f32 v[76:77], v[82:83], v[68:69], v[80:81]
	v_mul_f32_e32 v80, v52, v85
	v_fract_f32_e32 v81, v80
	v_cos_f32_e32 v80, v81
	v_sin_f32_e32 v82, v81
	v_mul_f32_e32 v81, v53, v85
	v_mul_f32_e32 v85, v55, v85
	v_fract_f32_e32 v83, v81
	v_fract_f32_e32 v86, v84
	v_fract_f32_e32 v87, v85
	v_cos_f32_e32 v81, v83
	v_cos_f32_e32 v84, v86
	v_sin_f32_e32 v86, v86
	v_cos_f32_e32 v85, v87
	v_sin_f32_e32 v87, v87
	v_sin_f32_e32 v83, v83
	v_pk_mul_f32 v[92:93], v[188:189], v[80:81] op_sel_hi:[0,1]
	v_pk_mul_f32 v[84:85], v[188:189], v[84:85] op_sel_hi:[0,1]
	v_pk_mul_f32 v[86:87], v[188:189], v[86:87] op_sel_hi:[0,1]
	v_pk_mul_f32 v[94:95], v[188:189], v[82:83] op_sel_hi:[0,1]
	v_pk_mul_f32 v[80:81], v[94:95], v[56:57]
	v_pk_mul_f32 v[82:83], v[86:87], v[58:59]
	v_pk_fma_f32 v[80:81], v[92:93], v[64:65], v[80:81] neg_lo:[0,0,1] neg_hi:[0,0,1]
	v_pk_fma_f32 v[82:83], v[84:85], v[66:67], v[82:83] neg_lo:[0,0,1] neg_hi:[0,0,1]
	v_pk_mul_f32 v[92:93], v[92:93], v[56:57]
	v_pk_mul_f32 v[84:85], v[84:85], v[58:59]
	s_nop 0
	v_pk_fma_f32 v[86:87], v[86:87], v[66:67], v[84:85]
	v_pk_fma_f32 v[84:85], v[94:95], v[64:65], v[92:93]
	s_cbranch_vccnz .LBB0_738
	v_pk_mul_f32 v[92:93], v[74:75], v[74:75]
	v_pk_mul_f32 v[94:95], v[72:73], v[72:73]
	v_mul_f32_e32 v90, v76, v76
	v_pk_mov_b32 v[96:97], v[94:95], v[92:93] op_sel:[1,0]
	v_mov_b32_e32 v95, v93
	v_pk_add_f32 v[92:93], v[96:97], v[94:95]
	v_pk_mul_f32 v[94:95], v[82:83], v[82:83]
	v_pk_mul_f32 v[96:97], v[80:81], v[80:81]
	v_pk_add_f32 v[92:93], v[92:93], v[92:93] op_sel_hi:[0,1]
	v_pk_mov_b32 v[98:99], v[96:97], v[94:95] op_sel:[1,0]
	v_mov_b32_e32 v97, v95
	v_pk_add_f32 v[94:95], v[98:99], v[96:97]
	v_pk_fma_f32 v[96:97], v[76:77], v[76:77], v[90:91] op_sel_hi:[1,1,0]
	v_mul_f32_e32 v90, v78, v78
	v_pk_add_f32 v[94:95], v[94:95], v[94:95] op_sel_hi:[0,1]
	v_pk_fma_f32 v[98:99], v[78:79], v[78:79], v[90:91] op_sel_hi:[1,1,0]
	v_mul_f32_e32 v96, v84, v84
	v_mul_f32_e32 v98, v85, v85
	v_mul_f32_e32 v92, v86, v86
	v_mul_f32_e32 v94, v87, v87
	v_pk_add_f32 v[96:97], v[96:97], v[98:99]
	v_pk_add_f32 v[92:93], v[92:93], v[94:95]
	s_nop 0
	v_pk_add_f32 v[92:93], v[96:97], v[92:93]
	s_nop 0
	v_add_f32_e32 v90, v92, v93
	v_and_b32_e32 v93, 64, v207
	v_xor_b32_e32 v92, 16, v207
	v_add_u32_e32 v93, 64, v93
	v_cmp_lt_i32_e32 vcc, v92, v93
	s_nop 1
	v_cndmask_b32_e32 v92, v207, v92, vcc
	v_lshlrev_b32_e32 v92, 2, v92
	ds_bpermute_b32 v92, v92, v90
	s_waitcnt lgkmcnt(0)
	v_add_f32_e32 v90, v90, v92
	v_xor_b32_e32 v92, 32, v207
	v_cmp_lt_i32_e32 vcc, v92, v93
	s_nop 1
	v_cndmask_b32_e32 v92, v207, v92, vcc
	v_lshlrev_b32_e32 v92, 2, v92
	ds_bpermute_b32 v92, v92, v90
	s_waitcnt lgkmcnt(0)
	v_add_f32_e32 v90, v90, v92
	v_max_f32_e32 v92, v106, v106
	v_max_f32_e32 v90, v92, v90

;     __device__ __forceinline__ void operator()(const f32x4 (&acc)[2][2][4][2], const Unit& u, int wr, int wc, int fr, int fq, PG8_LAS unsigned char* lds) const {
;     ...
;                 const int row = u.pm * BM + ai * HALF + wr * 64 + m * 16 + fr; const int t = row & tmask;
;                 const float rs = __builtin_amdgcn_rsqf((float)rss[row] * (2.3283064365386963e-10f / 1024.0f) + 1e-6f);
;                 f32x4 v[2][2];
; #pragma unroll
;                 for (int bj = 0; bj < 2; ++bj)
; #pragma unroll
;                     for (int n = 0; n < 2; ++n) v[bj][n] = acc[ai][bj][m][n] * rs;
;                 if (type <= 1) {
;                     float ss = 0.f;
; #pragma unroll
;                     for (int bj = 0; bj < 2; ++bj)
; #pragma unroll
;                         for (int n = 0; n < 2; ++n) { const f32x4 x = v[bj][n]; ss += (x[0] * x[0] + x[1] * x[1]) + (x[2] * x[2] + x[3] * x[3]); }
;                     ss += __shfl_xor(ss, 16); ss += __shfl_xor(ss, 32);
;                     float rn = __builtin_amdgcn_rsqf(ss * (1.0f / 64.0f) + 1e-6f); if (type == 0) rn *= QSCALE;
; #pragma unroll
;                     for (int bj = 0; bj < 2; ++bj) { const float pf = (float)(bj == 0 ? (t >> 6) : (t & 63)); f32x4 c, s;
; #pragma unroll
;                         for (int e = 0; e < 4; ++e) { const float a = __builtin_amdgcn_fractf(pf * f4[0][e]); c[e] = __builtin_amdgcn_cosf(a); s[e] = __builtin_amdgcn_sinf(a); }
;                         const f32x4 x1 = v[bj][0] * g[bj][0] * rn, x2 = v[bj][1] * g[bj][1] * rn;
;                         v[bj][0] = x1 * c - x2 * s; v[bj][1] = x1 * s + x2 * c; }
;                 } else if (type >= 3) {
;                     const float sc = type == 3 ? QSCALE : 1.0f; const float tf = (float)t;
; #pragma unroll
;                     for (int n = 0; n < 2; ++n) { f32x4 c, s;
; #pragma unroll
;                         for (int e = 0; e < 4; ++e) { const float a = __builtin_amdgcn_fractf(tf * f4[n][e]); c[e] = __builtin_amdgcn_cosf(a) * sc; s[e] = __builtin_amdgcn_sinf(a) * sc; }
;                         const f32x4 x1 = v[0][n], x2 = v[1][n];
;                         v[0][n] = x1 * c - x2 * s; v[1][n] = x1 * s + x2 * c; }
;                     if (type == 4) { float ks = 0.f;
; #pragma unroll
;                         for (int bj = 0; bj < 2; ++bj)
; #pragma unroll
.LBB0_741:
	v_lshl_add_u64 v[56:57], s[80:81], 0, v[88:89]
	v_lshlrev_b64 v[56:57], 7, v[56:57]
	v_lshl_add_u64 v[60:61], v[176:177], 0, v[56:57]
	v_cvt_pk_bf16_f32 v56, v72, v73
	v_cvt_pk_bf16_f32 v57, v74, v75
	v_cvt_pk_bf16_f32 v58, v80, v81
	v_cvt_pk_bf16_f32 v59, v82, v83
	v_add_u32_e32 v72, 0xa0, v190
	v_permlane16_swap_b32_e32 v56, v58
	v_permlane16_swap_b32_e32 v57, v59
	global_store_dwordx4 v[60:61], v[56:59], off
	v_ashrrev_i32_e32 v73, 31, v72
	s_and_b64 vcc, exec, s[12:13]
	v_cvt_pk_bf16_f32 v56, v76, v77
	v_cvt_pk_bf16_f32 v57, v78, v79
	v_cvt_pk_bf16_f32 v58, v84, v85
	v_cvt_pk_bf16_f32 v59, v86, v87
	v_and_b32_e32 v75, s69, v72
	v_permlane16_swap_b32_e32 v56, v58
	v_permlane16_swap_b32_e32 v57, v59
	global_store_dwordx4 v[60:61], v[56:59], off offset:64
	s_mov_b64 s[82:83], -1
	s_nop 0
	s_waitcnt vmcnt(12)
	v_mov_b64_e32 v[56:57], v[234:235]
	v_ffbh_u32_e32 v58, v57
	v_min_u32_e32 v58, 32, v58
	v_lshlrev_b64 v[56:57], v58, v[56:57]
	v_min_u32_e32 v56, 1, v56
	v_or_b32_e32 v56, v57, v56
	v_cvt_f32_u32_e32 v56, v56
	v_sub_u32_e32 v57, 32, v58
	v_ldexp_f32 v56, v56, v57
	v_fmamk_f32 v56, v56, 0x2a800000, v204
	v_rsq_f32_e32 v56, v56
	s_nop 0
	v_pk_mul_f32 v[34:35], v[34:35], v[56:57] op_sel_hi:[1,0]
	v_pk_mul_f32 v[32:33], v[32:33], v[56:57] op_sel_hi:[1,0]
	v_pk_mul_f32 v[26:27], v[26:27], v[56:57] op_sel_hi:[1,0]
	v_pk_mul_f32 v[24:25], v[24:25], v[56:57] op_sel_hi:[1,0]
	v_pk_mul_f32 v[22:23], v[22:23], v[56:57] op_sel_hi:[1,0]
	v_pk_mul_f32 v[20:21], v[20:21], v[56:57] op_sel_hi:[1,0]
	v_pk_mul_f32 v[18:19], v[18:19], v[56:57] op_sel_hi:[1,0]
	v_pk_mul_f32 v[16:17], v[16:17], v[56:57] op_sel_hi:[1,0]
	s_cbranch_vccnz .LBB0_746
	v_mov_b64_e32 v[58:59], v[34:35]
	v_mov_b64_e32 v[66:67], v[26:27]
	v_mov_b64_e32 v[62:63], v[22:23]
	v_mov_b64_e32 v[70:71], v[18:19]
	s_and_b64 vcc, exec, s[10:11]
	v_mov_b32_e32 v74, v90
	v_mov_b64_e32 v[56:57], v[32:33]
	v_mov_b64_e32 v[64:65], v[24:25]
	v_mov_b64_e32 v[60:61], v[20:21]
	v_mov_b64_e32 v[68:69], v[16:17]
	s_cbranch_vccnz .LBB0_745
	v_cvt_f32_u32_e32 v69, v75
	s_andn2_b64 vcc, exec, s[78:79]
	v_mov_b32_e32 v74, v90
	v_mul_f32_e32 v60, v30, v69
	v_fract_f32_e32 v61, v60
	v_mul_f32_e32 v56, v28, v69
	v_mul_f32_e32 v57, v29, v69
	v_cos_f32_e32 v60, v61
	v_sin_f32_e32 v62, v61
	v_mul_f32_e32 v61, v31, v69
	v_fract_f32_e32 v58, v56
	v_fract_f32_e32 v59, v57
	v_fract_f32_e32 v63, v61
	v_cos_f32_e32 v56, v58
	v_sin_f32_e32 v58, v58
	v_cos_f32_e32 v57, v59
	v_cos_f32_e32 v61, v63
	v_sin_f32_e32 v63, v63
	v_sin_f32_e32 v59, v59
	v_pk_mul_f32 v[64:65], v[188:189], v[56:57] op_sel_hi:[0,1]
	v_pk_mul_f32 v[60:61], v[188:189], v[60:61] op_sel_hi:[0,1]
	v_pk_mul_f32 v[62:63], v[188:189], v[62:63] op_sel_hi:[0,1]
	v_pk_mul_f32 v[66:67], v[188:189], v[58:59] op_sel_hi:[0,1]
	v_pk_mul_f32 v[56:57], v[66:67], v[20:21]
	v_pk_mul_f32 v[58:59], v[62:63], v[22:23]
	v_pk_fma_f32 v[56:57], v[64:65], v[32:33], v[56:57] neg_lo:[0,0,1] neg_hi:[0,0,1]
	v_pk_fma_f32 v[58:59], v[60:61], v[34:35], v[58:59] neg_lo:[0,0,1] neg_hi:[0,0,1]
	v_pk_mul_f32 v[64:65], v[64:65], v[20:21]
	v_pk_mul_f32 v[60:61], v[60:61], v[22:23]
	v_mul_f32_e32 v68, v54, v69
	v_pk_fma_f32 v[62:63], v[62:63], v[34:35], v[60:61]
	v_pk_fma_f32 v[60:61], v[66:67], v[32:33], v[64:65]
	v_mul_f32_e32 v64, v52, v69
	v_fract_f32_e32 v65, v64
	v_cos_f32_e32 v64, v65
	v_sin_f32_e32 v66, v65
	v_mul_f32_e32 v65, v53, v69
	v_mul_f32_e32 v69, v55, v69
	v_fract_f32_e32 v67, v65
	v_fract_f32_e32 v70, v68
	v_fract_f32_e32 v71, v69
	v_cos_f32_e32 v65, v67
	v_cos_f32_e32 v68, v70
	v_sin_f32_e32 v70, v70
	v_cos_f32_e32 v69, v71
	v_sin_f32_e32 v71, v71
	v_sin_f32_e32 v67, v67
	v_pk_mul_f32 v[76:77], v[188:189], v[64:65] op_sel_hi:[0,1]
	v_pk_mul_f32 v[68:69], v[188:189], v[68:69] op_sel_hi:[0,1]
	v_pk_mul_f32 v[70:71], v[188:189], v[70:71] op_sel_hi:[0,1]
	v_pk_mul_f32 v[78:79], v[188:189], v[66:67] op_sel_hi:[0,1]
	v_pk_mul_f32 v[64:65], v[78:79], v[16:17]
	v_pk_mul_f32 v[66:67], v[70:71], v[18:19]
	v_pk_fma_f32 v[64:65], v[76:77], v[24:25], v[64:65] neg_lo:[0,0,1] neg_hi:[0,0,1]
	v_pk_fma_f32 v[66:67], v[68:69], v[26:27], v[66:67] neg_lo:[0,0,1] neg_hi:[0,0,1]
	v_pk_mul_f32 v[76:77], v[76:77], v[16:17]
	v_pk_mul_f32 v[68:69], v[68:69], v[18:19]
	s_nop 0
	v_pk_fma_f32 v[70:71], v[70:71], v[26:27], v[68:69]
	v_pk_fma_f32 v[68:69], v[78:79], v[24:25], v[76:77]
	s_cbranch_vccnz .LBB0_745
	v_pk_mul_f32 v[76:77], v[58:59], v[58:59]
	v_pk_mul_f32 v[78:79], v[56:57], v[56:57]
	v_mul_f32_e32 v74, v60, v60
	v_pk_mov_b32 v[80:81], v[78:79], v[76:77] op_sel:[1,0]
	v_mov_b32_e32 v79, v77
	v_pk_add_f32 v[76:77], v[80:81], v[78:79]
	v_pk_mul_f32 v[78:79], v[66:67], v[66:67]
	v_pk_mul_f32 v[80:81], v[64:65], v[64:65]
	v_pk_add_f32 v[76:77], v[76:77], v[76:77] op_sel_hi:[0,1]
	v_pk_mov_b32 v[82:83], v[80:81], v[78:79] op_sel:[1,0]
	v_mov_b32_e32 v81, v79
	v_pk_add_f32 v[78:79], v[82:83], v[80:81]
	v_pk_fma_f32 v[80:81], v[60:61], v[60:61], v[74:75] op_sel_hi:[1,1,0]
	v_mul_f32_e32 v74, v62, v62
	v_pk_add_f32 v[78:79], v[78:79], v[78:79] op_sel_hi:[0,1]
	v_pk_fma_f32 v[82:83], v[62:63], v[62:63], v[74:75] op_sel_hi:[1,1,0]
	v_mul_f32_e32 v80, v68, v68
	v_mul_f32_e32 v82, v69, v69
	v_mul_f32_e32 v76, v70, v70
	v_mul_f32_e32 v78, v71, v71
	v_pk_add_f32 v[80:81], v[80:81], v[82:83]
	v_pk_add_f32 v[76:77], v[76:77], v[78:79]
	s_nop 0
	v_pk_add_f32 v[76:77], v[80:81], v[76:77]
	s_nop 0
	v_add_f32_e32 v74, v76, v77
	v_and_b32_e32 v77, 64, v207
	v_xor_b32_e32 v76, 16, v207
	v_add_u32_e32 v77, 64, v77
	v_cmp_lt_i32_e32 vcc, v76, v77
	s_nop 1
	v_cndmask_b32_e32 v76, v207, v76, vcc
	v_lshlrev_b32_e32 v76, 2, v76
	ds_bpermute_b32 v76, v76, v74
	s_waitcnt lgkmcnt(0)
	v_add_f32_e32 v74, v74, v76
	v_xor_b32_e32 v76, 32, v207
	v_cmp_lt_i32_e32 vcc, v76, v77
	s_nop 1
	v_cndmask_b32_e32 v76, v207, v76, vcc
	v_lshlrev_b32_e32 v76, 2, v76
	ds_bpermute_b32 v76, v76, v74
	s_waitcnt lgkmcnt(0)
	v_add_f32_e32 v74, v74, v76
	v_max_f32_e32 v76, v90, v90
	v_max_f32_e32 v74, v76, v74

;     __device__ __forceinline__ void operator()(const f32x4 (&acc)[2][2][4][2], const Unit& u, int wr, int wc, int fr, int fq, PG8_LAS unsigned char* lds) const {
;     ...
;                 const int row = u.pm * BM + ai * HALF + wr * 64 + m * 16 + fr; const int t = row & tmask;
;                 const float rs = __builtin_amdgcn_rsqf((float)rss[row] * (2.3283064365386963e-10f / 1024.0f) + 1e-6f);
;                 f32x4 v[2][2];
; #pragma unroll
;                 for (int bj = 0; bj < 2; ++bj)
; #pragma unroll
;                     for (int n = 0; n < 2; ++n) v[bj][n] = acc[ai][bj][m][n] * rs;
;                 if (type <= 1) {
;                     float ss = 0.f;
; #pragma unroll
;                     for (int bj = 0; bj < 2; ++bj)
; #pragma unroll
;                         for (int n = 0; n < 2; ++n) { const f32x4 x = v[bj][n]; ss += (x[0] * x[0] + x[1] * x[1]) + (x[2] * x[2] + x[3] * x[3]); }
;                     ss += __shfl_xor(ss, 16); ss += __shfl_xor(ss, 32);
;                     float rn = __builtin_amdgcn_rsqf(ss * (1.0f / 64.0f) + 1e-6f); if (type == 0) rn *= QSCALE;
; #pragma unroll
;                     for (int bj = 0; bj < 2; ++bj) { const float pf = (float)(bj == 0 ? (t >> 6) : (t & 63)); f32x4 c, s;
; #pragma unroll
;                         for (int e = 0; e < 4; ++e) { const float a = __builtin_amdgcn_fractf(pf * f4[0][e]); c[e] = __builtin_amdgcn_cosf(a); s[e] = __builtin_amdgcn_sinf(a); }
;                         const f32x4 x1 = v[bj][0] * g[bj][0] * rn, x2 = v[bj][1] * g[bj][1] * rn;
;                         v[bj][0] = x1 * c - x2 * s; v[bj][1] = x1 * s + x2 * c; }
;                 } else if (type >= 3) {
;                     const float sc = type == 3 ? QSCALE : 1.0f; const float tf = (float)t;
; #pragma unroll
;                     for (int n = 0; n < 2; ++n) { f32x4 c, s;
; #pragma unroll
;                         for (int e = 0; e < 4; ++e) { const float a = __builtin_amdgcn_fractf(tf * f4[n][e]); c[e] = __builtin_amdgcn_cosf(a) * sc; s[e] = __builtin_amdgcn_sinf(a) * sc; }
;                         const f32x4 x1 = v[0][n], x2 = v[1][n];
;                         v[0][n] = x1 * c - x2 * s; v[1][n] = x1 * s + x2 * c; }
;                     if (type == 4) { float ks = 0.f;
; #pragma unroll
;                         for (int bj = 0; bj < 2; ++bj)
; #pragma unroll
.LBB0_748:
	v_lshl_add_u64 v[16:17], s[80:81], 0, v[72:73]
	v_lshlrev_b64 v[16:17], 7, v[16:17]
	v_lshl_add_u64 v[20:21], v[176:177], 0, v[16:17]
	v_cvt_pk_bf16_f32 v16, v56, v57
	v_cvt_pk_bf16_f32 v17, v58, v59
	v_cvt_pk_bf16_f32 v18, v64, v65
	v_cvt_pk_bf16_f32 v19, v66, v67
	v_add_u32_e32 v56, 0xb0, v190
	v_permlane16_swap_b32_e32 v16, v18
	v_permlane16_swap_b32_e32 v17, v19
	global_store_dwordx4 v[20:21], v[16:19], off
	v_ashrrev_i32_e32 v57, 31, v56
	s_and_b64 vcc, exec, s[12:13]
	v_cvt_pk_bf16_f32 v16, v60, v61
	v_cvt_pk_bf16_f32 v17, v62, v63
	v_cvt_pk_bf16_f32 v18, v68, v69
	v_cvt_pk_bf16_f32 v19, v70, v71
	v_and_b32_e32 v58, s69, v56
	v_permlane16_swap_b32_e32 v16, v18
	v_permlane16_swap_b32_e32 v17, v19
	global_store_dwordx4 v[20:21], v[16:19], off offset:64
	s_mov_b64 s[12:13], -1
	s_nop 0
	s_waitcnt vmcnt(14)
	v_mov_b64_e32 v[16:17], v[236:237]
	v_ffbh_u32_e32 v18, v17
	v_min_u32_e32 v18, 32, v18
	v_lshlrev_b64 v[16:17], v18, v[16:17]
	v_min_u32_e32 v16, 1, v16
	v_or_b32_e32 v16, v17, v16
	v_cvt_f32_u32_e32 v16, v16
	v_sub_u32_e32 v17, 32, v18
	v_ldexp_f32 v16, v16, v17
	v_fmamk_f32 v16, v16, 0x2a800000, v204
	v_rsq_f32_e32 v16, v16
	s_nop 0
	v_pk_mul_f32 v[14:15], v[14:15], v[16:17] op_sel_hi:[1,0]
	v_pk_mul_f32 v[12:13], v[12:13], v[16:17] op_sel_hi:[1,0]
	v_pk_mul_f32 v[10:11], v[10:11], v[16:17] op_sel_hi:[1,0]
	v_pk_mul_f32 v[8:9], v[8:9], v[16:17] op_sel_hi:[1,0]
	v_pk_mul_f32 v[6:7], v[6:7], v[16:17] op_sel_hi:[1,0]
	v_pk_mul_f32 v[4:5], v[4:5], v[16:17] op_sel_hi:[1,0]
	v_pk_mul_f32 v[2:3], v[2:3], v[16:17] op_sel_hi:[1,0]
	v_pk_mul_f32 v[0:1], v[0:1], v[16:17] op_sel_hi:[1,0]
	s_cbranch_vccnz .LBB0_753
	v_mov_b64_e32 v[18:19], v[14:15]
	v_mov_b64_e32 v[26:27], v[10:11]
	v_mov_b64_e32 v[22:23], v[6:7]
	v_mov_b64_e32 v[34:35], v[2:3]
	s_and_b64 vcc, exec, s[10:11]
	v_mov_b32_e32 v59, v74
	v_mov_b64_e32 v[16:17], v[12:13]
	v_mov_b64_e32 v[24:25], v[8:9]
	v_mov_b64_e32 v[20:21], v[4:5]
	v_mov_b64_e32 v[32:33], v[0:1]
	s_cbranch_vccnz .LBB0_752
	v_cvt_f32_u32_e32 v33, v58
	s_andn2_b64 vcc, exec, s[78:79]
	v_mov_b32_e32 v59, v74
	v_mul_f32_e32 v20, v30, v33
	v_fract_f32_e32 v21, v20
	v_mul_f32_e32 v16, v28, v33
	v_mul_f32_e32 v17, v29, v33
	v_cos_f32_e32 v20, v21
	v_sin_f32_e32 v22, v21
	v_mul_f32_e32 v21, v31, v33
	v_fract_f32_e32 v18, v16
	v_fract_f32_e32 v19, v17
	v_fract_f32_e32 v23, v21
	v_cos_f32_e32 v16, v18
	v_sin_f32_e32 v18, v18
	v_cos_f32_e32 v17, v19
	v_cos_f32_e32 v21, v23
	v_sin_f32_e32 v23, v23
	v_sin_f32_e32 v19, v19
	v_pk_mul_f32 v[24:25], v[188:189], v[16:17] op_sel_hi:[0,1]
	v_pk_mul_f32 v[20:21], v[188:189], v[20:21] op_sel_hi:[0,1]
	v_pk_mul_f32 v[22:23], v[188:189], v[22:23] op_sel_hi:[0,1]
	v_pk_mul_f32 v[26:27], v[188:189], v[18:19] op_sel_hi:[0,1]
	v_pk_mul_f32 v[16:17], v[26:27], v[4:5]
	v_pk_mul_f32 v[18:19], v[22:23], v[6:7]
	v_pk_fma_f32 v[16:17], v[24:25], v[12:13], v[16:17] neg_lo:[0,0,1] neg_hi:[0,0,1]
	v_pk_fma_f32 v[18:19], v[20:21], v[14:15], v[18:19] neg_lo:[0,0,1] neg_hi:[0,0,1]
	v_pk_mul_f32 v[24:25], v[24:25], v[4:5]
	v_pk_mul_f32 v[20:21], v[20:21], v[6:7]
	v_mul_f32_e32 v32, v54, v33
	v_pk_fma_f32 v[22:23], v[22:23], v[14:15], v[20:21]
	v_pk_fma_f32 v[20:21], v[26:27], v[12:13], v[24:25]
	v_mul_f32_e32 v24, v52, v33
	v_fract_f32_e32 v25, v24
	v_cos_f32_e32 v24, v25
	v_sin_f32_e32 v26, v25
	v_mul_f32_e32 v25, v53, v33
	v_mul_f32_e32 v33, v55, v33
	v_fract_f32_e32 v27, v25
	v_fract_f32_e32 v34, v32
	v_fract_f32_e32 v35, v33
	v_cos_f32_e32 v25, v27
	v_cos_f32_e32 v32, v34
	v_sin_f32_e32 v34, v34
	v_cos_f32_e32 v33, v35
	v_sin_f32_e32 v35, v35
	v_sin_f32_e32 v27, v27
	v_pk_mul_f32 v[52:53], v[188:189], v[24:25] op_sel_hi:[0,1]
	v_pk_mul_f32 v[32:33], v[188:189], v[32:33] op_sel_hi:[0,1]
	v_pk_mul_f32 v[34:35], v[188:189], v[34:35] op_sel_hi:[0,1]
	v_pk_mul_f32 v[54:55], v[188:189], v[26:27] op_sel_hi:[0,1]
	v_pk_mul_f32 v[24:25], v[54:55], v[0:1]
	v_pk_mul_f32 v[26:27], v[34:35], v[2:3]
	v_pk_fma_f32 v[24:25], v[52:53], v[8:9], v[24:25] neg_lo:[0,0,1] neg_hi:[0,0,1]
	v_pk_fma_f32 v[26:27], v[32:33], v[10:11], v[26:27] neg_lo:[0,0,1] neg_hi:[0,0,1]
	v_pk_mul_f32 v[52:53], v[52:53], v[0:1]
	v_pk_mul_f32 v[32:33], v[32:33], v[2:3]
	s_nop 0
	v_pk_fma_f32 v[34:35], v[34:35], v[10:11], v[32:33]
	v_pk_fma_f32 v[32:33], v[54:55], v[8:9], v[52:53]
	s_cbranch_vccnz .LBB0_752
	v_pk_mul_f32 v[52:53], v[18:19], v[18:19]
	v_pk_mul_f32 v[54:55], v[16:17], v[16:17]
	s_nop 0
	v_pk_mov_b32 v[60:61], v[54:55], v[52:53] op_sel:[1,0]
	v_mov_b32_e32 v55, v53
	v_pk_add_f32 v[52:53], v[60:61], v[54:55]
	v_pk_mul_f32 v[54:55], v[26:27], v[26:27]
	v_pk_add_f32 v[52:53], v[52:53], v[52:53] op_sel_hi:[0,1]
	v_pk_mul_f32 v[60:61], v[24:25], v[24:25]
	v_mul_f32_e32 v52, v20, v20
	v_pk_mov_b32 v[62:63], v[60:61], v[54:55] op_sel:[1,0]
	v_mov_b32_e32 v61, v55
	v_pk_add_f32 v[54:55], v[62:63], v[60:61]
	v_pk_fma_f32 v[60:61], v[20:21], v[20:21], v[52:53] op_sel_hi:[1,1,0]
	v_mul_f32_e32 v52, v22, v22
	v_pk_add_f32 v[54:55], v[54:55], v[54:55] op_sel_hi:[0,1]
	v_pk_fma_f32 v[62:63], v[22:23], v[22:23], v[52:53] op_sel_hi:[1,1,0]
	v_mul_f32_e32 v60, v32, v32
	v_mul_f32_e32 v62, v33, v33
	v_mul_f32_e32 v52, v34, v34
	v_mul_f32_e32 v54, v35, v35
	v_pk_add_f32 v[60:61], v[60:61], v[62:63]
	v_pk_add_f32 v[52:53], v[52:53], v[54:55]
	v_and_b32_e32 v54, 64, v207
	v_pk_add_f32 v[52:53], v[60:61], v[52:53]
	v_add_u32_e32 v54, 64, v54
	v_add_f32_e32 v52, v52, v53
	v_xor_b32_e32 v53, 16, v207
	v_cmp_lt_i32_e32 vcc, v53, v54
	s_nop 1
	v_cndmask_b32_e32 v53, v207, v53, vcc
	v_lshlrev_b32_e32 v53, 2, v53
	ds_bpermute_b32 v53, v53, v52
	s_waitcnt lgkmcnt(0)
	v_add_f32_e32 v52, v52, v53
	v_xor_b32_e32 v53, 32, v207
	v_cmp_lt_i32_e32 vcc, v53, v54
	s_nop 1
	v_cndmask_b32_e32 v53, v207, v53, vcc
	v_lshlrev_b32_e32 v53, 2, v53
	ds_bpermute_b32 v53, v53, v52
	s_waitcnt lgkmcnt(0)
	v_add_f32_e32 v52, v52, v53
	v_max_f32_e32 v53, v74, v74
	v_max_f32_e32 v59, v53, v52
